# every 32-MFMA block of the GEMM K-loops starts on an 8-byte boundary (one s_nop in front of the block where needed): no MFMA straddles a 64-byte instruction-cache line
# speedup vs baseline: 1.0032x; 1.0008x over previous
; #define PG8_STAGEA(bufoff, gbase, voff) PG8_STAGE_X(bufoff, gbase, voff, AUXA)
; #define PG8_STAGEB(bufoff, gbase, voff) PG8_STAGE_X(bufoff, gbase, voff, AUXB)
; #define PG8_LDA(dst, b, h) do { _Pragma("unroll") for (int m = 0; m < 4; ++m) _Pragma("unroll") for (int k = 0; k < 2; ++k) dst[m][k] = *(const PG8_LAS bf16x8*)(lds + PG8_SA(b, h) + aoff + m * 2048 + k * 1024); } while (0)
; #define PG8_LDB(dst, b, h) do { _Pragma("unroll") for (int n = 0; n < 2; ++n) _Pragma("unroll") for (int k = 0; k < 2; ++k) dst[n][k] = *(const PG8_LAS bf16x8*)(lds + PG8_SB(b, h) + boff + n * 2048 + k * 1024); } while (0)
; #define PG8_MMA(ai, bj, At, Bt) do { if (GEMM_PRIO_MODE == 0) __builtin_amdgcn_s_setprio(1); PG8_MMA_LOOPS \
;         acc[ai][bj][m][n] = __builtin_amdgcn_mfma_f32_16x16x32_bf16(Bt[n][k], At[m][k], acc[ai][bj][m][n], 0, 0, 0); if (GEMM_PRIO_MODE == 0) __builtin_amdgcn_s_setprio(0); } while (0)
; #define PG8_WAIT_V(n) asm volatile("s_waitcnt vmcnt(" #n ")" ::: "memory")
; #define PG8_WAIT_L(n) asm volatile("s_waitcnt lgkmcnt(" #n ")" ::: "memory")
;     ...
;         for (int t = t0; t < nt; t += 2) {
;             const bool last = (t == nt - 2);
;             const char* a1 = cA + (size_t)(t + 1) * kstepA;
;             const char* a2 = last ? nA : cA + (size_t)(t + 2) * kstepA; const char* b2 = last ? nB : cB + (size_t)(t + 2) * kstepB;
;             const char* a3 = a2 + kstepA; const char* b3 = b2 + kstepB;
;             if (last && has_next) S.a_ready(nxt);
;             if constexpr (SP2) {
;             PG8_LDB(B0, 0, 0); PG8_LDB(B1, 0, 1); PG8_SCHED; PG8_LDA(At, 0, 0); PG8_STAGEA(PG8_SA(1, 1), a1 + hstepA, voffA);
;     ...
;             const int relax = __builtin_amdgcn_readfirstlane((t == 0 && ui > 0) ? 1 : 0);
;             PG8_WAIT_VR(8, 24, relax); PG8_WAIT_L(0); PG8_BAR; PG8_MMA(0, 0, At, B0); PG8_MMA(0, 1, At, B1); PG8_BAR; PG8_SCHED;
;     ...
;             PG8_WAIT_V(8); PG8_WAIT_L(0); PG8_BAR; PG8_MMA(0, 0, At, B0); PG8_MMA(0, 1, At, B1); PG8_BAR; PG8_SCHED;
;     ...
;             PG8_LDA(At, 0, 1); PG8_STAGEB(PG8_SB(0, 0), b2, voffB); PG8_STAGEB(PG8_SB(0, 1), b2 + hstepB, voffB); PG8_STAGEA(PG8_SA(0, 0), a2, voffA);
;     ...
;             PG8_WAIT_VR(8, 24, relax); PG8_WAIT_L(0); PG8_BAR; PG8_MMA(1, 0, At, B0); PG8_MMA(1, 1, At, B1); PG8_BAR; PG8_SCHED;
;     ...
;             PG8_WAIT_V(8); PG8_WAIT_L(0); PG8_BAR; PG8_MMA(1, 0, At, B0); PG8_MMA(1, 1, At, B1); PG8_BAR; PG8_SCHED;
.LBB0_128:
	s_ashr_i32 s37, s36, 31
	s_lshl_b64 s[4:5], s[36:37], 21
	s_add_u32 s38, s56, s4
	s_addc_u32 s39, s57, s5
	s_and_b64 s[4:5], s[6:7], exec
	s_cselect_b32 s4, s39, s1
	s_cselect_b32 s5, s38, s0
	s_ashr_i32 s27, s26, 31
	s_lshl_b64 s[8:9], s[26:27], 21
	s_add_u32 s40, s43, s8
	s_addc_u32 s41, s50, s9
	s_and_b64 s[8:9], s[6:7], exec
	s_cselect_b32 s16, s41, s11
	s_cselect_b32 s17, s40, s10
	s_add_u32 s8, s0, 0x100080
	s_addc_u32 s9, s1, 0
	s_add_u32 s0, s10, 0x100
	s_addc_u32 s1, s11, 0
	s_mov_b32 s27, -2
	s_add_u32 s10, s8, 0xfff00080
	s_addc_u32 s11, s9, -1
	s_add_i32 s18, 0, 0x10000
	s_cmp_eq_u32 s27, 60
	s_cselect_b32 s15, s4, s11
	s_cselect_b32 s14, s5, s10
	v_add_u32_e32 v16, s18, v167
	s_cselect_b32 s11, s16, s1
	s_cselect_b32 s10, s17, s0
	s_add_i32 s20, 0, 0x14000
	s_waitcnt lgkmcnt(0)
	ds_read_b128 v[130:133], v16
	ds_read_b128 v[134:137], v16 offset:1024
	ds_read_b128 v[152:155], v16 offset:2048
	ds_read_b128 v[156:159], v16 offset:3072
	v_add_u32_e32 v16, s20, v167
	ds_read_b128 v[160:163], v16
	ds_read_b128 v[174:177], v16 offset:1024
	ds_read_b128 v[178:181], v16 offset:2048
	ds_read_b128 v[182:185], v16 offset:3072
	v_lshl_add_u64 v[164:165], s[8:9], 0, v[148:149]
	s_add_i32 m0, s51, 0xc000
	ds_read_b128 v[186:189], v172
	ds_read_b128 v[190:193], v172 offset:1024
	ds_read_b128 v[194:197], v172 offset:2048
	ds_read_b128 v[198:201], v172 offset:3072
	ds_read_b128 v[202:205], v172 offset:4096
	ds_read_b128 v[206:209], v172 offset:5120
	ds_read_b128 v[210:213], v172 offset:6144
	ds_read_b128 v[214:217], v172 offset:7168
	global_load_lds_dwordx4 v[164:165], off
	v_lshl_add_u64 v[164:165], s[8:9], 0, v[150:151]
	s_add_i32 m0, s51, 0xe000
	s_nop 0
	global_load_lds_dwordx4 v[164:165], off
	s_waitcnt vmcnt(8)
	s_waitcnt lgkmcnt(0)
	s_setprio 1
	s_barrier
	v_mfma_f32_16x16x32_bf16 v[126:129], v[130:133], v[186:189], 0
	v_mfma_f32_16x16x32_bf16 v[122:125], v[152:155], v[186:189], 0
	v_mfma_f32_16x16x32_bf16 v[110:113], v[130:133], v[194:197], 0
	v_mfma_f32_16x16x32_bf16 v[106:109], v[152:155], v[194:197], 0
	v_mfma_f32_16x16x32_bf16 v[94:97], v[130:133], v[202:205], 0
	v_mfma_f32_16x16x32_bf16 v[90:93], v[152:155], v[202:205], 0
	v_mfma_f32_16x16x32_bf16 v[78:81], v[130:133], v[210:213], 0
	v_mfma_f32_16x16x32_bf16 v[74:77], v[152:155], v[210:213], 0
	v_mfma_f32_16x16x32_bf16 v[126:129], v[134:137], v[190:193], v[126:129]
	v_mfma_f32_16x16x32_bf16 v[122:125], v[156:159], v[190:193], v[122:125]
	v_mfma_f32_16x16x32_bf16 v[110:113], v[134:137], v[198:201], v[110:113]
	v_mfma_f32_16x16x32_bf16 v[106:109], v[156:159], v[198:201], v[106:109]
	v_mfma_f32_16x16x32_bf16 v[94:97], v[134:137], v[206:209], v[94:97]
	v_mfma_f32_16x16x32_bf16 v[90:93], v[156:159], v[206:209], v[90:93]
	v_mfma_f32_16x16x32_bf16 v[78:81], v[134:137], v[214:217], v[78:81]
	v_mfma_f32_16x16x32_bf16 v[74:77], v[156:159], v[214:217], v[74:77]
	v_mfma_f32_16x16x32_bf16 v[118:121], v[160:163], v[186:189], 0
	v_mfma_f32_16x16x32_bf16 v[114:117], v[178:181], v[186:189], 0
	v_mfma_f32_16x16x32_bf16 v[102:105], v[160:163], v[194:197], 0
	v_mfma_f32_16x16x32_bf16 v[98:101], v[178:181], v[194:197], 0
	v_mfma_f32_16x16x32_bf16 v[86:89], v[160:163], v[202:205], 0
	v_mfma_f32_16x16x32_bf16 v[82:85], v[178:181], v[202:205], 0
	v_mfma_f32_16x16x32_bf16 v[70:73], v[160:163], v[210:213], 0
	v_mfma_f32_16x16x32_bf16 v[66:69], v[178:181], v[210:213], 0
	v_mfma_f32_16x16x32_bf16 v[118:121], v[174:177], v[190:193], v[118:121]
	v_mfma_f32_16x16x32_bf16 v[114:117], v[182:185], v[190:193], v[114:117]
	v_mfma_f32_16x16x32_bf16 v[102:105], v[174:177], v[198:201], v[102:105]
	v_mfma_f32_16x16x32_bf16 v[98:101], v[182:185], v[198:201], v[98:101]
	v_mfma_f32_16x16x32_bf16 v[86:89], v[174:177], v[206:209], v[86:89]
	v_mfma_f32_16x16x32_bf16 v[82:85], v[182:185], v[206:209], v[82:85]
	v_mfma_f32_16x16x32_bf16 v[70:73], v[174:177], v[214:217], v[70:73]
	v_mfma_f32_16x16x32_bf16 v[66:69], v[182:185], v[214:217], v[66:69]
	s_barrier
	s_setprio 0
	s_add_i32 s18, s18, s42
	v_lshl_add_u64 v[164:165], s[10:11], 0, v[142:143]
	s_mov_b32 m0, s18
	ds_read_b128 v[186:189], v172 offset:16384
	ds_read_b128 v[190:193], v172 offset:17408
	ds_read_b128 v[194:197], v172 offset:18432
	ds_read_b128 v[198:201], v172 offset:19456
	ds_read_b128 v[202:205], v172 offset:20480
	ds_read_b128 v[206:209], v172 offset:21504
	ds_read_b128 v[210:213], v172 offset:22528
	ds_read_b128 v[214:217], v172 offset:23552
	global_load_lds_dwordx4 v[164:165], off
	s_add_i32 m0, s18, 0x2000
	s_add_u32 s18, s10, 0x100000
	v_lshl_add_u64 v[218:219], s[10:11], 0, v[138:139]
	s_addc_u32 s19, s11, 0
	s_add_i32 s20, s20, s42
	global_load_lds_dwordx4 v[218:219], off
	v_lshl_add_u64 v[220:221], s[18:19], 0, v[142:143]
	s_mov_b32 m0, s20
	v_lshl_add_u64 v[222:223], s[14:15], 0, v[140:141]
	global_load_lds_dwordx4 v[220:221], off
	v_lshl_add_u64 v[220:221], s[18:19], 0, v[138:139]
	s_add_i32 m0, s20, 0x2000
	s_nop 0
	global_load_lds_dwordx4 v[220:221], off
	v_lshl_add_u64 v[220:221], s[14:15], 0, v[144:145]
	s_mov_b32 m0, s51
	s_nop 0
	global_load_lds_dwordx4 v[220:221], off
	s_mov_b32 m0, s68
	s_nop 0
	global_load_lds_dwordx4 v[222:223], off
	s_waitcnt vmcnt(8)
	s_waitcnt lgkmcnt(0)
	s_setprio 1
	s_barrier
; #define PG8_STAGEA(bufoff, gbase, voff) PG8_STAGE_X(bufoff, gbase, voff, AUXA)
; #define PG8_STAGEB(bufoff, gbase, voff) PG8_STAGE_X(bufoff, gbase, voff, AUXB)
; #define PG8_LDA(dst, b, h) do { _Pragma("unroll") for (int m = 0; m < 4; ++m) _Pragma("unroll") for (int k = 0; k < 2; ++k) dst[m][k] = *(const PG8_LAS bf16x8*)(lds + PG8_SA(b, h) + aoff + m * 2048 + k * 1024); } while (0)
; #define PG8_LDB(dst, b, h) do { _Pragma("unroll") for (int n = 0; n < 2; ++n) _Pragma("unroll") for (int k = 0; k < 2; ++k) dst[n][k] = *(const PG8_LAS bf16x8*)(lds + PG8_SB(b, h) + boff + n * 2048 + k * 1024); } while (0)
; #define PG8_MMA(ai, bj, At, Bt) do { if (GEMM_PRIO_MODE == 0) __builtin_amdgcn_s_setprio(1); PG8_MMA_LOOPS \
;         acc[ai][bj][m][n] = __builtin_amdgcn_mfma_f32_16x16x32_bf16(Bt[n][k], At[m][k], acc[ai][bj][m][n], 0, 0, 0); if (GEMM_PRIO_MODE == 0) __builtin_amdgcn_s_setprio(0); } while (0)
; #define PG8_WAIT_V(n) asm volatile("s_waitcnt vmcnt(" #n ")" ::: "memory")
; #define PG8_WAIT_VR(n, nr, flag) asm volatile("s_cmp_eq_u32 %0, 0\n\ts_cbranch_scc1 .Lpg8s%=\n\ts_waitcnt vmcnt(" #nr ")\n\ts_branch .Lpg8d%=\n.Lpg8s%=:\n\ts_waitcnt vmcnt(" #n ")\n.Lpg8d%=:" :: "s"(flag) : "memory", "scc")
; #define PG8_WAIT_L(n) asm volatile("s_waitcnt lgkmcnt(" #n ")" ::: "memory")
; #define PG8_BAR __builtin_amdgcn_s_barrier()
; #define PG8_SCHED __builtin_amdgcn_sched_barrier(0)
;     ...
;             PG8_WAIT_VR(8, 24, relax); PG8_WAIT_L(0); PG8_BAR; PG8_MMA(1, 0, At, B0); PG8_MMA(1, 1, At, B1); PG8_BAR; PG8_SCHED;
;     ...
;             PG8_WAIT_V(8); PG8_WAIT_L(0); PG8_BAR; PG8_MMA(1, 0, At, B0); PG8_MMA(1, 1, At, B1); PG8_BAR; PG8_SCHED;
;     ...
;             PG8_LDB(B0, 1, 0); PG8_LDB(B1, 1, 1); PG8_SCHED; PG8_LDA(At, 1, 0); PG8_STAGEA(PG8_SA(0, 1), a2 + hstepA, voffA);
;             PG8_WAIT_V(8); PG8_WAIT_L(0); PG8_BAR; PG8_MMA(0, 0, At, B0); PG8_MMA(0, 1, At, B1); PG8_BAR; PG8_SCHED;
;             PG8_LDA(At, 1, 1); PG8_STAGEB(PG8_SB(1, 0), b3, voffB); PG8_STAGEB(PG8_SB(1, 1), b3 + hstepB, voffB); PG8_STAGEA(PG8_SA(1, 0), a3, voffA);
	v_mfma_f32_16x16x32_bf16 v[62:65], v[130:133], v[186:189], 0
	v_mfma_f32_16x16x32_bf16 v[58:61], v[152:155], v[186:189], 0
	v_mfma_f32_16x16x32_bf16 v[46:49], v[130:133], v[194:197], 0
	v_mfma_f32_16x16x32_bf16 v[42:45], v[152:155], v[194:197], 0
	v_mfma_f32_16x16x32_bf16 v[30:33], v[130:133], v[202:205], 0
	v_mfma_f32_16x16x32_bf16 v[26:29], v[152:155], v[202:205], 0
	v_mfma_f32_16x16x32_bf16 v[12:15], v[130:133], v[210:213], 0
	v_mfma_f32_16x16x32_bf16 v[8:11], v[152:155], v[210:213], 0
	v_mfma_f32_16x16x32_bf16 v[62:65], v[134:137], v[190:193], v[62:65]
	v_mfma_f32_16x16x32_bf16 v[58:61], v[156:159], v[190:193], v[58:61]
	v_mfma_f32_16x16x32_bf16 v[46:49], v[134:137], v[198:201], v[46:49]
	v_mfma_f32_16x16x32_bf16 v[42:45], v[156:159], v[198:201], v[42:45]
	v_mfma_f32_16x16x32_bf16 v[30:33], v[134:137], v[206:209], v[30:33]
	v_mfma_f32_16x16x32_bf16 v[26:29], v[156:159], v[206:209], v[26:29]
	v_mfma_f32_16x16x32_bf16 v[12:15], v[134:137], v[214:217], v[12:15]
	v_mfma_f32_16x16x32_bf16 v[8:11], v[156:159], v[214:217], v[8:11]
	v_mfma_f32_16x16x32_bf16 v[54:57], v[160:163], v[186:189], 0
	v_mfma_f32_16x16x32_bf16 v[50:53], v[178:181], v[186:189], 0
	v_mfma_f32_16x16x32_bf16 v[38:41], v[160:163], v[194:197], 0
	v_mfma_f32_16x16x32_bf16 v[34:37], v[178:181], v[194:197], 0
	v_mfma_f32_16x16x32_bf16 v[22:25], v[160:163], v[202:205], 0
	v_mfma_f32_16x16x32_bf16 v[18:21], v[178:181], v[202:205], 0
	v_mfma_f32_16x16x32_bf16 v[4:7], v[160:163], v[210:213], 0
	v_mfma_f32_16x16x32_bf16 v[0:3], v[178:181], v[210:213], 0
	v_mfma_f32_16x16x32_bf16 v[54:57], v[174:177], v[190:193], v[54:57]
	v_mfma_f32_16x16x32_bf16 v[50:53], v[182:185], v[190:193], v[50:53]
	v_mfma_f32_16x16x32_bf16 v[38:41], v[174:177], v[198:201], v[38:41]
	v_mfma_f32_16x16x32_bf16 v[34:37], v[182:185], v[198:201], v[34:37]
	v_mfma_f32_16x16x32_bf16 v[22:25], v[174:177], v[206:209], v[22:25]
	v_mfma_f32_16x16x32_bf16 v[18:21], v[182:185], v[206:209], v[18:21]
	v_mfma_f32_16x16x32_bf16 v[4:7], v[174:177], v[214:217], v[4:7]
	v_mfma_f32_16x16x32_bf16 v[0:3], v[182:185], v[214:217], v[0:3]
	s_barrier
	s_setprio 0
	s_add_i32 s18, 0, 0x18000
	v_add_u32_e32 v16, s18, v167
	s_add_i32 s19, 0, 0x1c000
	ds_read_b128 v[130:133], v16
	ds_read_b128 v[134:137], v16 offset:1024
	ds_read_b128 v[152:155], v16 offset:2048
	ds_read_b128 v[156:159], v16 offset:3072
	v_add_u32_e32 v16, s19, v167
	ds_read_b128 v[160:163], v16
	ds_read_b128 v[174:177], v16 offset:1024
	ds_read_b128 v[178:181], v16 offset:2048
	ds_read_b128 v[182:185], v16 offset:3072
	s_add_u32 s14, s14, 0x100000
	s_addc_u32 s15, s15, 0
	s_mov_b32 m0, s69
	v_lshl_add_u64 v[224:225], s[14:15], 0, v[144:145]
	ds_read_b128 v[186:189], v172 offset:32768
	ds_read_b128 v[190:193], v172 offset:33792
	ds_read_b128 v[194:197], v172 offset:34816
	ds_read_b128 v[198:201], v172 offset:35840
	ds_read_b128 v[202:205], v172 offset:36864
	ds_read_b128 v[206:209], v172 offset:37888
	ds_read_b128 v[210:213], v172 offset:38912
	ds_read_b128 v[214:217], v172 offset:39936
	global_load_lds_dwordx4 v[224:225], off
	v_lshl_add_u64 v[224:225], s[14:15], 0, v[140:141]
	s_mov_b32 m0, s72
	s_nop 0
	global_load_lds_dwordx4 v[224:225], off
	s_waitcnt vmcnt(8)
	s_waitcnt lgkmcnt(0)
	s_setprio 1
	s_barrier
	v_mfma_f32_16x16x32_bf16 v[126:129], v[130:133], v[186:189], v[126:129]
	v_mfma_f32_16x16x32_bf16 v[122:125], v[152:155], v[186:189], v[122:125]
	v_mfma_f32_16x16x32_bf16 v[110:113], v[130:133], v[194:197], v[110:113]
	v_mfma_f32_16x16x32_bf16 v[106:109], v[152:155], v[194:197], v[106:109]
	v_mfma_f32_16x16x32_bf16 v[94:97], v[130:133], v[202:205], v[94:97]
	v_mfma_f32_16x16x32_bf16 v[90:93], v[152:155], v[202:205], v[90:93]
	v_mfma_f32_16x16x32_bf16 v[78:81], v[130:133], v[210:213], v[78:81]
	v_mfma_f32_16x16x32_bf16 v[74:77], v[152:155], v[210:213], v[74:77]
	v_mfma_f32_16x16x32_bf16 v[126:129], v[134:137], v[190:193], v[126:129]
	v_mfma_f32_16x16x32_bf16 v[122:125], v[156:159], v[190:193], v[122:125]
	v_mfma_f32_16x16x32_bf16 v[110:113], v[134:137], v[198:201], v[110:113]
	v_mfma_f32_16x16x32_bf16 v[106:109], v[156:159], v[198:201], v[106:109]
	v_mfma_f32_16x16x32_bf16 v[94:97], v[134:137], v[206:209], v[94:97]
	v_mfma_f32_16x16x32_bf16 v[90:93], v[156:159], v[206:209], v[90:93]
	v_mfma_f32_16x16x32_bf16 v[78:81], v[134:137], v[214:217], v[78:81]
	v_mfma_f32_16x16x32_bf16 v[74:77], v[156:159], v[214:217], v[74:77]
	v_mfma_f32_16x16x32_bf16 v[118:121], v[160:163], v[186:189], v[118:121]
	v_mfma_f32_16x16x32_bf16 v[114:117], v[178:181], v[186:189], v[114:117]
	v_mfma_f32_16x16x32_bf16 v[102:105], v[160:163], v[194:197], v[102:105]
	v_mfma_f32_16x16x32_bf16 v[98:101], v[178:181], v[194:197], v[98:101]
	v_mfma_f32_16x16x32_bf16 v[86:89], v[160:163], v[202:205], v[86:89]
	v_mfma_f32_16x16x32_bf16 v[82:85], v[178:181], v[202:205], v[82:85]
	v_mfma_f32_16x16x32_bf16 v[70:73], v[160:163], v[210:213], v[70:73]
	v_mfma_f32_16x16x32_bf16 v[66:69], v[178:181], v[210:213], v[66:69]
	v_mfma_f32_16x16x32_bf16 v[118:121], v[174:177], v[190:193], v[118:121]
	v_mfma_f32_16x16x32_bf16 v[114:117], v[182:185], v[190:193], v[114:117]
	v_mfma_f32_16x16x32_bf16 v[102:105], v[174:177], v[198:201], v[102:105]
	v_mfma_f32_16x16x32_bf16 v[98:101], v[182:185], v[198:201], v[98:101]
	v_mfma_f32_16x16x32_bf16 v[86:89], v[174:177], v[206:209], v[86:89]
	v_mfma_f32_16x16x32_bf16 v[82:85], v[182:185], v[206:209], v[82:85]
	v_mfma_f32_16x16x32_bf16 v[70:73], v[174:177], v[214:217], v[70:73]
	v_mfma_f32_16x16x32_bf16 v[66:69], v[182:185], v[214:217], v[66:69]
	s_barrier
; #define PG8_STAGEA(bufoff, gbase, voff) PG8_STAGE_X(bufoff, gbase, voff, AUXA)
; #define PG8_STAGEB(bufoff, gbase, voff) PG8_STAGE_X(bufoff, gbase, voff, AUXB)
; #define PG8_LDA(dst, b, h) do { _Pragma("unroll") for (int m = 0; m < 4; ++m) _Pragma("unroll") for (int k = 0; k < 2; ++k) dst[m][k] = *(const PG8_LAS bf16x8*)(lds + PG8_SA(b, h) + aoff + m * 2048 + k * 1024); } while (0)
; #define PG8_LDB(dst, b, h) do { _Pragma("unroll") for (int n = 0; n < 2; ++n) _Pragma("unroll") for (int k = 0; k < 2; ++k) dst[n][k] = *(const PG8_LAS bf16x8*)(lds + PG8_SB(b, h) + boff + n * 2048 + k * 1024); } while (0)
; #define PG8_MMA(ai, bj, At, Bt) do { if (GEMM_PRIO_MODE == 0) __builtin_amdgcn_s_setprio(1); PG8_MMA_LOOPS \
;         acc[ai][bj][m][n] = __builtin_amdgcn_mfma_f32_16x16x32_bf16(Bt[n][k], At[m][k], acc[ai][bj][m][n], 0, 0, 0); if (GEMM_PRIO_MODE == 0) __builtin_amdgcn_s_setprio(0); } while (0)
; #define PG8_BAR __builtin_amdgcn_s_barrier()
;     ...
;         for (int t = t0; t < nt; t += 2) {
;             const bool last = (t == nt - 2);
;             const char* a1 = cA + (size_t)(t + 1) * kstepA;
;             const char* a2 = last ? nA : cA + (size_t)(t + 2) * kstepA; const char* b2 = last ? nB : cB + (size_t)(t + 2) * kstepB;
;             const char* a3 = a2 + kstepA; const char* b3 = b2 + kstepB;
;             if (last && has_next) S.a_ready(nxt);
;             if constexpr (SP2) {
;             PG8_LDB(B0, 0, 0); PG8_LDB(B1, 0, 1); PG8_SCHED; PG8_LDA(At, 0, 0); PG8_STAGEA(PG8_SA(1, 1), a1 + hstepA, voffA);
;     ...
;             const int relax = __builtin_amdgcn_readfirstlane((t == 0 && ui > 0) ? 1 : 0);
;             PG8_WAIT_VR(8, 24, relax); PG8_WAIT_L(0); PG8_BAR; PG8_MMA(0, 0, At, B0); PG8_MMA(0, 1, At, B1); PG8_BAR; PG8_SCHED;
;     ...
;             PG8_WAIT_V(8); PG8_WAIT_L(0); PG8_BAR; PG8_MMA(0, 0, At, B0); PG8_MMA(0, 1, At, B1); PG8_BAR; PG8_SCHED;
;     ...
;             PG8_LDB(B0, 1, 0); PG8_LDB(B1, 1, 1); PG8_SCHED; PG8_LDA(At, 1, 0); PG8_STAGEA(PG8_SA(0, 1), a2 + hstepA, voffA);
;             PG8_WAIT_V(8); PG8_WAIT_L(0); PG8_BAR; PG8_MMA(0, 0, At, B0); PG8_MMA(0, 1, At, B1); PG8_BAR; PG8_SCHED;
;             PG8_LDA(At, 1, 1); PG8_STAGEB(PG8_SB(1, 0), b3, voffB); PG8_STAGEB(PG8_SB(1, 1), b3 + hstepB, voffB); PG8_STAGEA(PG8_SA(1, 0), a3, voffA);
;             PG8_WAIT_V(8); PG8_WAIT_L(0); PG8_BAR; PG8_MMA(1, 0, At, B0); PG8_MMA(1, 1, At, B1); PG8_BAR; PG8_SCHED;
	s_setprio 0
	s_add_i32 s14, s18, s42
	v_lshl_add_u64 v[164:165], v[164:165], 0, s[86:87]
	s_mov_b32 m0, s14
	ds_read_b128 v[186:189], v172 offset:49152
	ds_read_b128 v[190:193], v172 offset:50176
	ds_read_b128 v[194:197], v172 offset:51200
	ds_read_b128 v[198:201], v172 offset:52224
	ds_read_b128 v[202:205], v172 offset:53248
	ds_read_b128 v[206:209], v172 offset:54272
	ds_read_b128 v[210:213], v172 offset:55296
	ds_read_b128 v[214:217], v172 offset:56320
	global_load_lds_dwordx4 v[164:165], off
	s_add_i32 m0, s14, 0x2000
	s_add_u32 s10, s10, 0x100080
	v_lshl_add_u64 v[164:165], v[218:219], 0, s[86:87]
	s_addc_u32 s11, s11, 0
	s_add_i32 s14, s19, s42
	global_load_lds_dwordx4 v[164:165], off
	v_lshl_add_u64 v[164:165], s[10:11], 0, v[142:143]
	s_mov_b32 m0, s14
	s_nop 0
	global_load_lds_dwordx4 v[164:165], off
	v_lshl_add_u64 v[164:165], s[10:11], 0, v[138:139]
	s_add_i32 m0, s14, 0x2000
	s_nop 0
	global_load_lds_dwordx4 v[164:165], off
	v_lshl_add_u64 v[164:165], v[220:221], 0, s[86:87]
	s_mov_b32 m0, s73
	s_nop 0
	global_load_lds_dwordx4 v[164:165], off
	v_lshl_add_u64 v[164:165], v[222:223], 0, s[86:87]
	s_mov_b32 m0, s82
	s_nop 0
	global_load_lds_dwordx4 v[164:165], off
	s_waitcnt vmcnt(8)
	s_waitcnt lgkmcnt(0)
	s_nop 0
	s_setprio 1
	s_barrier
	v_mfma_f32_16x16x32_bf16 v[62:65], v[130:133], v[186:189], v[62:65]
	v_mfma_f32_16x16x32_bf16 v[58:61], v[152:155], v[186:189], v[58:61]
	v_mfma_f32_16x16x32_bf16 v[46:49], v[130:133], v[194:197], v[46:49]
	v_mfma_f32_16x16x32_bf16 v[42:45], v[152:155], v[194:197], v[42:45]
	v_mfma_f32_16x16x32_bf16 v[30:33], v[130:133], v[202:205], v[30:33]
	v_mfma_f32_16x16x32_bf16 v[26:29], v[152:155], v[202:205], v[26:29]
	v_mfma_f32_16x16x32_bf16 v[12:15], v[130:133], v[210:213], v[12:15]
	v_mfma_f32_16x16x32_bf16 v[8:11], v[152:155], v[210:213], v[8:11]
	v_mfma_f32_16x16x32_bf16 v[62:65], v[134:137], v[190:193], v[62:65]
	v_mfma_f32_16x16x32_bf16 v[58:61], v[156:159], v[190:193], v[58:61]
	v_mfma_f32_16x16x32_bf16 v[46:49], v[134:137], v[198:201], v[46:49]
	v_mfma_f32_16x16x32_bf16 v[42:45], v[156:159], v[198:201], v[42:45]
	v_mfma_f32_16x16x32_bf16 v[30:33], v[134:137], v[206:209], v[30:33]
	v_mfma_f32_16x16x32_bf16 v[26:29], v[156:159], v[206:209], v[26:29]
	v_mfma_f32_16x16x32_bf16 v[12:15], v[134:137], v[214:217], v[12:15]
	v_mfma_f32_16x16x32_bf16 v[8:11], v[156:159], v[214:217], v[8:11]
	v_mfma_f32_16x16x32_bf16 v[54:57], v[160:163], v[186:189], v[54:57]
	v_mfma_f32_16x16x32_bf16 v[50:53], v[178:181], v[186:189], v[50:53]
	v_mfma_f32_16x16x32_bf16 v[38:41], v[160:163], v[194:197], v[38:41]
	v_mfma_f32_16x16x32_bf16 v[34:37], v[178:181], v[194:197], v[34:37]
	v_mfma_f32_16x16x32_bf16 v[22:25], v[160:163], v[202:205], v[22:25]
	v_mfma_f32_16x16x32_bf16 v[18:21], v[178:181], v[202:205], v[18:21]
	v_mfma_f32_16x16x32_bf16 v[4:7], v[160:163], v[210:213], v[4:7]
	v_mfma_f32_16x16x32_bf16 v[0:3], v[178:181], v[210:213], v[0:3]
	v_mfma_f32_16x16x32_bf16 v[54:57], v[174:177], v[190:193], v[54:57]
	v_mfma_f32_16x16x32_bf16 v[50:53], v[182:185], v[190:193], v[50:53]
	v_mfma_f32_16x16x32_bf16 v[38:41], v[174:177], v[198:201], v[38:41]
	v_mfma_f32_16x16x32_bf16 v[34:37], v[182:185], v[198:201], v[34:37]
	v_mfma_f32_16x16x32_bf16 v[22:25], v[174:177], v[206:209], v[22:25]
	v_mfma_f32_16x16x32_bf16 v[18:21], v[182:185], v[206:209], v[18:21]
	v_mfma_f32_16x16x32_bf16 v[4:7], v[174:177], v[214:217], v[4:7]
	v_mfma_f32_16x16x32_bf16 v[0:3], v[182:185], v[214:217], v[0:3]
	s_barrier
	s_setprio 0
	s_add_i32 s27, s27, 2
	s_add_u32 s8, s8, 0x100
	s_addc_u32 s9, s9, 0
	s_add_u32 s0, s0, 0x100
	s_addc_u32 s1, s1, 0
.LBB0_129:
	s_add_u32 s10, s8, 0xfff00080
	s_addc_u32 s11, s9, -1
	s_add_i32 s18, 0, 0x10000
	s_cmp_eq_u32 s27, 60
	s_cselect_b32 s15, s4, s11
	s_cselect_b32 s14, s5, s10
	v_add_u32_e32 v16, s18, v167
	s_cselect_b32 s11, s16, s1
	s_cselect_b32 s10, s17, s0
	s_add_i32 s20, 0, 0x14000
	s_waitcnt lgkmcnt(0)
	ds_read_b128 v[130:133], v16
	ds_read_b128 v[134:137], v16 offset:1024
	ds_read_b128 v[152:155], v16 offset:2048
	ds_read_b128 v[156:159], v16 offset:3072
	v_add_u32_e32 v16, s20, v167
	ds_read_b128 v[160:163], v16
	ds_read_b128 v[174:177], v16 offset:1024
	ds_read_b128 v[178:181], v16 offset:2048
	ds_read_b128 v[182:185], v16 offset:3072
	v_lshl_add_u64 v[164:165], s[8:9], 0, v[148:149]
	s_add_i32 m0, s51, 0xc000
	ds_read_b128 v[186:189], v172
	ds_read_b128 v[190:193], v172 offset:1024
	ds_read_b128 v[194:197], v172 offset:2048
	ds_read_b128 v[198:201], v172 offset:3072
	ds_read_b128 v[202:205], v172 offset:4096
	ds_read_b128 v[206:209], v172 offset:5120
	ds_read_b128 v[210:213], v172 offset:6144
	ds_read_b128 v[214:217], v172 offset:7168
	global_load_lds_dwordx4 v[164:165], off
	v_lshl_add_u64 v[164:165], s[8:9], 0, v[150:151]
	s_add_i32 m0, s51, 0xe000
	s_nop 0
	global_load_lds_dwordx4 v[164:165], off
	s_waitcnt vmcnt(8)
	s_waitcnt lgkmcnt(0)
	s_nop 0
	s_setprio 1
	s_barrier
; #define PG8_STAGEA(bufoff, gbase, voff) PG8_STAGE_X(bufoff, gbase, voff, AUXA)
; #define PG8_STAGEB(bufoff, gbase, voff) PG8_STAGE_X(bufoff, gbase, voff, AUXB)
; #define PG8_LDA(dst, b, h) do { _Pragma("unroll") for (int m = 0; m < 4; ++m) _Pragma("unroll") for (int k = 0; k < 2; ++k) dst[m][k] = *(const PG8_LAS bf16x8*)(lds + PG8_SA(b, h) + aoff + m * 2048 + k * 1024); } while (0)
; #define PG8_LDB(dst, b, h) do { _Pragma("unroll") for (int n = 0; n < 2; ++n) _Pragma("unroll") for (int k = 0; k < 2; ++k) dst[n][k] = *(const PG8_LAS bf16x8*)(lds + PG8_SB(b, h) + boff + n * 2048 + k * 1024); } while (0)
; #define PG8_MMA(ai, bj, At, Bt) do { if (GEMM_PRIO_MODE == 0) __builtin_amdgcn_s_setprio(1); PG8_MMA_LOOPS \
;         acc[ai][bj][m][n] = __builtin_amdgcn_mfma_f32_16x16x32_bf16(Bt[n][k], At[m][k], acc[ai][bj][m][n], 0, 0, 0); if (GEMM_PRIO_MODE == 0) __builtin_amdgcn_s_setprio(0); } while (0)
; #define PG8_WAIT_V(n) asm volatile("s_waitcnt vmcnt(" #n ")" ::: "memory")
; #define PG8_WAIT_VR(n, nr, flag) asm volatile("s_cmp_eq_u32 %0, 0\n\ts_cbranch_scc1 .Lpg8s%=\n\ts_waitcnt vmcnt(" #nr ")\n\ts_branch .Lpg8d%=\n.Lpg8s%=:\n\ts_waitcnt vmcnt(" #n ")\n.Lpg8d%=:" :: "s"(flag) : "memory", "scc")
; #define PG8_WAIT_L(n) asm volatile("s_waitcnt lgkmcnt(" #n ")" ::: "memory")
; #define PG8_BAR __builtin_amdgcn_s_barrier()
; #define PG8_SCHED __builtin_amdgcn_sched_barrier(0)
;     ...
;             PG8_LDB(B0, 0, 0); PG8_LDB(B1, 0, 1); PG8_SCHED; PG8_LDA(At, 0, 0); PG8_STAGEA(PG8_SA(1, 1), a1 + hstepA, voffA);
;     ...
;             const int relax = __builtin_amdgcn_readfirstlane((t == 0 && ui > 0) ? 1 : 0);
;             PG8_WAIT_VR(8, 24, relax); PG8_WAIT_L(0); PG8_BAR; PG8_MMA(0, 0, At, B0); PG8_MMA(0, 1, At, B1); PG8_BAR; PG8_SCHED;
;     ...
;             PG8_WAIT_V(8); PG8_WAIT_L(0); PG8_BAR; PG8_MMA(0, 0, At, B0); PG8_MMA(0, 1, At, B1); PG8_BAR; PG8_SCHED;
;     ...
;             PG8_LDA(At, 0, 1); PG8_STAGEB(PG8_SB(0, 0), b2, voffB); PG8_STAGEB(PG8_SB(0, 1), b2 + hstepB, voffB); PG8_STAGEA(PG8_SA(0, 0), a2, voffA);
	v_mfma_f32_16x16x32_bf16 v[126:129], v[130:133], v[186:189], v[126:129]
	v_mfma_f32_16x16x32_bf16 v[122:125], v[152:155], v[186:189], v[122:125]
	v_mfma_f32_16x16x32_bf16 v[110:113], v[130:133], v[194:197], v[110:113]
	v_mfma_f32_16x16x32_bf16 v[106:109], v[152:155], v[194:197], v[106:109]
	v_mfma_f32_16x16x32_bf16 v[94:97], v[130:133], v[202:205], v[94:97]
	v_mfma_f32_16x16x32_bf16 v[90:93], v[152:155], v[202:205], v[90:93]
	v_mfma_f32_16x16x32_bf16 v[78:81], v[130:133], v[210:213], v[78:81]
	v_mfma_f32_16x16x32_bf16 v[74:77], v[152:155], v[210:213], v[74:77]
	v_mfma_f32_16x16x32_bf16 v[126:129], v[134:137], v[190:193], v[126:129]
	v_mfma_f32_16x16x32_bf16 v[122:125], v[156:159], v[190:193], v[122:125]
	v_mfma_f32_16x16x32_bf16 v[110:113], v[134:137], v[198:201], v[110:113]
	v_mfma_f32_16x16x32_bf16 v[106:109], v[156:159], v[198:201], v[106:109]
	v_mfma_f32_16x16x32_bf16 v[94:97], v[134:137], v[206:209], v[94:97]
	v_mfma_f32_16x16x32_bf16 v[90:93], v[156:159], v[206:209], v[90:93]
	v_mfma_f32_16x16x32_bf16 v[78:81], v[134:137], v[214:217], v[78:81]
	v_mfma_f32_16x16x32_bf16 v[74:77], v[156:159], v[214:217], v[74:77]
	v_mfma_f32_16x16x32_bf16 v[118:121], v[160:163], v[186:189], v[118:121]
	v_mfma_f32_16x16x32_bf16 v[114:117], v[178:181], v[186:189], v[114:117]
	v_mfma_f32_16x16x32_bf16 v[102:105], v[160:163], v[194:197], v[102:105]
	v_mfma_f32_16x16x32_bf16 v[98:101], v[178:181], v[194:197], v[98:101]
	v_mfma_f32_16x16x32_bf16 v[86:89], v[160:163], v[202:205], v[86:89]
	v_mfma_f32_16x16x32_bf16 v[82:85], v[178:181], v[202:205], v[82:85]
	v_mfma_f32_16x16x32_bf16 v[70:73], v[160:163], v[210:213], v[70:73]
	v_mfma_f32_16x16x32_bf16 v[66:69], v[178:181], v[210:213], v[66:69]
	v_mfma_f32_16x16x32_bf16 v[118:121], v[174:177], v[190:193], v[118:121]
	v_mfma_f32_16x16x32_bf16 v[114:117], v[182:185], v[190:193], v[114:117]
	v_mfma_f32_16x16x32_bf16 v[102:105], v[174:177], v[198:201], v[102:105]
	v_mfma_f32_16x16x32_bf16 v[98:101], v[182:185], v[198:201], v[98:101]
	v_mfma_f32_16x16x32_bf16 v[86:89], v[174:177], v[206:209], v[86:89]
	v_mfma_f32_16x16x32_bf16 v[82:85], v[182:185], v[206:209], v[82:85]
	v_mfma_f32_16x16x32_bf16 v[70:73], v[174:177], v[214:217], v[70:73]
	v_mfma_f32_16x16x32_bf16 v[66:69], v[182:185], v[214:217], v[66:69]
	s_barrier
	s_setprio 0
	s_add_i32 s18, s18, s42
	v_lshl_add_u64 v[164:165], s[10:11], 0, v[142:143]
	s_mov_b32 m0, s18
	ds_read_b128 v[186:189], v172 offset:16384
	ds_read_b128 v[190:193], v172 offset:17408
	ds_read_b128 v[194:197], v172 offset:18432
	ds_read_b128 v[198:201], v172 offset:19456
	ds_read_b128 v[202:205], v172 offset:20480
	ds_read_b128 v[206:209], v172 offset:21504
	ds_read_b128 v[210:213], v172 offset:22528
	ds_read_b128 v[214:217], v172 offset:23552
	global_load_lds_dwordx4 v[164:165], off
	s_add_i32 m0, s18, 0x2000
	s_add_u32 s18, s10, 0x100000
	v_lshl_add_u64 v[218:219], s[10:11], 0, v[138:139]
	s_addc_u32 s19, s11, 0
	s_add_i32 s20, s20, s42
	global_load_lds_dwordx4 v[218:219], off
	v_lshl_add_u64 v[220:221], s[18:19], 0, v[142:143]
	s_mov_b32 m0, s20
	v_lshl_add_u64 v[222:223], s[14:15], 0, v[140:141]
	global_load_lds_dwordx4 v[220:221], off
	v_lshl_add_u64 v[220:221], s[18:19], 0, v[138:139]
	s_add_i32 m0, s20, 0x2000
	s_nop 0
	global_load_lds_dwordx4 v[220:221], off
	v_lshl_add_u64 v[220:221], s[14:15], 0, v[144:145]
	s_mov_b32 m0, s51
	s_nop 0
	global_load_lds_dwordx4 v[220:221], off
	s_mov_b32 m0, s68
	s_nop 0
	global_load_lds_dwordx4 v[222:223], off
	s_waitcnt vmcnt(8)
	s_waitcnt lgkmcnt(0)
	s_setprio 1
	s_barrier
	v_mfma_f32_16x16x32_bf16 v[62:65], v[130:133], v[186:189], v[62:65]
	v_mfma_f32_16x16x32_bf16 v[58:61], v[152:155], v[186:189], v[58:61]
	v_mfma_f32_16x16x32_bf16 v[46:49], v[130:133], v[194:197], v[46:49]
	v_mfma_f32_16x16x32_bf16 v[42:45], v[152:155], v[194:197], v[42:45]
	v_mfma_f32_16x16x32_bf16 v[30:33], v[130:133], v[202:205], v[30:33]
	v_mfma_f32_16x16x32_bf16 v[26:29], v[152:155], v[202:205], v[26:29]
	v_mfma_f32_16x16x32_bf16 v[12:15], v[130:133], v[210:213], v[12:15]
	v_mfma_f32_16x16x32_bf16 v[8:11], v[152:155], v[210:213], v[8:11]
	v_mfma_f32_16x16x32_bf16 v[62:65], v[134:137], v[190:193], v[62:65]
	v_mfma_f32_16x16x32_bf16 v[58:61], v[156:159], v[190:193], v[58:61]
	v_mfma_f32_16x16x32_bf16 v[46:49], v[134:137], v[198:201], v[46:49]
	v_mfma_f32_16x16x32_bf16 v[42:45], v[156:159], v[198:201], v[42:45]
	v_mfma_f32_16x16x32_bf16 v[30:33], v[134:137], v[206:209], v[30:33]
	v_mfma_f32_16x16x32_bf16 v[26:29], v[156:159], v[206:209], v[26:29]
	v_mfma_f32_16x16x32_bf16 v[12:15], v[134:137], v[214:217], v[12:15]
	v_mfma_f32_16x16x32_bf16 v[8:11], v[156:159], v[214:217], v[8:11]
	v_mfma_f32_16x16x32_bf16 v[54:57], v[160:163], v[186:189], v[54:57]
	v_mfma_f32_16x16x32_bf16 v[50:53], v[178:181], v[186:189], v[50:53]
	v_mfma_f32_16x16x32_bf16 v[38:41], v[160:163], v[194:197], v[38:41]
	v_mfma_f32_16x16x32_bf16 v[34:37], v[178:181], v[194:197], v[34:37]
	v_mfma_f32_16x16x32_bf16 v[22:25], v[160:163], v[202:205], v[22:25]
	v_mfma_f32_16x16x32_bf16 v[18:21], v[178:181], v[202:205], v[18:21]
	v_mfma_f32_16x16x32_bf16 v[4:7], v[160:163], v[210:213], v[4:7]
	v_mfma_f32_16x16x32_bf16 v[0:3], v[178:181], v[210:213], v[0:3]
	v_mfma_f32_16x16x32_bf16 v[54:57], v[174:177], v[190:193], v[54:57]
	v_mfma_f32_16x16x32_bf16 v[50:53], v[182:185], v[190:193], v[50:53]
	v_mfma_f32_16x16x32_bf16 v[38:41], v[174:177], v[198:201], v[38:41]
	v_mfma_f32_16x16x32_bf16 v[34:37], v[182:185], v[198:201], v[34:37]
	v_mfma_f32_16x16x32_bf16 v[22:25], v[174:177], v[206:209], v[22:25]
	v_mfma_f32_16x16x32_bf16 v[18:21], v[182:185], v[206:209], v[18:21]
	v_mfma_f32_16x16x32_bf16 v[4:7], v[174:177], v[214:217], v[4:7]
	v_mfma_f32_16x16x32_bf16 v[0:3], v[182:185], v[214:217], v[0:3]
	s_barrier
; #define PG8_STAGEA(bufoff, gbase, voff) PG8_STAGE_X(bufoff, gbase, voff, AUXA)
; #define PG8_LDA(dst, b, h) do { _Pragma("unroll") for (int m = 0; m < 4; ++m) _Pragma("unroll") for (int k = 0; k < 2; ++k) dst[m][k] = *(const PG8_LAS bf16x8*)(lds + PG8_SA(b, h) + aoff + m * 2048 + k * 1024); } while (0)
; #define PG8_LDB(dst, b, h) do { _Pragma("unroll") for (int n = 0; n < 2; ++n) _Pragma("unroll") for (int k = 0; k < 2; ++k) dst[n][k] = *(const PG8_LAS bf16x8*)(lds + PG8_SB(b, h) + boff + n * 2048 + k * 1024); } while (0)
; #define PG8_MMA(ai, bj, At, Bt) do { if (GEMM_PRIO_MODE == 0) __builtin_amdgcn_s_setprio(1); PG8_MMA_LOOPS \
;         acc[ai][bj][m][n] = __builtin_amdgcn_mfma_f32_16x16x32_bf16(Bt[n][k], At[m][k], acc[ai][bj][m][n], 0, 0, 0); if (GEMM_PRIO_MODE == 0) __builtin_amdgcn_s_setprio(0); } while (0)
; #define PG8_WAIT_V(n) asm volatile("s_waitcnt vmcnt(" #n ")" ::: "memory")
; #define PG8_WAIT_L(n) asm volatile("s_waitcnt lgkmcnt(" #n ")" ::: "memory")
; #define PG8_BAR __builtin_amdgcn_s_barrier()
; #define PG8_SCHED __builtin_amdgcn_sched_barrier(0)
;     ...
;             PG8_LDB(B0, 1, 0); PG8_LDB(B1, 1, 1); PG8_SCHED; PG8_LDA(At, 1, 0); PG8_STAGEA(PG8_SA(0, 1), a2 + hstepA, voffA);
;             PG8_WAIT_V(8); PG8_WAIT_L(0); PG8_BAR; PG8_MMA(0, 0, At, B0); PG8_MMA(0, 1, At, B1); PG8_BAR; PG8_SCHED;
	s_setprio 0
	s_add_i32 s18, 0, 0x18000
	v_add_u32_e32 v16, s18, v167
	s_add_i32 s19, 0, 0x1c000
	ds_read_b128 v[130:133], v16
	ds_read_b128 v[134:137], v16 offset:1024
	ds_read_b128 v[152:155], v16 offset:2048
	ds_read_b128 v[156:159], v16 offset:3072
	v_add_u32_e32 v16, s19, v167
	ds_read_b128 v[160:163], v16
	ds_read_b128 v[174:177], v16 offset:1024
	ds_read_b128 v[178:181], v16 offset:2048
	ds_read_b128 v[182:185], v16 offset:3072
	s_add_u32 s14, s14, 0x100000
	s_addc_u32 s15, s15, 0
	s_mov_b32 m0, s69
	v_lshl_add_u64 v[224:225], s[14:15], 0, v[144:145]
	ds_read_b128 v[186:189], v172 offset:32768
	ds_read_b128 v[190:193], v172 offset:33792
	ds_read_b128 v[194:197], v172 offset:34816
	ds_read_b128 v[198:201], v172 offset:35840
	ds_read_b128 v[202:205], v172 offset:36864
	ds_read_b128 v[206:209], v172 offset:37888
	ds_read_b128 v[210:213], v172 offset:38912
	ds_read_b128 v[214:217], v172 offset:39936
	global_load_lds_dwordx4 v[224:225], off
	v_lshl_add_u64 v[224:225], s[14:15], 0, v[140:141]
	s_mov_b32 m0, s72
	s_nop 0
	global_load_lds_dwordx4 v[224:225], off
	s_waitcnt vmcnt(8)
	s_waitcnt lgkmcnt(0)
	s_setprio 1
	s_barrier
	v_mfma_f32_16x16x32_bf16 v[126:129], v[130:133], v[186:189], v[126:129]
	v_mfma_f32_16x16x32_bf16 v[122:125], v[152:155], v[186:189], v[122:125]
	v_mfma_f32_16x16x32_bf16 v[110:113], v[130:133], v[194:197], v[110:113]
	v_mfma_f32_16x16x32_bf16 v[106:109], v[152:155], v[194:197], v[106:109]
	v_mfma_f32_16x16x32_bf16 v[94:97], v[130:133], v[202:205], v[94:97]
	v_mfma_f32_16x16x32_bf16 v[90:93], v[152:155], v[202:205], v[90:93]
	v_mfma_f32_16x16x32_bf16 v[78:81], v[130:133], v[210:213], v[78:81]
	v_mfma_f32_16x16x32_bf16 v[74:77], v[152:155], v[210:213], v[74:77]
	v_mfma_f32_16x16x32_bf16 v[126:129], v[134:137], v[190:193], v[126:129]
	v_mfma_f32_16x16x32_bf16 v[122:125], v[156:159], v[190:193], v[122:125]
	v_mfma_f32_16x16x32_bf16 v[110:113], v[134:137], v[198:201], v[110:113]
	v_mfma_f32_16x16x32_bf16 v[106:109], v[156:159], v[198:201], v[106:109]
	v_mfma_f32_16x16x32_bf16 v[94:97], v[134:137], v[206:209], v[94:97]
	v_mfma_f32_16x16x32_bf16 v[90:93], v[156:159], v[206:209], v[90:93]
	v_mfma_f32_16x16x32_bf16 v[78:81], v[134:137], v[214:217], v[78:81]
	v_mfma_f32_16x16x32_bf16 v[74:77], v[156:159], v[214:217], v[74:77]
	v_mfma_f32_16x16x32_bf16 v[118:121], v[160:163], v[186:189], v[118:121]
	v_mfma_f32_16x16x32_bf16 v[114:117], v[178:181], v[186:189], v[114:117]
	v_mfma_f32_16x16x32_bf16 v[102:105], v[160:163], v[194:197], v[102:105]
	v_mfma_f32_16x16x32_bf16 v[98:101], v[178:181], v[194:197], v[98:101]
	v_mfma_f32_16x16x32_bf16 v[86:89], v[160:163], v[202:205], v[86:89]
	v_mfma_f32_16x16x32_bf16 v[82:85], v[178:181], v[202:205], v[82:85]
	v_mfma_f32_16x16x32_bf16 v[70:73], v[160:163], v[210:213], v[70:73]
	v_mfma_f32_16x16x32_bf16 v[66:69], v[178:181], v[210:213], v[66:69]
	v_mfma_f32_16x16x32_bf16 v[118:121], v[174:177], v[190:193], v[118:121]
	v_mfma_f32_16x16x32_bf16 v[114:117], v[182:185], v[190:193], v[114:117]
	v_mfma_f32_16x16x32_bf16 v[102:105], v[174:177], v[198:201], v[102:105]
	v_mfma_f32_16x16x32_bf16 v[98:101], v[182:185], v[198:201], v[98:101]
	v_mfma_f32_16x16x32_bf16 v[86:89], v[174:177], v[206:209], v[86:89]
	v_mfma_f32_16x16x32_bf16 v[82:85], v[182:185], v[206:209], v[82:85]
	v_mfma_f32_16x16x32_bf16 v[70:73], v[174:177], v[214:217], v[70:73]
	v_mfma_f32_16x16x32_bf16 v[66:69], v[182:185], v[214:217], v[66:69]
	s_barrier
; #define PG8_STAGEA(bufoff, gbase, voff) PG8_STAGE_X(bufoff, gbase, voff, AUXA)
; #define PG8_STAGEB(bufoff, gbase, voff) PG8_STAGE_X(bufoff, gbase, voff, AUXB)
; #define PG8_LDA(dst, b, h) do { _Pragma("unroll") for (int m = 0; m < 4; ++m) _Pragma("unroll") for (int k = 0; k < 2; ++k) dst[m][k] = *(const PG8_LAS bf16x8*)(lds + PG8_SA(b, h) + aoff + m * 2048 + k * 1024); } while (0)
; #define PG8_MMA(ai, bj, At, Bt) do { if (GEMM_PRIO_MODE == 0) __builtin_amdgcn_s_setprio(1); PG8_MMA_LOOPS \
;         acc[ai][bj][m][n] = __builtin_amdgcn_mfma_f32_16x16x32_bf16(Bt[n][k], At[m][k], acc[ai][bj][m][n], 0, 0, 0); if (GEMM_PRIO_MODE == 0) __builtin_amdgcn_s_setprio(0); } while (0)
; #define PG8_WAIT_V(n) asm volatile("s_waitcnt vmcnt(" #n ")" ::: "memory")
; #define PG8_WAIT_L(n) asm volatile("s_waitcnt lgkmcnt(" #n ")" ::: "memory")
; #define PG8_BAR __builtin_amdgcn_s_barrier()
; #define PG8_SCHED __builtin_amdgcn_sched_barrier(0)
;     ...
;             PG8_LDA(At, 1, 1); PG8_STAGEB(PG8_SB(1, 0), b3, voffB); PG8_STAGEB(PG8_SB(1, 1), b3 + hstepB, voffB); PG8_STAGEA(PG8_SA(1, 0), a3, voffA);
;             PG8_WAIT_V(8); PG8_WAIT_L(0); PG8_BAR; PG8_MMA(1, 0, At, B0); PG8_MMA(1, 1, At, B1); PG8_BAR; PG8_SCHED;
;     ...
;         }
;         if constexpr (ALIGN_EPI) { if (wr == 0) PG8_BAR; }
	s_setprio 0
	s_add_i32 s14, s18, s42
	v_lshl_add_u64 v[164:165], v[164:165], 0, s[86:87]
	s_mov_b32 m0, s14
	ds_read_b128 v[186:189], v172 offset:49152
	ds_read_b128 v[190:193], v172 offset:50176
	ds_read_b128 v[194:197], v172 offset:51200
	ds_read_b128 v[198:201], v172 offset:52224
	ds_read_b128 v[202:205], v172 offset:53248
	ds_read_b128 v[206:209], v172 offset:54272
	ds_read_b128 v[210:213], v172 offset:55296
	ds_read_b128 v[214:217], v172 offset:56320
	global_load_lds_dwordx4 v[164:165], off
	s_add_i32 m0, s14, 0x2000
	s_add_u32 s10, s10, 0x100080
	v_lshl_add_u64 v[164:165], v[218:219], 0, s[86:87]
	s_addc_u32 s11, s11, 0
	s_add_i32 s14, s19, s42
	global_load_lds_dwordx4 v[164:165], off
	v_lshl_add_u64 v[164:165], s[10:11], 0, v[142:143]
	s_mov_b32 m0, s14
	s_nop 0
	global_load_lds_dwordx4 v[164:165], off
	v_lshl_add_u64 v[164:165], s[10:11], 0, v[138:139]
	s_add_i32 m0, s14, 0x2000
	s_nop 0
	global_load_lds_dwordx4 v[164:165], off
	v_lshl_add_u64 v[164:165], v[220:221], 0, s[86:87]
	s_mov_b32 m0, s73
	s_nop 0
	global_load_lds_dwordx4 v[164:165], off
	v_lshl_add_u64 v[164:165], v[222:223], 0, s[86:87]
	s_mov_b32 m0, s82
	s_nop 0
	global_load_lds_dwordx4 v[164:165], off
	s_waitcnt vmcnt(8)
	s_waitcnt lgkmcnt(0)
	s_nop 0
	s_setprio 1
	s_barrier
	v_mfma_f32_16x16x32_bf16 v[62:65], v[130:133], v[186:189], v[62:65]
	v_mfma_f32_16x16x32_bf16 v[58:61], v[152:155], v[186:189], v[58:61]
	v_mfma_f32_16x16x32_bf16 v[46:49], v[130:133], v[194:197], v[46:49]
	v_mfma_f32_16x16x32_bf16 v[42:45], v[152:155], v[194:197], v[42:45]
	v_mfma_f32_16x16x32_bf16 v[30:33], v[130:133], v[202:205], v[30:33]
	v_mfma_f32_16x16x32_bf16 v[26:29], v[152:155], v[202:205], v[26:29]
	v_mfma_f32_16x16x32_bf16 v[12:15], v[130:133], v[210:213], v[12:15]
	v_mfma_f32_16x16x32_bf16 v[8:11], v[152:155], v[210:213], v[8:11]
	v_mfma_f32_16x16x32_bf16 v[62:65], v[134:137], v[190:193], v[62:65]
	v_mfma_f32_16x16x32_bf16 v[58:61], v[156:159], v[190:193], v[58:61]
	v_mfma_f32_16x16x32_bf16 v[46:49], v[134:137], v[198:201], v[46:49]
	v_mfma_f32_16x16x32_bf16 v[42:45], v[156:159], v[198:201], v[42:45]
	v_mfma_f32_16x16x32_bf16 v[30:33], v[134:137], v[206:209], v[30:33]
	v_mfma_f32_16x16x32_bf16 v[26:29], v[156:159], v[206:209], v[26:29]
	v_mfma_f32_16x16x32_bf16 v[12:15], v[134:137], v[214:217], v[12:15]
	v_mfma_f32_16x16x32_bf16 v[8:11], v[156:159], v[214:217], v[8:11]
	v_mfma_f32_16x16x32_bf16 v[54:57], v[160:163], v[186:189], v[54:57]
	v_mfma_f32_16x16x32_bf16 v[50:53], v[178:181], v[186:189], v[50:53]
	v_mfma_f32_16x16x32_bf16 v[38:41], v[160:163], v[194:197], v[38:41]
	v_mfma_f32_16x16x32_bf16 v[34:37], v[178:181], v[194:197], v[34:37]
	v_mfma_f32_16x16x32_bf16 v[22:25], v[160:163], v[202:205], v[22:25]
	v_mfma_f32_16x16x32_bf16 v[18:21], v[178:181], v[202:205], v[18:21]
	v_mfma_f32_16x16x32_bf16 v[4:7], v[160:163], v[210:213], v[4:7]
	v_mfma_f32_16x16x32_bf16 v[0:3], v[178:181], v[210:213], v[0:3]
	v_mfma_f32_16x16x32_bf16 v[54:57], v[174:177], v[190:193], v[54:57]
	v_mfma_f32_16x16x32_bf16 v[50:53], v[182:185], v[190:193], v[50:53]
	v_mfma_f32_16x16x32_bf16 v[38:41], v[174:177], v[198:201], v[38:41]
	v_mfma_f32_16x16x32_bf16 v[34:37], v[182:185], v[198:201], v[34:37]
	v_mfma_f32_16x16x32_bf16 v[22:25], v[174:177], v[206:209], v[22:25]
	v_mfma_f32_16x16x32_bf16 v[18:21], v[182:185], v[206:209], v[18:21]
	v_mfma_f32_16x16x32_bf16 v[4:7], v[174:177], v[214:217], v[4:7]
	v_mfma_f32_16x16x32_bf16 v[0:3], v[182:185], v[214:217], v[0:3]
	s_barrier
	s_setprio 0
	s_add_i32 s27, s27, 2
	s_add_u32 s8, s8, 0x100
	s_addc_u32 s9, s9, 0
	s_add_u32 s0, s0, 0x100
	s_addc_u32 s1, s1, 0
	s_cmp_gt_u32 s27, 61
	s_cbranch_scc0 .LBB0_129
	s_and_b64 vcc, exec, s[24:25]
	s_cbranch_vccz .LBB0_132
	s_barrier

; #define PG8_STAGEA(bufoff, gbase, voff) PG8_STAGE_X(bufoff, gbase, voff, AUXA)
; #define PG8_STAGEB(bufoff, gbase, voff) PG8_STAGE_X(bufoff, gbase, voff, AUXB)
; #define PG8_LDA(dst, b, h) do { _Pragma("unroll") for (int m = 0; m < 4; ++m) _Pragma("unroll") for (int k = 0; k < 2; ++k) dst[m][k] = *(const PG8_LAS bf16x8*)(lds + PG8_SA(b, h) + aoff + m * 2048 + k * 1024); } while (0)
; #define PG8_LDB(dst, b, h) do { _Pragma("unroll") for (int n = 0; n < 2; ++n) _Pragma("unroll") for (int k = 0; k < 2; ++k) dst[n][k] = *(const PG8_LAS bf16x8*)(lds + PG8_SB(b, h) + boff + n * 2048 + k * 1024); } while (0)
; #define PG8_MMA(ai, bj, At, Bt) do { if (GEMM_PRIO_MODE == 0) __builtin_amdgcn_s_setprio(1); PG8_MMA_LOOPS \
;         acc[ai][bj][m][n] = __builtin_amdgcn_mfma_f32_16x16x32_bf16(Bt[n][k], At[m][k], acc[ai][bj][m][n], 0, 0, 0); if (GEMM_PRIO_MODE == 0) __builtin_amdgcn_s_setprio(0); } while (0)
; #define PG8_WAIT_V(n) asm volatile("s_waitcnt vmcnt(" #n ")" ::: "memory")
; #define PG8_WAIT_VR(n, nr, flag) asm volatile("s_cmp_eq_u32 %0, 0\n\ts_cbranch_scc1 .Lpg8s%=\n\ts_waitcnt vmcnt(" #nr ")\n\ts_branch .Lpg8d%=\n.Lpg8s%=:\n\ts_waitcnt vmcnt(" #n ")\n.Lpg8d%=:" :: "s"(flag) : "memory", "scc")
; #define PG8_WAIT_L(n) asm volatile("s_waitcnt lgkmcnt(" #n ")" ::: "memory")
;     ...
;         for (int t = t0; t < nt; t += 2) {
;             const bool last = (t == nt - 2);
;             const char* a1 = cA + (size_t)(t + 1) * kstepA;
;             const char* a2 = last ? nA : cA + (size_t)(t + 2) * kstepA; const char* b2 = last ? nB : cB + (size_t)(t + 2) * kstepB;
;             const char* a3 = a2 + kstepA; const char* b3 = b2 + kstepB;
;             if (last && has_next) S.a_ready(nxt);
;             if constexpr (SP2) {
;             PG8_LDB(B0, 0, 0); PG8_LDB(B1, 0, 1); PG8_SCHED; PG8_LDA(At, 0, 0); PG8_STAGEA(PG8_SA(1, 1), a1 + hstepA, voffA);
;     ...
;             const int relax = __builtin_amdgcn_readfirstlane((t == 0 && ui > 0) ? 1 : 0);
;             PG8_WAIT_VR(8, 24, relax); PG8_WAIT_L(0); PG8_BAR; PG8_MMA(0, 0, At, B0); PG8_MMA(0, 1, At, B1); PG8_BAR; PG8_SCHED;
;     ...
;             PG8_WAIT_V(8); PG8_WAIT_L(0); PG8_BAR; PG8_MMA(0, 0, At, B0); PG8_MMA(0, 1, At, B1); PG8_BAR; PG8_SCHED;
;     ...
;             PG8_LDA(At, 0, 1); PG8_STAGEB(PG8_SB(0, 0), b2, voffB); PG8_STAGEB(PG8_SB(0, 1), b2 + hstepB, voffB); PG8_STAGEA(PG8_SA(0, 0), a2, voffA);
.LBB0_557:
	s_ashr_i32 s21, s20, 31
	s_lshl_b64 s[6:7], s[20:21], 21
	s_add_u32 s24, s60, s6
	s_addc_u32 s25, s61, s7
	s_and_b64 s[6:7], s[26:27], exec
	s_cselect_b32 s21, s25, s1
	s_cselect_b32 s82, s24, s0
	s_ashr_i32 s23, s22, 31
	s_lshl_b64 s[6:7], s[22:23], 21
	s_add_u32 s36, s4, s6
	s_addc_u32 s37, s5, s7
	s_and_b64 s[6:7], s[26:27], exec
	s_cselect_b32 s23, s37, s41
	s_cselect_b32 s83, s36, s40
	s_add_u32 s38, s0, 0x100080
	s_addc_u32 s39, s1, 0
	s_add_u32 s0, s40, 0x100
	s_addc_u32 s1, s41, 0
	s_mov_b32 s90, -2
	s_waitcnt lgkmcnt(0)
	s_waitcnt vmcnt(0)
	s_add_u32 s6, s38, 0xfff00080
	s_addc_u32 s7, s39, -1
	s_add_i32 s91, 0, 0x10000
	s_cmp_eq_u32 s90, 60
	s_cselect_b32 s41, s21, s7
	s_cselect_b32 s40, s82, s6
	s_cselect_b32 s17, s23, s1
	s_cselect_b32 s16, s83, s0
	s_add_i32 s94, 0, 0x14000
	v_add_u32_e32 v152, s91, v157
	v_add_u32_e32 v174, s94, v157
	ds_read_b128 v[130:133], v152
	ds_read_b128 v[134:137], v152 offset:1024
	ds_read_b128 v[148:151], v152 offset:2048
	ds_read_b128 v[152:155], v152 offset:3072
	ds_read_b128 v[162:165], v174
	ds_read_b128 v[166:169], v174 offset:1024
	ds_read_b128 v[170:173], v174 offset:2048
	ds_read_b128 v[174:177], v174 offset:3072
	v_lshl_add_u64 v[210:211], s[38:39], 0, v[144:145]
	s_add_i32 m0, s13, 0xc000
	ds_read_b128 v[178:181], v161
	ds_read_b128 v[182:185], v161 offset:1024
	ds_read_b128 v[186:189], v161 offset:2048
	ds_read_b128 v[190:193], v161 offset:3072
	ds_read_b128 v[194:197], v161 offset:4096
	ds_read_b128 v[198:201], v161 offset:5120
	ds_read_b128 v[202:205], v161 offset:6144
	ds_read_b128 v[206:209], v161 offset:7168
	global_load_lds_dwordx4 v[210:211], off
	v_lshl_add_u64 v[210:211], s[38:39], 0, v[146:147]
	s_add_i32 m0, s13, 0xe000
	s_nop 0
	global_load_lds_dwordx4 v[210:211], off
	s_waitcnt vmcnt(8)
	s_waitcnt lgkmcnt(0)
	s_setprio 1
	s_barrier
	v_mfma_f32_16x16x32_bf16 v[126:129], v[130:133], v[178:181], 0
	v_mfma_f32_16x16x32_bf16 v[122:125], v[148:151], v[178:181], 0
	v_mfma_f32_16x16x32_bf16 v[110:113], v[130:133], v[186:189], 0
	v_mfma_f32_16x16x32_bf16 v[106:109], v[148:151], v[186:189], 0
	v_mfma_f32_16x16x32_bf16 v[94:97], v[130:133], v[194:197], 0
	v_mfma_f32_16x16x32_bf16 v[90:93], v[148:151], v[194:197], 0
	v_mfma_f32_16x16x32_bf16 v[78:81], v[130:133], v[202:205], 0
	v_mfma_f32_16x16x32_bf16 v[74:77], v[148:151], v[202:205], 0
	v_mfma_f32_16x16x32_bf16 v[126:129], v[134:137], v[182:185], v[126:129]
	v_mfma_f32_16x16x32_bf16 v[122:125], v[152:155], v[182:185], v[122:125]
	v_mfma_f32_16x16x32_bf16 v[110:113], v[134:137], v[190:193], v[110:113]
	v_mfma_f32_16x16x32_bf16 v[106:109], v[152:155], v[190:193], v[106:109]
	v_mfma_f32_16x16x32_bf16 v[94:97], v[134:137], v[198:201], v[94:97]
	v_mfma_f32_16x16x32_bf16 v[90:93], v[152:155], v[198:201], v[90:93]
	v_mfma_f32_16x16x32_bf16 v[78:81], v[134:137], v[206:209], v[78:81]
	v_mfma_f32_16x16x32_bf16 v[74:77], v[152:155], v[206:209], v[74:77]
	v_mfma_f32_16x16x32_bf16 v[118:121], v[162:165], v[178:181], 0
	v_mfma_f32_16x16x32_bf16 v[114:117], v[170:173], v[178:181], 0
	v_mfma_f32_16x16x32_bf16 v[102:105], v[162:165], v[186:189], 0
	v_mfma_f32_16x16x32_bf16 v[98:101], v[170:173], v[186:189], 0
	v_mfma_f32_16x16x32_bf16 v[86:89], v[162:165], v[194:197], 0
	v_mfma_f32_16x16x32_bf16 v[82:85], v[170:173], v[194:197], 0
	v_mfma_f32_16x16x32_bf16 v[70:73], v[162:165], v[202:205], 0
	v_mfma_f32_16x16x32_bf16 v[66:69], v[170:173], v[202:205], 0
	v_mfma_f32_16x16x32_bf16 v[118:121], v[166:169], v[182:185], v[118:121]
	v_mfma_f32_16x16x32_bf16 v[114:117], v[174:177], v[182:185], v[114:117]
	v_mfma_f32_16x16x32_bf16 v[102:105], v[166:169], v[190:193], v[102:105]
	v_mfma_f32_16x16x32_bf16 v[98:101], v[174:177], v[190:193], v[98:101]
	v_mfma_f32_16x16x32_bf16 v[86:89], v[166:169], v[198:201], v[86:89]
	v_mfma_f32_16x16x32_bf16 v[82:85], v[174:177], v[198:201], v[82:85]
	v_mfma_f32_16x16x32_bf16 v[70:73], v[166:169], v[206:209], v[70:73]
	v_mfma_f32_16x16x32_bf16 v[66:69], v[174:177], v[206:209], v[66:69]
	s_barrier
	s_setprio 0
	s_add_i32 s6, s91, s12
	v_lshl_add_u64 v[210:211], s[16:17], 0, v[16:17]
	s_mov_b32 m0, s6
	ds_read_b128 v[178:181], v161 offset:16384
	ds_read_b128 v[182:185], v161 offset:17408
	ds_read_b128 v[186:189], v161 offset:18432
	ds_read_b128 v[190:193], v161 offset:19456
	ds_read_b128 v[194:197], v161 offset:20480
	ds_read_b128 v[198:201], v161 offset:21504
	ds_read_b128 v[202:205], v161 offset:22528
	ds_read_b128 v[206:209], v161 offset:23552
	global_load_lds_dwordx4 v[210:211], off
	s_add_i32 m0, s6, 0x2000
	s_add_u32 s6, s16, 0x100000
	v_lshl_add_u64 v[212:213], s[16:17], 0, v[138:139]
	s_addc_u32 s7, s17, 0
	s_add_i32 s91, s94, s12
	global_load_lds_dwordx4 v[212:213], off
	v_lshl_add_u64 v[214:215], s[6:7], 0, v[16:17]
	s_mov_b32 m0, s91
	v_lshl_add_u64 v[216:217], s[40:41], 0, v[140:141]
	global_load_lds_dwordx4 v[214:215], off
	v_lshl_add_u64 v[214:215], s[6:7], 0, v[138:139]
	s_add_i32 m0, s91, 0x2000
	s_nop 0
	global_load_lds_dwordx4 v[214:215], off
	v_lshl_add_u64 v[214:215], s[40:41], 0, v[142:143]
	s_mov_b32 m0, s13
	s_nop 0
	global_load_lds_dwordx4 v[214:215], off
	s_mov_b32 m0, s42
	s_nop 0
	global_load_lds_dwordx4 v[216:217], off
	s_waitcnt vmcnt(8)
	s_waitcnt lgkmcnt(0)
	s_setprio 1
	s_barrier
; #define PG8_STAGEA(bufoff, gbase, voff) PG8_STAGE_X(bufoff, gbase, voff, AUXA)
; #define PG8_STAGEB(bufoff, gbase, voff) PG8_STAGE_X(bufoff, gbase, voff, AUXB)
; #define PG8_LDA(dst, b, h) do { _Pragma("unroll") for (int m = 0; m < 4; ++m) _Pragma("unroll") for (int k = 0; k < 2; ++k) dst[m][k] = *(const PG8_LAS bf16x8*)(lds + PG8_SA(b, h) + aoff + m * 2048 + k * 1024); } while (0)
; #define PG8_LDB(dst, b, h) do { _Pragma("unroll") for (int n = 0; n < 2; ++n) _Pragma("unroll") for (int k = 0; k < 2; ++k) dst[n][k] = *(const PG8_LAS bf16x8*)(lds + PG8_SB(b, h) + boff + n * 2048 + k * 1024); } while (0)
; #define PG8_MMA(ai, bj, At, Bt) do { if (GEMM_PRIO_MODE == 0) __builtin_amdgcn_s_setprio(1); PG8_MMA_LOOPS \
;         acc[ai][bj][m][n] = __builtin_amdgcn_mfma_f32_16x16x32_bf16(Bt[n][k], At[m][k], acc[ai][bj][m][n], 0, 0, 0); if (GEMM_PRIO_MODE == 0) __builtin_amdgcn_s_setprio(0); } while (0)
; #define PG8_WAIT_V(n) asm volatile("s_waitcnt vmcnt(" #n ")" ::: "memory")
; #define PG8_WAIT_VR(n, nr, flag) asm volatile("s_cmp_eq_u32 %0, 0\n\ts_cbranch_scc1 .Lpg8s%=\n\ts_waitcnt vmcnt(" #nr ")\n\ts_branch .Lpg8d%=\n.Lpg8s%=:\n\ts_waitcnt vmcnt(" #n ")\n.Lpg8d%=:" :: "s"(flag) : "memory", "scc")
; #define PG8_WAIT_L(n) asm volatile("s_waitcnt lgkmcnt(" #n ")" ::: "memory")
; #define PG8_BAR __builtin_amdgcn_s_barrier()
; #define PG8_SCHED __builtin_amdgcn_sched_barrier(0)
;     ...
;             PG8_WAIT_VR(8, 24, relax); PG8_WAIT_L(0); PG8_BAR; PG8_MMA(1, 0, At, B0); PG8_MMA(1, 1, At, B1); PG8_BAR; PG8_SCHED;
;     ...
;             PG8_WAIT_V(8); PG8_WAIT_L(0); PG8_BAR; PG8_MMA(1, 0, At, B0); PG8_MMA(1, 1, At, B1); PG8_BAR; PG8_SCHED;
;     ...
;             PG8_LDB(B0, 1, 0); PG8_LDB(B1, 1, 1); PG8_SCHED; PG8_LDA(At, 1, 0); PG8_STAGEA(PG8_SA(0, 1), a2 + hstepA, voffA);
;             PG8_WAIT_V(8); PG8_WAIT_L(0); PG8_BAR; PG8_MMA(0, 0, At, B0); PG8_MMA(0, 1, At, B1); PG8_BAR; PG8_SCHED;
;             PG8_LDA(At, 1, 1); PG8_STAGEB(PG8_SB(1, 0), b3, voffB); PG8_STAGEB(PG8_SB(1, 1), b3 + hstepB, voffB); PG8_STAGEA(PG8_SA(1, 0), a3, voffA);
	v_mfma_f32_16x16x32_bf16 v[62:65], v[130:133], v[178:181], 0
	v_mfma_f32_16x16x32_bf16 v[58:61], v[148:151], v[178:181], 0
	v_mfma_f32_16x16x32_bf16 v[46:49], v[130:133], v[186:189], 0
	v_mfma_f32_16x16x32_bf16 v[42:45], v[148:151], v[186:189], 0
	v_mfma_f32_16x16x32_bf16 v[30:33], v[130:133], v[194:197], 0
	v_mfma_f32_16x16x32_bf16 v[26:29], v[148:151], v[194:197], 0
	v_mfma_f32_16x16x32_bf16 v[12:15], v[130:133], v[202:205], 0
	v_mfma_f32_16x16x32_bf16 v[8:11], v[148:151], v[202:205], 0
	v_mfma_f32_16x16x32_bf16 v[62:65], v[134:137], v[182:185], v[62:65]
	v_mfma_f32_16x16x32_bf16 v[58:61], v[152:155], v[182:185], v[58:61]
	v_mfma_f32_16x16x32_bf16 v[46:49], v[134:137], v[190:193], v[46:49]
	v_mfma_f32_16x16x32_bf16 v[42:45], v[152:155], v[190:193], v[42:45]
	v_mfma_f32_16x16x32_bf16 v[30:33], v[134:137], v[198:201], v[30:33]
	v_mfma_f32_16x16x32_bf16 v[26:29], v[152:155], v[198:201], v[26:29]
	v_mfma_f32_16x16x32_bf16 v[12:15], v[134:137], v[206:209], v[12:15]
	v_mfma_f32_16x16x32_bf16 v[8:11], v[152:155], v[206:209], v[8:11]
	v_mfma_f32_16x16x32_bf16 v[54:57], v[162:165], v[178:181], 0
	v_mfma_f32_16x16x32_bf16 v[50:53], v[170:173], v[178:181], 0
	v_mfma_f32_16x16x32_bf16 v[38:41], v[162:165], v[186:189], 0
	v_mfma_f32_16x16x32_bf16 v[34:37], v[170:173], v[186:189], 0
	v_mfma_f32_16x16x32_bf16 v[22:25], v[162:165], v[194:197], 0
	v_mfma_f32_16x16x32_bf16 v[18:21], v[170:173], v[194:197], 0
	v_mfma_f32_16x16x32_bf16 v[4:7], v[162:165], v[202:205], 0
	v_mfma_f32_16x16x32_bf16 v[0:3], v[170:173], v[202:205], 0
	v_mfma_f32_16x16x32_bf16 v[54:57], v[166:169], v[182:185], v[54:57]
	v_mfma_f32_16x16x32_bf16 v[50:53], v[174:177], v[182:185], v[50:53]
	v_mfma_f32_16x16x32_bf16 v[38:41], v[166:169], v[190:193], v[38:41]
	v_mfma_f32_16x16x32_bf16 v[34:37], v[174:177], v[190:193], v[34:37]
	v_mfma_f32_16x16x32_bf16 v[22:25], v[166:169], v[198:201], v[22:25]
	v_mfma_f32_16x16x32_bf16 v[18:21], v[174:177], v[198:201], v[18:21]
	v_mfma_f32_16x16x32_bf16 v[4:7], v[166:169], v[206:209], v[4:7]
	v_mfma_f32_16x16x32_bf16 v[0:3], v[174:177], v[206:209], v[0:3]
	s_barrier
	s_setprio 0
	s_add_i32 s91, 0, 0x18000
	s_add_i32 s94, 0, 0x1c000
	v_add_u32_e32 v152, s91, v157
	v_add_u32_e32 v174, s94, v157
	ds_read_b128 v[130:133], v152
	ds_read_b128 v[134:137], v152 offset:1024
	ds_read_b128 v[148:151], v152 offset:2048
	ds_read_b128 v[152:155], v152 offset:3072
	ds_read_b128 v[162:165], v174
	ds_read_b128 v[166:169], v174 offset:1024
	ds_read_b128 v[170:173], v174 offset:2048
	ds_read_b128 v[174:177], v174 offset:3072
	s_add_u32 s6, s40, 0x100000
	s_addc_u32 s7, s41, 0
	s_mov_b32 m0, s43
	v_lshl_add_u64 v[218:219], s[6:7], 0, v[142:143]
	ds_read_b128 v[178:181], v161 offset:32768
	ds_read_b128 v[182:185], v161 offset:33792
	ds_read_b128 v[186:189], v161 offset:34816
	ds_read_b128 v[190:193], v161 offset:35840
	ds_read_b128 v[194:197], v161 offset:36864
	ds_read_b128 v[198:201], v161 offset:37888
	ds_read_b128 v[202:205], v161 offset:38912
	ds_read_b128 v[206:209], v161 offset:39936
	global_load_lds_dwordx4 v[218:219], off
	v_lshl_add_u64 v[218:219], s[6:7], 0, v[140:141]
	s_mov_b32 m0, s50
	s_nop 0
	global_load_lds_dwordx4 v[218:219], off
	s_waitcnt vmcnt(8)
	s_waitcnt lgkmcnt(0)
	s_setprio 1
	s_barrier
	v_mfma_f32_16x16x32_bf16 v[126:129], v[130:133], v[178:181], v[126:129]
	v_mfma_f32_16x16x32_bf16 v[122:125], v[148:151], v[178:181], v[122:125]
	v_mfma_f32_16x16x32_bf16 v[110:113], v[130:133], v[186:189], v[110:113]
	v_mfma_f32_16x16x32_bf16 v[106:109], v[148:151], v[186:189], v[106:109]
	v_mfma_f32_16x16x32_bf16 v[94:97], v[130:133], v[194:197], v[94:97]
	v_mfma_f32_16x16x32_bf16 v[90:93], v[148:151], v[194:197], v[90:93]
	v_mfma_f32_16x16x32_bf16 v[78:81], v[130:133], v[202:205], v[78:81]
	v_mfma_f32_16x16x32_bf16 v[74:77], v[148:151], v[202:205], v[74:77]
	v_mfma_f32_16x16x32_bf16 v[126:129], v[134:137], v[182:185], v[126:129]
	v_mfma_f32_16x16x32_bf16 v[122:125], v[152:155], v[182:185], v[122:125]
	v_mfma_f32_16x16x32_bf16 v[110:113], v[134:137], v[190:193], v[110:113]
	v_mfma_f32_16x16x32_bf16 v[106:109], v[152:155], v[190:193], v[106:109]
	v_mfma_f32_16x16x32_bf16 v[94:97], v[134:137], v[198:201], v[94:97]
	v_mfma_f32_16x16x32_bf16 v[90:93], v[152:155], v[198:201], v[90:93]
	v_mfma_f32_16x16x32_bf16 v[78:81], v[134:137], v[206:209], v[78:81]
	v_mfma_f32_16x16x32_bf16 v[74:77], v[152:155], v[206:209], v[74:77]
	v_mfma_f32_16x16x32_bf16 v[118:121], v[162:165], v[178:181], v[118:121]
	v_mfma_f32_16x16x32_bf16 v[114:117], v[170:173], v[178:181], v[114:117]
	v_mfma_f32_16x16x32_bf16 v[102:105], v[162:165], v[186:189], v[102:105]
	v_mfma_f32_16x16x32_bf16 v[98:101], v[170:173], v[186:189], v[98:101]
	v_mfma_f32_16x16x32_bf16 v[86:89], v[162:165], v[194:197], v[86:89]
	v_mfma_f32_16x16x32_bf16 v[82:85], v[170:173], v[194:197], v[82:85]
	v_mfma_f32_16x16x32_bf16 v[70:73], v[162:165], v[202:205], v[70:73]
	v_mfma_f32_16x16x32_bf16 v[66:69], v[170:173], v[202:205], v[66:69]
	v_mfma_f32_16x16x32_bf16 v[118:121], v[166:169], v[182:185], v[118:121]
	v_mfma_f32_16x16x32_bf16 v[114:117], v[174:177], v[182:185], v[114:117]
	v_mfma_f32_16x16x32_bf16 v[102:105], v[166:169], v[190:193], v[102:105]
	v_mfma_f32_16x16x32_bf16 v[98:101], v[174:177], v[190:193], v[98:101]
	v_mfma_f32_16x16x32_bf16 v[86:89], v[166:169], v[198:201], v[86:89]
	v_mfma_f32_16x16x32_bf16 v[82:85], v[174:177], v[198:201], v[82:85]
	v_mfma_f32_16x16x32_bf16 v[70:73], v[166:169], v[206:209], v[70:73]
	v_mfma_f32_16x16x32_bf16 v[66:69], v[174:177], v[206:209], v[66:69]
	s_barrier
; #define PG8_STAGEA(bufoff, gbase, voff) PG8_STAGE_X(bufoff, gbase, voff, AUXA)
; #define PG8_STAGEB(bufoff, gbase, voff) PG8_STAGE_X(bufoff, gbase, voff, AUXB)
; #define PG8_LDA(dst, b, h) do { _Pragma("unroll") for (int m = 0; m < 4; ++m) _Pragma("unroll") for (int k = 0; k < 2; ++k) dst[m][k] = *(const PG8_LAS bf16x8*)(lds + PG8_SA(b, h) + aoff + m * 2048 + k * 1024); } while (0)
; #define PG8_LDB(dst, b, h) do { _Pragma("unroll") for (int n = 0; n < 2; ++n) _Pragma("unroll") for (int k = 0; k < 2; ++k) dst[n][k] = *(const PG8_LAS bf16x8*)(lds + PG8_SB(b, h) + boff + n * 2048 + k * 1024); } while (0)
; #define PG8_MMA(ai, bj, At, Bt) do { if (GEMM_PRIO_MODE == 0) __builtin_amdgcn_s_setprio(1); PG8_MMA_LOOPS \
;         acc[ai][bj][m][n] = __builtin_amdgcn_mfma_f32_16x16x32_bf16(Bt[n][k], At[m][k], acc[ai][bj][m][n], 0, 0, 0); if (GEMM_PRIO_MODE == 0) __builtin_amdgcn_s_setprio(0); } while (0)
; #define PG8_WAIT_V(n) asm volatile("s_waitcnt vmcnt(" #n ")" ::: "memory")
; #define PG8_WAIT_L(n) asm volatile("s_waitcnt lgkmcnt(" #n ")" ::: "memory")
; #define PG8_BAR __builtin_amdgcn_s_barrier()
; #define PG8_SCHED __builtin_amdgcn_sched_barrier(0)
;     ...
;         for (int t = t0; t < nt; t += 2) {
;             const bool last = (t == nt - 2);
;             const char* a1 = cA + (size_t)(t + 1) * kstepA;
;             const char* a2 = last ? nA : cA + (size_t)(t + 2) * kstepA; const char* b2 = last ? nB : cB + (size_t)(t + 2) * kstepB;
;             const char* a3 = a2 + kstepA; const char* b3 = b2 + kstepB;
;             if (last && has_next) S.a_ready(nxt);
;             if constexpr (SP2) {
;             PG8_LDB(B0, 0, 0); PG8_LDB(B1, 0, 1); PG8_SCHED; PG8_LDA(At, 0, 0); PG8_STAGEA(PG8_SA(1, 1), a1 + hstepA, voffA);
;     ...
;             const int relax = __builtin_amdgcn_readfirstlane((t == 0 && ui > 0) ? 1 : 0);
;             PG8_WAIT_VR(8, 24, relax); PG8_WAIT_L(0); PG8_BAR; PG8_MMA(0, 0, At, B0); PG8_MMA(0, 1, At, B1); PG8_BAR; PG8_SCHED;
;     ...
;             PG8_WAIT_V(8); PG8_WAIT_L(0); PG8_BAR; PG8_MMA(0, 0, At, B0); PG8_MMA(0, 1, At, B1); PG8_BAR; PG8_SCHED;
;     ...
;             PG8_LDA(At, 1, 1); PG8_STAGEB(PG8_SB(1, 0), b3, voffB); PG8_STAGEB(PG8_SB(1, 1), b3 + hstepB, voffB); PG8_STAGEA(PG8_SA(1, 0), a3, voffA);
;             PG8_WAIT_V(8); PG8_WAIT_L(0); PG8_BAR; PG8_MMA(1, 0, At, B0); PG8_MMA(1, 1, At, B1); PG8_BAR; PG8_SCHED;
	s_setprio 0
	s_add_i32 s6, s91, s12
	v_lshl_add_u64 v[210:211], v[210:211], 0, s[86:87]
	s_mov_b32 m0, s6
	ds_read_b128 v[178:181], v161 offset:49152
	ds_read_b128 v[182:185], v161 offset:50176
	ds_read_b128 v[186:189], v161 offset:51200
	ds_read_b128 v[190:193], v161 offset:52224
	ds_read_b128 v[194:197], v161 offset:53248
	ds_read_b128 v[198:201], v161 offset:54272
	ds_read_b128 v[202:205], v161 offset:55296
	ds_read_b128 v[206:209], v161 offset:56320
	global_load_lds_dwordx4 v[210:211], off
	s_add_i32 m0, s6, 0x2000
	s_add_u32 s6, s16, 0x100080
	v_lshl_add_u64 v[210:211], v[212:213], 0, s[86:87]
	s_addc_u32 s7, s17, 0
	s_add_i32 s16, s94, s12
	global_load_lds_dwordx4 v[210:211], off
	v_lshl_add_u64 v[210:211], s[6:7], 0, v[16:17]
	s_mov_b32 m0, s16
	s_nop 0
	global_load_lds_dwordx4 v[210:211], off
	v_lshl_add_u64 v[210:211], s[6:7], 0, v[138:139]
	s_add_i32 m0, s16, 0x2000
	s_nop 0
	global_load_lds_dwordx4 v[210:211], off
	v_lshl_add_u64 v[210:211], v[214:215], 0, s[86:87]
	s_mov_b32 m0, s68
	s_nop 0
	global_load_lds_dwordx4 v[210:211], off
	v_lshl_add_u64 v[210:211], v[216:217], 0, s[86:87]
	s_mov_b32 m0, s69
	s_nop 0
	global_load_lds_dwordx4 v[210:211], off
	s_waitcnt vmcnt(8)
	s_waitcnt lgkmcnt(0)
	s_nop 0
	s_setprio 1
	s_barrier
	v_mfma_f32_16x16x32_bf16 v[62:65], v[130:133], v[178:181], v[62:65]
	v_mfma_f32_16x16x32_bf16 v[58:61], v[148:151], v[178:181], v[58:61]
	v_mfma_f32_16x16x32_bf16 v[46:49], v[130:133], v[186:189], v[46:49]
	v_mfma_f32_16x16x32_bf16 v[42:45], v[148:151], v[186:189], v[42:45]
	v_mfma_f32_16x16x32_bf16 v[30:33], v[130:133], v[194:197], v[30:33]
	v_mfma_f32_16x16x32_bf16 v[26:29], v[148:151], v[194:197], v[26:29]
	v_mfma_f32_16x16x32_bf16 v[12:15], v[130:133], v[202:205], v[12:15]
	v_mfma_f32_16x16x32_bf16 v[8:11], v[148:151], v[202:205], v[8:11]
	v_mfma_f32_16x16x32_bf16 v[62:65], v[134:137], v[182:185], v[62:65]
	v_mfma_f32_16x16x32_bf16 v[58:61], v[152:155], v[182:185], v[58:61]
	v_mfma_f32_16x16x32_bf16 v[46:49], v[134:137], v[190:193], v[46:49]
	v_mfma_f32_16x16x32_bf16 v[42:45], v[152:155], v[190:193], v[42:45]
	v_mfma_f32_16x16x32_bf16 v[30:33], v[134:137], v[198:201], v[30:33]
	v_mfma_f32_16x16x32_bf16 v[26:29], v[152:155], v[198:201], v[26:29]
	v_mfma_f32_16x16x32_bf16 v[12:15], v[134:137], v[206:209], v[12:15]
	v_mfma_f32_16x16x32_bf16 v[8:11], v[152:155], v[206:209], v[8:11]
	v_mfma_f32_16x16x32_bf16 v[54:57], v[162:165], v[178:181], v[54:57]
	v_mfma_f32_16x16x32_bf16 v[50:53], v[170:173], v[178:181], v[50:53]
	v_mfma_f32_16x16x32_bf16 v[38:41], v[162:165], v[186:189], v[38:41]
	v_mfma_f32_16x16x32_bf16 v[34:37], v[170:173], v[186:189], v[34:37]
	v_mfma_f32_16x16x32_bf16 v[22:25], v[162:165], v[194:197], v[22:25]
	v_mfma_f32_16x16x32_bf16 v[18:21], v[170:173], v[194:197], v[18:21]
	v_mfma_f32_16x16x32_bf16 v[4:7], v[162:165], v[202:205], v[4:7]
	v_mfma_f32_16x16x32_bf16 v[0:3], v[170:173], v[202:205], v[0:3]
	v_mfma_f32_16x16x32_bf16 v[54:57], v[166:169], v[182:185], v[54:57]
	v_mfma_f32_16x16x32_bf16 v[50:53], v[174:177], v[182:185], v[50:53]
	v_mfma_f32_16x16x32_bf16 v[38:41], v[166:169], v[190:193], v[38:41]
	v_mfma_f32_16x16x32_bf16 v[34:37], v[174:177], v[190:193], v[34:37]
	v_mfma_f32_16x16x32_bf16 v[22:25], v[166:169], v[198:201], v[22:25]
	v_mfma_f32_16x16x32_bf16 v[18:21], v[174:177], v[198:201], v[18:21]
	v_mfma_f32_16x16x32_bf16 v[4:7], v[166:169], v[206:209], v[4:7]
	v_mfma_f32_16x16x32_bf16 v[0:3], v[174:177], v[206:209], v[0:3]
	s_barrier
	s_setprio 0
	s_add_i32 s90, s90, 2
	s_add_u32 s38, s38, 0x100
	s_addc_u32 s39, s39, 0
	s_add_u32 s0, s0, 0x100
	s_addc_u32 s1, s1, 0
.LBB0_558:
	s_add_u32 s6, s38, 0xfff00080
	s_addc_u32 s7, s39, -1
	s_add_i32 s91, 0, 0x10000
	s_cmp_eq_u32 s90, 60
	s_cselect_b32 s41, s21, s7
	s_cselect_b32 s40, s82, s6
	s_cselect_b32 s17, s23, s1
	s_cselect_b32 s16, s83, s0
	s_add_i32 s94, 0, 0x14000
	v_add_u32_e32 v152, s91, v157
	v_add_u32_e32 v174, s94, v157
	ds_read_b128 v[130:133], v152
	ds_read_b128 v[134:137], v152 offset:1024
	ds_read_b128 v[148:151], v152 offset:2048
	ds_read_b128 v[152:155], v152 offset:3072
	ds_read_b128 v[162:165], v174
	ds_read_b128 v[166:169], v174 offset:1024
	ds_read_b128 v[170:173], v174 offset:2048
	ds_read_b128 v[174:177], v174 offset:3072
	v_lshl_add_u64 v[210:211], s[38:39], 0, v[144:145]
	s_add_i32 m0, s13, 0xc000
	ds_read_b128 v[178:181], v161
	ds_read_b128 v[182:185], v161 offset:1024
	ds_read_b128 v[186:189], v161 offset:2048
	ds_read_b128 v[190:193], v161 offset:3072
	ds_read_b128 v[194:197], v161 offset:4096
	ds_read_b128 v[198:201], v161 offset:5120
	ds_read_b128 v[202:205], v161 offset:6144
	ds_read_b128 v[206:209], v161 offset:7168
	global_load_lds_dwordx4 v[210:211], off
	v_lshl_add_u64 v[210:211], s[38:39], 0, v[146:147]
	s_add_i32 m0, s13, 0xe000
	s_nop 0
	global_load_lds_dwordx4 v[210:211], off
	s_waitcnt vmcnt(8)
	s_waitcnt lgkmcnt(0)
	s_setprio 1
	s_barrier
; #define PG8_STAGEA(bufoff, gbase, voff) PG8_STAGE_X(bufoff, gbase, voff, AUXA)
; #define PG8_STAGEB(bufoff, gbase, voff) PG8_STAGE_X(bufoff, gbase, voff, AUXB)
; #define PG8_LDA(dst, b, h) do { _Pragma("unroll") for (int m = 0; m < 4; ++m) _Pragma("unroll") for (int k = 0; k < 2; ++k) dst[m][k] = *(const PG8_LAS bf16x8*)(lds + PG8_SA(b, h) + aoff + m * 2048 + k * 1024); } while (0)
; #define PG8_LDB(dst, b, h) do { _Pragma("unroll") for (int n = 0; n < 2; ++n) _Pragma("unroll") for (int k = 0; k < 2; ++k) dst[n][k] = *(const PG8_LAS bf16x8*)(lds + PG8_SB(b, h) + boff + n * 2048 + k * 1024); } while (0)
; #define PG8_MMA(ai, bj, At, Bt) do { if (GEMM_PRIO_MODE == 0) __builtin_amdgcn_s_setprio(1); PG8_MMA_LOOPS \
;         acc[ai][bj][m][n] = __builtin_amdgcn_mfma_f32_16x16x32_bf16(Bt[n][k], At[m][k], acc[ai][bj][m][n], 0, 0, 0); if (GEMM_PRIO_MODE == 0) __builtin_amdgcn_s_setprio(0); } while (0)
; #define PG8_WAIT_V(n) asm volatile("s_waitcnt vmcnt(" #n ")" ::: "memory")
; #define PG8_WAIT_VR(n, nr, flag) asm volatile("s_cmp_eq_u32 %0, 0\n\ts_cbranch_scc1 .Lpg8s%=\n\ts_waitcnt vmcnt(" #nr ")\n\ts_branch .Lpg8d%=\n.Lpg8s%=:\n\ts_waitcnt vmcnt(" #n ")\n.Lpg8d%=:" :: "s"(flag) : "memory", "scc")
; #define PG8_WAIT_L(n) asm volatile("s_waitcnt lgkmcnt(" #n ")" ::: "memory")
; #define PG8_BAR __builtin_amdgcn_s_barrier()
; #define PG8_SCHED __builtin_amdgcn_sched_barrier(0)
;     ...
;             PG8_LDB(B0, 0, 0); PG8_LDB(B1, 0, 1); PG8_SCHED; PG8_LDA(At, 0, 0); PG8_STAGEA(PG8_SA(1, 1), a1 + hstepA, voffA);
;     ...
;             const int relax = __builtin_amdgcn_readfirstlane((t == 0 && ui > 0) ? 1 : 0);
;             PG8_WAIT_VR(8, 24, relax); PG8_WAIT_L(0); PG8_BAR; PG8_MMA(0, 0, At, B0); PG8_MMA(0, 1, At, B1); PG8_BAR; PG8_SCHED;
;     ...
;             PG8_WAIT_V(8); PG8_WAIT_L(0); PG8_BAR; PG8_MMA(0, 0, At, B0); PG8_MMA(0, 1, At, B1); PG8_BAR; PG8_SCHED;
;     ...
;             PG8_LDA(At, 0, 1); PG8_STAGEB(PG8_SB(0, 0), b2, voffB); PG8_STAGEB(PG8_SB(0, 1), b2 + hstepB, voffB); PG8_STAGEA(PG8_SA(0, 0), a2, voffA);
	v_mfma_f32_16x16x32_bf16 v[126:129], v[130:133], v[178:181], v[126:129]
	v_mfma_f32_16x16x32_bf16 v[122:125], v[148:151], v[178:181], v[122:125]
	v_mfma_f32_16x16x32_bf16 v[110:113], v[130:133], v[186:189], v[110:113]
	v_mfma_f32_16x16x32_bf16 v[106:109], v[148:151], v[186:189], v[106:109]
	v_mfma_f32_16x16x32_bf16 v[94:97], v[130:133], v[194:197], v[94:97]
	v_mfma_f32_16x16x32_bf16 v[90:93], v[148:151], v[194:197], v[90:93]
	v_mfma_f32_16x16x32_bf16 v[78:81], v[130:133], v[202:205], v[78:81]
	v_mfma_f32_16x16x32_bf16 v[74:77], v[148:151], v[202:205], v[74:77]
	v_mfma_f32_16x16x32_bf16 v[126:129], v[134:137], v[182:185], v[126:129]
	v_mfma_f32_16x16x32_bf16 v[122:125], v[152:155], v[182:185], v[122:125]
	v_mfma_f32_16x16x32_bf16 v[110:113], v[134:137], v[190:193], v[110:113]
	v_mfma_f32_16x16x32_bf16 v[106:109], v[152:155], v[190:193], v[106:109]
	v_mfma_f32_16x16x32_bf16 v[94:97], v[134:137], v[198:201], v[94:97]
	v_mfma_f32_16x16x32_bf16 v[90:93], v[152:155], v[198:201], v[90:93]
	v_mfma_f32_16x16x32_bf16 v[78:81], v[134:137], v[206:209], v[78:81]
	v_mfma_f32_16x16x32_bf16 v[74:77], v[152:155], v[206:209], v[74:77]
	v_mfma_f32_16x16x32_bf16 v[118:121], v[162:165], v[178:181], v[118:121]
	v_mfma_f32_16x16x32_bf16 v[114:117], v[170:173], v[178:181], v[114:117]
	v_mfma_f32_16x16x32_bf16 v[102:105], v[162:165], v[186:189], v[102:105]
	v_mfma_f32_16x16x32_bf16 v[98:101], v[170:173], v[186:189], v[98:101]
	v_mfma_f32_16x16x32_bf16 v[86:89], v[162:165], v[194:197], v[86:89]
	v_mfma_f32_16x16x32_bf16 v[82:85], v[170:173], v[194:197], v[82:85]
	v_mfma_f32_16x16x32_bf16 v[70:73], v[162:165], v[202:205], v[70:73]
	v_mfma_f32_16x16x32_bf16 v[66:69], v[170:173], v[202:205], v[66:69]
	v_mfma_f32_16x16x32_bf16 v[118:121], v[166:169], v[182:185], v[118:121]
	v_mfma_f32_16x16x32_bf16 v[114:117], v[174:177], v[182:185], v[114:117]
	v_mfma_f32_16x16x32_bf16 v[102:105], v[166:169], v[190:193], v[102:105]
	v_mfma_f32_16x16x32_bf16 v[98:101], v[174:177], v[190:193], v[98:101]
	v_mfma_f32_16x16x32_bf16 v[86:89], v[166:169], v[198:201], v[86:89]
	v_mfma_f32_16x16x32_bf16 v[82:85], v[174:177], v[198:201], v[82:85]
	v_mfma_f32_16x16x32_bf16 v[70:73], v[166:169], v[206:209], v[70:73]
	v_mfma_f32_16x16x32_bf16 v[66:69], v[174:177], v[206:209], v[66:69]
	s_barrier
	s_setprio 0
	s_add_i32 s6, s91, s12
	v_lshl_add_u64 v[210:211], s[16:17], 0, v[16:17]
	s_mov_b32 m0, s6
	ds_read_b128 v[178:181], v161 offset:16384
	ds_read_b128 v[182:185], v161 offset:17408
	ds_read_b128 v[186:189], v161 offset:18432
	ds_read_b128 v[190:193], v161 offset:19456
	ds_read_b128 v[194:197], v161 offset:20480
	ds_read_b128 v[198:201], v161 offset:21504
	ds_read_b128 v[202:205], v161 offset:22528
	ds_read_b128 v[206:209], v161 offset:23552
	global_load_lds_dwordx4 v[210:211], off
	s_add_i32 m0, s6, 0x2000
	s_add_u32 s6, s16, 0x100000
	v_lshl_add_u64 v[212:213], s[16:17], 0, v[138:139]
	s_addc_u32 s7, s17, 0
	s_add_i32 s91, s94, s12
	global_load_lds_dwordx4 v[212:213], off
	v_lshl_add_u64 v[214:215], s[6:7], 0, v[16:17]
	s_mov_b32 m0, s91
	v_lshl_add_u64 v[216:217], s[40:41], 0, v[140:141]
	global_load_lds_dwordx4 v[214:215], off
	v_lshl_add_u64 v[214:215], s[6:7], 0, v[138:139]
	s_add_i32 m0, s91, 0x2000
	s_nop 0
	global_load_lds_dwordx4 v[214:215], off
	v_lshl_add_u64 v[214:215], s[40:41], 0, v[142:143]
	s_mov_b32 m0, s13
	s_nop 0
	global_load_lds_dwordx4 v[214:215], off
	s_mov_b32 m0, s42
	s_nop 0
	global_load_lds_dwordx4 v[216:217], off
	s_waitcnt vmcnt(8)
	s_waitcnt lgkmcnt(0)
	s_setprio 1
	s_barrier
	v_mfma_f32_16x16x32_bf16 v[62:65], v[130:133], v[178:181], v[62:65]
	v_mfma_f32_16x16x32_bf16 v[58:61], v[148:151], v[178:181], v[58:61]
	v_mfma_f32_16x16x32_bf16 v[46:49], v[130:133], v[186:189], v[46:49]
	v_mfma_f32_16x16x32_bf16 v[42:45], v[148:151], v[186:189], v[42:45]
	v_mfma_f32_16x16x32_bf16 v[30:33], v[130:133], v[194:197], v[30:33]
	v_mfma_f32_16x16x32_bf16 v[26:29], v[148:151], v[194:197], v[26:29]
	v_mfma_f32_16x16x32_bf16 v[12:15], v[130:133], v[202:205], v[12:15]
	v_mfma_f32_16x16x32_bf16 v[8:11], v[148:151], v[202:205], v[8:11]
	v_mfma_f32_16x16x32_bf16 v[62:65], v[134:137], v[182:185], v[62:65]
	v_mfma_f32_16x16x32_bf16 v[58:61], v[152:155], v[182:185], v[58:61]
	v_mfma_f32_16x16x32_bf16 v[46:49], v[134:137], v[190:193], v[46:49]
	v_mfma_f32_16x16x32_bf16 v[42:45], v[152:155], v[190:193], v[42:45]
	v_mfma_f32_16x16x32_bf16 v[30:33], v[134:137], v[198:201], v[30:33]
	v_mfma_f32_16x16x32_bf16 v[26:29], v[152:155], v[198:201], v[26:29]
	v_mfma_f32_16x16x32_bf16 v[12:15], v[134:137], v[206:209], v[12:15]
	v_mfma_f32_16x16x32_bf16 v[8:11], v[152:155], v[206:209], v[8:11]
	v_mfma_f32_16x16x32_bf16 v[54:57], v[162:165], v[178:181], v[54:57]
	v_mfma_f32_16x16x32_bf16 v[50:53], v[170:173], v[178:181], v[50:53]
	v_mfma_f32_16x16x32_bf16 v[38:41], v[162:165], v[186:189], v[38:41]
	v_mfma_f32_16x16x32_bf16 v[34:37], v[170:173], v[186:189], v[34:37]
	v_mfma_f32_16x16x32_bf16 v[22:25], v[162:165], v[194:197], v[22:25]
	v_mfma_f32_16x16x32_bf16 v[18:21], v[170:173], v[194:197], v[18:21]
	v_mfma_f32_16x16x32_bf16 v[4:7], v[162:165], v[202:205], v[4:7]
	v_mfma_f32_16x16x32_bf16 v[0:3], v[170:173], v[202:205], v[0:3]
	v_mfma_f32_16x16x32_bf16 v[54:57], v[166:169], v[182:185], v[54:57]
	v_mfma_f32_16x16x32_bf16 v[50:53], v[174:177], v[182:185], v[50:53]
	v_mfma_f32_16x16x32_bf16 v[38:41], v[166:169], v[190:193], v[38:41]
	v_mfma_f32_16x16x32_bf16 v[34:37], v[174:177], v[190:193], v[34:37]
	v_mfma_f32_16x16x32_bf16 v[22:25], v[166:169], v[198:201], v[22:25]
	v_mfma_f32_16x16x32_bf16 v[18:21], v[174:177], v[198:201], v[18:21]
	v_mfma_f32_16x16x32_bf16 v[4:7], v[166:169], v[206:209], v[4:7]
	v_mfma_f32_16x16x32_bf16 v[0:3], v[174:177], v[206:209], v[0:3]
	s_barrier
; #define PG8_STAGEA(bufoff, gbase, voff) PG8_STAGE_X(bufoff, gbase, voff, AUXA)
; #define PG8_LDA(dst, b, h) do { _Pragma("unroll") for (int m = 0; m < 4; ++m) _Pragma("unroll") for (int k = 0; k < 2; ++k) dst[m][k] = *(const PG8_LAS bf16x8*)(lds + PG8_SA(b, h) + aoff + m * 2048 + k * 1024); } while (0)
; #define PG8_LDB(dst, b, h) do { _Pragma("unroll") for (int n = 0; n < 2; ++n) _Pragma("unroll") for (int k = 0; k < 2; ++k) dst[n][k] = *(const PG8_LAS bf16x8*)(lds + PG8_SB(b, h) + boff + n * 2048 + k * 1024); } while (0)
; #define PG8_MMA(ai, bj, At, Bt) do { if (GEMM_PRIO_MODE == 0) __builtin_amdgcn_s_setprio(1); PG8_MMA_LOOPS \
;         acc[ai][bj][m][n] = __builtin_amdgcn_mfma_f32_16x16x32_bf16(Bt[n][k], At[m][k], acc[ai][bj][m][n], 0, 0, 0); if (GEMM_PRIO_MODE == 0) __builtin_amdgcn_s_setprio(0); } while (0)
; #define PG8_WAIT_V(n) asm volatile("s_waitcnt vmcnt(" #n ")" ::: "memory")
; #define PG8_WAIT_L(n) asm volatile("s_waitcnt lgkmcnt(" #n ")" ::: "memory")
; #define PG8_BAR __builtin_amdgcn_s_barrier()
; #define PG8_SCHED __builtin_amdgcn_sched_barrier(0)
;     ...
;             PG8_LDB(B0, 1, 0); PG8_LDB(B1, 1, 1); PG8_SCHED; PG8_LDA(At, 1, 0); PG8_STAGEA(PG8_SA(0, 1), a2 + hstepA, voffA);
;             PG8_WAIT_V(8); PG8_WAIT_L(0); PG8_BAR; PG8_MMA(0, 0, At, B0); PG8_MMA(0, 1, At, B1); PG8_BAR; PG8_SCHED;
	s_setprio 0
	s_add_i32 s91, 0, 0x18000
	s_add_i32 s94, 0, 0x1c000
	v_add_u32_e32 v152, s91, v157
	v_add_u32_e32 v174, s94, v157
	ds_read_b128 v[130:133], v152
	ds_read_b128 v[134:137], v152 offset:1024
	ds_read_b128 v[148:151], v152 offset:2048
	ds_read_b128 v[152:155], v152 offset:3072
	ds_read_b128 v[162:165], v174
	ds_read_b128 v[166:169], v174 offset:1024
	ds_read_b128 v[170:173], v174 offset:2048
	ds_read_b128 v[174:177], v174 offset:3072
	s_add_u32 s6, s40, 0x100000
	s_addc_u32 s7, s41, 0
	s_mov_b32 m0, s43
	v_lshl_add_u64 v[218:219], s[6:7], 0, v[142:143]
	ds_read_b128 v[178:181], v161 offset:32768
	ds_read_b128 v[182:185], v161 offset:33792
	ds_read_b128 v[186:189], v161 offset:34816
	ds_read_b128 v[190:193], v161 offset:35840
	ds_read_b128 v[194:197], v161 offset:36864
	ds_read_b128 v[198:201], v161 offset:37888
	ds_read_b128 v[202:205], v161 offset:38912
	ds_read_b128 v[206:209], v161 offset:39936
	global_load_lds_dwordx4 v[218:219], off
	v_lshl_add_u64 v[218:219], s[6:7], 0, v[140:141]
	s_mov_b32 m0, s50
	s_nop 0
	global_load_lds_dwordx4 v[218:219], off
	s_waitcnt vmcnt(8)
	s_waitcnt lgkmcnt(0)
	s_setprio 1
	s_barrier
	v_mfma_f32_16x16x32_bf16 v[126:129], v[130:133], v[178:181], v[126:129]
	v_mfma_f32_16x16x32_bf16 v[122:125], v[148:151], v[178:181], v[122:125]
	v_mfma_f32_16x16x32_bf16 v[110:113], v[130:133], v[186:189], v[110:113]
	v_mfma_f32_16x16x32_bf16 v[106:109], v[148:151], v[186:189], v[106:109]
	v_mfma_f32_16x16x32_bf16 v[94:97], v[130:133], v[194:197], v[94:97]
	v_mfma_f32_16x16x32_bf16 v[90:93], v[148:151], v[194:197], v[90:93]
	v_mfma_f32_16x16x32_bf16 v[78:81], v[130:133], v[202:205], v[78:81]
	v_mfma_f32_16x16x32_bf16 v[74:77], v[148:151], v[202:205], v[74:77]
	v_mfma_f32_16x16x32_bf16 v[126:129], v[134:137], v[182:185], v[126:129]
	v_mfma_f32_16x16x32_bf16 v[122:125], v[152:155], v[182:185], v[122:125]
	v_mfma_f32_16x16x32_bf16 v[110:113], v[134:137], v[190:193], v[110:113]
	v_mfma_f32_16x16x32_bf16 v[106:109], v[152:155], v[190:193], v[106:109]
	v_mfma_f32_16x16x32_bf16 v[94:97], v[134:137], v[198:201], v[94:97]
	v_mfma_f32_16x16x32_bf16 v[90:93], v[152:155], v[198:201], v[90:93]
	v_mfma_f32_16x16x32_bf16 v[78:81], v[134:137], v[206:209], v[78:81]
	v_mfma_f32_16x16x32_bf16 v[74:77], v[152:155], v[206:209], v[74:77]
	v_mfma_f32_16x16x32_bf16 v[118:121], v[162:165], v[178:181], v[118:121]
	v_mfma_f32_16x16x32_bf16 v[114:117], v[170:173], v[178:181], v[114:117]
	v_mfma_f32_16x16x32_bf16 v[102:105], v[162:165], v[186:189], v[102:105]
	v_mfma_f32_16x16x32_bf16 v[98:101], v[170:173], v[186:189], v[98:101]
	v_mfma_f32_16x16x32_bf16 v[86:89], v[162:165], v[194:197], v[86:89]
	v_mfma_f32_16x16x32_bf16 v[82:85], v[170:173], v[194:197], v[82:85]
	v_mfma_f32_16x16x32_bf16 v[70:73], v[162:165], v[202:205], v[70:73]
	v_mfma_f32_16x16x32_bf16 v[66:69], v[170:173], v[202:205], v[66:69]
	v_mfma_f32_16x16x32_bf16 v[118:121], v[166:169], v[182:185], v[118:121]
	v_mfma_f32_16x16x32_bf16 v[114:117], v[174:177], v[182:185], v[114:117]
	v_mfma_f32_16x16x32_bf16 v[102:105], v[166:169], v[190:193], v[102:105]
	v_mfma_f32_16x16x32_bf16 v[98:101], v[174:177], v[190:193], v[98:101]
	v_mfma_f32_16x16x32_bf16 v[86:89], v[166:169], v[198:201], v[86:89]
	v_mfma_f32_16x16x32_bf16 v[82:85], v[174:177], v[198:201], v[82:85]
	v_mfma_f32_16x16x32_bf16 v[70:73], v[166:169], v[206:209], v[70:73]
	v_mfma_f32_16x16x32_bf16 v[66:69], v[174:177], v[206:209], v[66:69]
	s_barrier
; #define PG8_STAGEA(bufoff, gbase, voff) PG8_STAGE_X(bufoff, gbase, voff, AUXA)
; #define PG8_STAGEB(bufoff, gbase, voff) PG8_STAGE_X(bufoff, gbase, voff, AUXB)
; #define PG8_LDA(dst, b, h) do { _Pragma("unroll") for (int m = 0; m < 4; ++m) _Pragma("unroll") for (int k = 0; k < 2; ++k) dst[m][k] = *(const PG8_LAS bf16x8*)(lds + PG8_SA(b, h) + aoff + m * 2048 + k * 1024); } while (0)
; #define PG8_MMA(ai, bj, At, Bt) do { if (GEMM_PRIO_MODE == 0) __builtin_amdgcn_s_setprio(1); PG8_MMA_LOOPS \
;         acc[ai][bj][m][n] = __builtin_amdgcn_mfma_f32_16x16x32_bf16(Bt[n][k], At[m][k], acc[ai][bj][m][n], 0, 0, 0); if (GEMM_PRIO_MODE == 0) __builtin_amdgcn_s_setprio(0); } while (0)
; #define PG8_WAIT_V(n) asm volatile("s_waitcnt vmcnt(" #n ")" ::: "memory")
; #define PG8_WAIT_L(n) asm volatile("s_waitcnt lgkmcnt(" #n ")" ::: "memory")
; #define PG8_BAR __builtin_amdgcn_s_barrier()
; #define PG8_SCHED __builtin_amdgcn_sched_barrier(0)
;     ...
;             PG8_LDA(At, 1, 1); PG8_STAGEB(PG8_SB(1, 0), b3, voffB); PG8_STAGEB(PG8_SB(1, 1), b3 + hstepB, voffB); PG8_STAGEA(PG8_SA(1, 0), a3, voffA);
;             PG8_WAIT_V(8); PG8_WAIT_L(0); PG8_BAR; PG8_MMA(1, 0, At, B0); PG8_MMA(1, 1, At, B1); PG8_BAR; PG8_SCHED;
;     ...
;         }
;         if constexpr (ALIGN_EPI) { if (wr == 0) PG8_BAR; }
	s_setprio 0
	s_add_i32 s6, s91, s12
	v_lshl_add_u64 v[210:211], v[210:211], 0, s[86:87]
	s_mov_b32 m0, s6
	ds_read_b128 v[178:181], v161 offset:49152
	ds_read_b128 v[182:185], v161 offset:50176
	ds_read_b128 v[186:189], v161 offset:51200
	ds_read_b128 v[190:193], v161 offset:52224
	ds_read_b128 v[194:197], v161 offset:53248
	ds_read_b128 v[198:201], v161 offset:54272
	ds_read_b128 v[202:205], v161 offset:55296
	ds_read_b128 v[206:209], v161 offset:56320
	global_load_lds_dwordx4 v[210:211], off
	s_add_i32 m0, s6, 0x2000
	s_add_u32 s6, s16, 0x100080
	v_lshl_add_u64 v[210:211], v[212:213], 0, s[86:87]
	s_addc_u32 s7, s17, 0
	s_add_i32 s16, s94, s12
	global_load_lds_dwordx4 v[210:211], off
	v_lshl_add_u64 v[210:211], s[6:7], 0, v[16:17]
	s_mov_b32 m0, s16
	s_nop 0
	global_load_lds_dwordx4 v[210:211], off
	v_lshl_add_u64 v[210:211], s[6:7], 0, v[138:139]
	s_add_i32 m0, s16, 0x2000
	s_nop 0
	global_load_lds_dwordx4 v[210:211], off
	v_lshl_add_u64 v[210:211], v[214:215], 0, s[86:87]
	s_mov_b32 m0, s68
	s_nop 0
	global_load_lds_dwordx4 v[210:211], off
	v_lshl_add_u64 v[210:211], v[216:217], 0, s[86:87]
	s_mov_b32 m0, s69
	s_nop 0
	global_load_lds_dwordx4 v[210:211], off
	s_waitcnt vmcnt(8)
	s_waitcnt lgkmcnt(0)
	s_nop 0
	s_setprio 1
	s_barrier
	v_mfma_f32_16x16x32_bf16 v[62:65], v[130:133], v[178:181], v[62:65]
	v_mfma_f32_16x16x32_bf16 v[58:61], v[148:151], v[178:181], v[58:61]
	v_mfma_f32_16x16x32_bf16 v[46:49], v[130:133], v[186:189], v[46:49]
	v_mfma_f32_16x16x32_bf16 v[42:45], v[148:151], v[186:189], v[42:45]
	v_mfma_f32_16x16x32_bf16 v[30:33], v[130:133], v[194:197], v[30:33]
	v_mfma_f32_16x16x32_bf16 v[26:29], v[148:151], v[194:197], v[26:29]
	v_mfma_f32_16x16x32_bf16 v[12:15], v[130:133], v[202:205], v[12:15]
	v_mfma_f32_16x16x32_bf16 v[8:11], v[148:151], v[202:205], v[8:11]
	v_mfma_f32_16x16x32_bf16 v[62:65], v[134:137], v[182:185], v[62:65]
	v_mfma_f32_16x16x32_bf16 v[58:61], v[152:155], v[182:185], v[58:61]
	v_mfma_f32_16x16x32_bf16 v[46:49], v[134:137], v[190:193], v[46:49]
	v_mfma_f32_16x16x32_bf16 v[42:45], v[152:155], v[190:193], v[42:45]
	v_mfma_f32_16x16x32_bf16 v[30:33], v[134:137], v[198:201], v[30:33]
	v_mfma_f32_16x16x32_bf16 v[26:29], v[152:155], v[198:201], v[26:29]
	v_mfma_f32_16x16x32_bf16 v[12:15], v[134:137], v[206:209], v[12:15]
	v_mfma_f32_16x16x32_bf16 v[8:11], v[152:155], v[206:209], v[8:11]
	v_mfma_f32_16x16x32_bf16 v[54:57], v[162:165], v[178:181], v[54:57]
	v_mfma_f32_16x16x32_bf16 v[50:53], v[170:173], v[178:181], v[50:53]
	v_mfma_f32_16x16x32_bf16 v[38:41], v[162:165], v[186:189], v[38:41]
	v_mfma_f32_16x16x32_bf16 v[34:37], v[170:173], v[186:189], v[34:37]
	v_mfma_f32_16x16x32_bf16 v[22:25], v[162:165], v[194:197], v[22:25]
	v_mfma_f32_16x16x32_bf16 v[18:21], v[170:173], v[194:197], v[18:21]
	v_mfma_f32_16x16x32_bf16 v[4:7], v[162:165], v[202:205], v[4:7]
	v_mfma_f32_16x16x32_bf16 v[0:3], v[170:173], v[202:205], v[0:3]
	v_mfma_f32_16x16x32_bf16 v[54:57], v[166:169], v[182:185], v[54:57]
	v_mfma_f32_16x16x32_bf16 v[50:53], v[174:177], v[182:185], v[50:53]
	v_mfma_f32_16x16x32_bf16 v[38:41], v[166:169], v[190:193], v[38:41]
	v_mfma_f32_16x16x32_bf16 v[34:37], v[174:177], v[190:193], v[34:37]
	v_mfma_f32_16x16x32_bf16 v[22:25], v[166:169], v[198:201], v[22:25]
	v_mfma_f32_16x16x32_bf16 v[18:21], v[174:177], v[198:201], v[18:21]
	v_mfma_f32_16x16x32_bf16 v[4:7], v[166:169], v[206:209], v[4:7]
	v_mfma_f32_16x16x32_bf16 v[0:3], v[174:177], v[206:209], v[0:3]
	s_barrier
	s_setprio 0
	s_add_i32 s90, s90, 2
	s_add_u32 s38, s38, 0x100
	s_addc_u32 s39, s39, 0
	s_add_u32 s0, s0, 0x100
	s_addc_u32 s1, s1, 0
	s_cmp_gt_u32 s90, 61
	s_cbranch_scc0 .LBB0_558
	s_and_b64 vcc, exec, s[18:19]
	s_cbranch_vccz .LBB0_561
	s_barrier

; #define PG8_STAGEA(bufoff, gbase, voff) PG8_STAGE_X(bufoff, gbase, voff, AUXA)
; #define PG8_STR(x) PG8_STR2(x)
;     ...
;         const bool has_next = S.next(ui + 1, nxt);
;         const char* nA = has_next ? (const char*)g.A + (size_t)nxt.pm * tstepA : cA; const char* nB = has_next ? (const char*)g.Bt + (size_t)nxt.pn * tstepB : cB;
;         int t0 = 0;
;         if constexpr (SP2 && GEMM_RELAX == 1) { if (ui > 0) {
;             const char* a1 = cA + kstepA; const char* a2 = cA + 2 * kstepA; const char* b2 = cB + 2 * kstepB; const char* a3 = a2 + kstepA; const char* b3 = b2 + kstepB;
;             PG8_LDB(B0, 0, 0); PG8_LDB(B1, 0, 1); PG8_SCHED; PG8_LDA(At, 0, 0); PG8_STAGEA(PG8_SA(1, 1), a1 + hstepA, voffA);
;             PG8_WAIT_V(24); PG8_WAIT_L(0); PG8_BAR; PG8_MMA(0, 0, At, B0); PG8_MMA(0, 1, At, B1); PG8_BAR; PG8_SCHED;
;             PG8_LDA(At, 0, 1); PG8_STAGEB(PG8_SB(0, 0), b2, voffB); PG8_STAGEB(PG8_SB(0, 1), b2 + hstepB, voffB); PG8_STAGEA(PG8_SA(0, 0), a2, voffA);
;             PG8_WAIT_V(24); PG8_WAIT_L(0); PG8_BAR; PG8_MMA(1, 0, At, B0); PG8_MMA(1, 1, At, B1); PG8_BAR; PG8_SCHED;
;             PG8_LDB(B0, 1, 0); PG8_LDB(B1, 1, 1); PG8_SCHED; PG8_LDA(At, 1, 0); PG8_STAGEA(PG8_SA(0, 1), a2 + hstepA, voffA);
;             PG8_WAIT_V(8); PG8_WAIT_L(0); PG8_BAR; PG8_MMA(0, 0, At, B0); PG8_MMA(0, 1, At, B1); PG8_BAR; PG8_SCHED;
;             PG8_LDA(At, 1, 1); PG8_STAGEB(PG8_SB(1, 0), b3, voffB); PG8_STAGEB(PG8_SB(1, 1), b3 + hstepB, voffB); PG8_STAGEA(PG8_SA(1, 0), a3, voffA);
;             PG8_WAIT_V(8); PG8_WAIT_L(0); PG8_BAR; PG8_MMA(1, 0, At, B0); PG8_MMA(1, 1, At, B1); PG8_BAR; PG8_SCHED;
;             t0 = 2; } }
;     ...
;         asm volatile(".p2align " PG8_STR(GEMM_LOOP_ALIGN) ::: "memory");
;     ...
;         for (int t = t0; t < nt; t += 2) {
;             const bool last = (t == nt - 2);
;             const char* a1 = cA + (size_t)(t + 1) * kstepA;
;             const char* a2 = last ? nA : cA + (size_t)(t + 2) * kstepA; const char* b2 = last ? nB : cB + (size_t)(t + 2) * kstepB;
;             const char* a3 = a2 + kstepA; const char* b3 = b2 + kstepB;
;             if (last && has_next) S.a_ready(nxt);
;             if constexpr (SP2) {
;             PG8_LDB(B0, 0, 0); PG8_LDB(B1, 0, 1); PG8_SCHED; PG8_LDA(At, 0, 0); PG8_STAGEA(PG8_SA(1, 1), a1 + hstepA, voffA);
;     ...
;             const int relax = __builtin_amdgcn_readfirstlane((t == 0 && ui > 0) ? 1 : 0);
.LBB0_711:
	s_ashr_i32 s25, s24, 31
	s_lshl_b64 s[0:1], s[24:25], 21
	s_add_u32 s26, s56, s0
	s_addc_u32 s27, s57, s1
	s_and_b64 s[0:1], s[10:11], exec
	s_cselect_b32 s0, s27, s13
	s_cselect_b32 s1, s26, s12
	s_ashr_i32 s23, s22, 31
	s_lshl_b64 s[6:7], s[22:23], 21
	s_add_u32 s36, s51, s6
	s_addc_u32 s37, s68, s7
	s_and_b64 s[6:7], s[10:11], exec
	s_cselect_b32 s23, s37, s43
	s_cselect_b32 s25, s36, s42
	s_add_u32 s40, s12, 0x100080
	s_addc_u32 s41, s13, 0
	s_add_u32 s12, s42, 0x100
	s_addc_u32 s13, s43, 0
	s_mov_b32 s39, -2
	s_add_u32 s6, s40, 0xfff00080
	s_addc_u32 s7, s41, -1
	s_add_i32 s95, 0, 0x10000
	s_cmp_eq_u32 s39, 60
	s_cselect_b32 s43, s0, s7
	s_cselect_b32 s42, s1, s6
	v_add_u32_e32 v144, s95, v146
	s_cselect_b32 s17, s23, s13
	s_cselect_b32 s16, s25, s12
	s_add_i32 vcc_lo, 0, 0x14000
	ds_read_b128 v[150:153], v144
	ds_read_b128 v[154:157], v144 offset:1024
	ds_read_b128 v[158:161], v144 offset:2048
	ds_read_b128 v[162:165], v144 offset:3072
	v_add_u32_e32 v144, vcc_lo, v146
	ds_read_b128 v[166:169], v144
	ds_read_b128 v[170:173], v144 offset:1024
	ds_read_b128 v[174:177], v144 offset:2048
	ds_read_b128 v[178:181], v144 offset:3072
	v_lshl_add_u64 v[144:145], s[40:41], 0, v[140:141]
	s_add_i32 m0, s69, 0xc000
	ds_read_b128 v[182:185], v148
	ds_read_b128 v[186:189], v148 offset:1024
	ds_read_b128 v[190:193], v148 offset:2048
	ds_read_b128 v[194:197], v148 offset:3072
	ds_read_b128 v[198:201], v148 offset:4096
	ds_read_b128 v[202:205], v148 offset:5120
	ds_read_b128 v[206:209], v148 offset:6144
	ds_read_b128 v[210:213], v148 offset:7168
	global_load_lds_dwordx4 v[144:145], off
	v_lshl_add_u64 v[144:145], s[40:41], 0, v[142:143]
	s_add_i32 m0, s69, 0xe000
	s_nop 0
	global_load_lds_dwordx4 v[144:145], off
	s_waitcnt vmcnt(8)
	s_waitcnt lgkmcnt(0)
	s_nop 0
	s_setprio 1
	s_barrier
	v_mfma_f32_16x16x32_bf16 v[126:129], v[150:153], v[182:185], 0
	v_mfma_f32_16x16x32_bf16 v[122:125], v[158:161], v[182:185], 0
	v_mfma_f32_16x16x32_bf16 v[110:113], v[150:153], v[190:193], 0
	v_mfma_f32_16x16x32_bf16 v[106:109], v[158:161], v[190:193], 0
	v_mfma_f32_16x16x32_bf16 v[94:97], v[150:153], v[198:201], 0
	v_mfma_f32_16x16x32_bf16 v[90:93], v[158:161], v[198:201], 0
	v_mfma_f32_16x16x32_bf16 v[78:81], v[150:153], v[206:209], 0
	v_mfma_f32_16x16x32_bf16 v[74:77], v[158:161], v[206:209], 0
	v_mfma_f32_16x16x32_bf16 v[126:129], v[154:157], v[186:189], v[126:129]
	v_mfma_f32_16x16x32_bf16 v[122:125], v[162:165], v[186:189], v[122:125]
	v_mfma_f32_16x16x32_bf16 v[110:113], v[154:157], v[194:197], v[110:113]
	v_mfma_f32_16x16x32_bf16 v[106:109], v[162:165], v[194:197], v[106:109]
	v_mfma_f32_16x16x32_bf16 v[94:97], v[154:157], v[202:205], v[94:97]
	v_mfma_f32_16x16x32_bf16 v[90:93], v[162:165], v[202:205], v[90:93]
	v_mfma_f32_16x16x32_bf16 v[78:81], v[154:157], v[210:213], v[78:81]
	v_mfma_f32_16x16x32_bf16 v[74:77], v[162:165], v[210:213], v[74:77]
	v_mfma_f32_16x16x32_bf16 v[118:121], v[166:169], v[182:185], 0
	v_mfma_f32_16x16x32_bf16 v[114:117], v[174:177], v[182:185], 0
	v_mfma_f32_16x16x32_bf16 v[102:105], v[166:169], v[190:193], 0
	v_mfma_f32_16x16x32_bf16 v[98:101], v[174:177], v[190:193], 0
	v_mfma_f32_16x16x32_bf16 v[86:89], v[166:169], v[198:201], 0
	v_mfma_f32_16x16x32_bf16 v[82:85], v[174:177], v[198:201], 0
	v_mfma_f32_16x16x32_bf16 v[70:73], v[166:169], v[206:209], 0
	v_mfma_f32_16x16x32_bf16 v[66:69], v[174:177], v[206:209], 0
	v_mfma_f32_16x16x32_bf16 v[118:121], v[170:173], v[186:189], v[118:121]
	v_mfma_f32_16x16x32_bf16 v[114:117], v[178:181], v[186:189], v[114:117]
	v_mfma_f32_16x16x32_bf16 v[102:105], v[170:173], v[194:197], v[102:105]
	v_mfma_f32_16x16x32_bf16 v[98:101], v[178:181], v[194:197], v[98:101]
	v_mfma_f32_16x16x32_bf16 v[86:89], v[170:173], v[202:205], v[86:89]
	v_mfma_f32_16x16x32_bf16 v[82:85], v[178:181], v[202:205], v[82:85]
	v_mfma_f32_16x16x32_bf16 v[70:73], v[170:173], v[210:213], v[70:73]
	v_mfma_f32_16x16x32_bf16 v[66:69], v[178:181], v[210:213], v[66:69]
	s_barrier
	s_setprio 0
	s_add_i32 s6, s95, s50
	v_lshl_add_u64 v[144:145], s[16:17], 0, v[134:135]
	s_mov_b32 m0, s6
	ds_read_b128 v[182:185], v148 offset:16384
	ds_read_b128 v[186:189], v148 offset:17408
	ds_read_b128 v[190:193], v148 offset:18432
	ds_read_b128 v[194:197], v148 offset:19456
	ds_read_b128 v[198:201], v148 offset:20480
	ds_read_b128 v[202:205], v148 offset:21504
	ds_read_b128 v[206:209], v148 offset:22528
	ds_read_b128 v[210:213], v148 offset:23552
	global_load_lds_dwordx4 v[144:145], off
	s_add_i32 m0, s6, 0x2000
	s_add_u32 s6, s16, 0x100000
	v_lshl_add_u64 v[214:215], s[16:17], 0, v[130:131]
	s_addc_u32 s7, s17, 0
	s_add_i32 s95, vcc_lo, s50
	global_load_lds_dwordx4 v[214:215], off
	v_lshl_add_u64 v[216:217], s[6:7], 0, v[134:135]
	s_mov_b32 m0, s95
	v_lshl_add_u64 v[218:219], s[42:43], 0, v[132:133]
	global_load_lds_dwordx4 v[216:217], off
	v_lshl_add_u64 v[216:217], s[6:7], 0, v[130:131]
	s_add_i32 m0, s95, 0x2000
	s_nop 0
	global_load_lds_dwordx4 v[216:217], off
	v_lshl_add_u64 v[216:217], s[42:43], 0, v[136:137]
	s_mov_b32 m0, s69
	s_nop 0
	global_load_lds_dwordx4 v[216:217], off
	s_mov_b32 m0, s72
	s_nop 0
	global_load_lds_dwordx4 v[218:219], off
	s_waitcnt vmcnt(8)
	s_waitcnt lgkmcnt(0)
	s_setprio 1
	s_barrier
; #define PG8_STAGEA(bufoff, gbase, voff) PG8_STAGE_X(bufoff, gbase, voff, AUXA)
; #define PG8_STAGEB(bufoff, gbase, voff) PG8_STAGE_X(bufoff, gbase, voff, AUXB)
; #define PG8_LDA(dst, b, h) do { _Pragma("unroll") for (int m = 0; m < 4; ++m) _Pragma("unroll") for (int k = 0; k < 2; ++k) dst[m][k] = *(const PG8_LAS bf16x8*)(lds + PG8_SA(b, h) + aoff + m * 2048 + k * 1024); } while (0)
; #define PG8_LDB(dst, b, h) do { _Pragma("unroll") for (int n = 0; n < 2; ++n) _Pragma("unroll") for (int k = 0; k < 2; ++k) dst[n][k] = *(const PG8_LAS bf16x8*)(lds + PG8_SB(b, h) + boff + n * 2048 + k * 1024); } while (0)
; #define PG8_MMA(ai, bj, At, Bt) do { if (GEMM_PRIO_MODE == 0) __builtin_amdgcn_s_setprio(1); PG8_MMA_LOOPS \
;         acc[ai][bj][m][n] = __builtin_amdgcn_mfma_f32_16x16x32_bf16(Bt[n][k], At[m][k], acc[ai][bj][m][n], 0, 0, 0); if (GEMM_PRIO_MODE == 0) __builtin_amdgcn_s_setprio(0); } while (0)
; #define PG8_WAIT_V(n) asm volatile("s_waitcnt vmcnt(" #n ")" ::: "memory")
; #define PG8_WAIT_VR(n, nr, flag) asm volatile("s_cmp_eq_u32 %0, 0\n\ts_cbranch_scc1 .Lpg8s%=\n\ts_waitcnt vmcnt(" #nr ")\n\ts_branch .Lpg8d%=\n.Lpg8s%=:\n\ts_waitcnt vmcnt(" #n ")\n.Lpg8d%=:" :: "s"(flag) : "memory", "scc")
; #define PG8_WAIT_L(n) asm volatile("s_waitcnt lgkmcnt(" #n ")" ::: "memory")
; #define PG8_BAR __builtin_amdgcn_s_barrier()
; #define PG8_SCHED __builtin_amdgcn_sched_barrier(0)
;     ...
;             PG8_LDA(At, 0, 1); PG8_STAGEB(PG8_SB(0, 0), b2, voffB); PG8_STAGEB(PG8_SB(0, 1), b2 + hstepB, voffB); PG8_STAGEA(PG8_SA(0, 0), a2, voffA);
;     ...
;             PG8_WAIT_VR(8, 24, relax); PG8_WAIT_L(0); PG8_BAR; PG8_MMA(1, 0, At, B0); PG8_MMA(1, 1, At, B1); PG8_BAR; PG8_SCHED;
;     ...
;             PG8_WAIT_V(8); PG8_WAIT_L(0); PG8_BAR; PG8_MMA(1, 0, At, B0); PG8_MMA(1, 1, At, B1); PG8_BAR; PG8_SCHED;
;     ...
;             PG8_LDB(B0, 1, 0); PG8_LDB(B1, 1, 1); PG8_SCHED; PG8_LDA(At, 1, 0); PG8_STAGEA(PG8_SA(0, 1), a2 + hstepA, voffA);
;             PG8_WAIT_V(8); PG8_WAIT_L(0); PG8_BAR; PG8_MMA(0, 0, At, B0); PG8_MMA(0, 1, At, B1); PG8_BAR; PG8_SCHED;
	v_mfma_f32_16x16x32_bf16 v[62:65], v[150:153], v[182:185], 0
	v_mfma_f32_16x16x32_bf16 v[58:61], v[158:161], v[182:185], 0
	v_mfma_f32_16x16x32_bf16 v[46:49], v[150:153], v[190:193], 0
	v_mfma_f32_16x16x32_bf16 v[42:45], v[158:161], v[190:193], 0
	v_mfma_f32_16x16x32_bf16 v[30:33], v[150:153], v[198:201], 0
	v_mfma_f32_16x16x32_bf16 v[26:29], v[158:161], v[198:201], 0
	v_mfma_f32_16x16x32_bf16 v[12:15], v[150:153], v[206:209], 0
	v_mfma_f32_16x16x32_bf16 v[8:11], v[158:161], v[206:209], 0
	v_mfma_f32_16x16x32_bf16 v[62:65], v[154:157], v[186:189], v[62:65]
	v_mfma_f32_16x16x32_bf16 v[58:61], v[162:165], v[186:189], v[58:61]
	v_mfma_f32_16x16x32_bf16 v[46:49], v[154:157], v[194:197], v[46:49]
	v_mfma_f32_16x16x32_bf16 v[42:45], v[162:165], v[194:197], v[42:45]
	v_mfma_f32_16x16x32_bf16 v[30:33], v[154:157], v[202:205], v[30:33]
	v_mfma_f32_16x16x32_bf16 v[26:29], v[162:165], v[202:205], v[26:29]
	v_mfma_f32_16x16x32_bf16 v[12:15], v[154:157], v[210:213], v[12:15]
	v_mfma_f32_16x16x32_bf16 v[8:11], v[162:165], v[210:213], v[8:11]
	v_mfma_f32_16x16x32_bf16 v[54:57], v[166:169], v[182:185], 0
	v_mfma_f32_16x16x32_bf16 v[50:53], v[174:177], v[182:185], 0
	v_mfma_f32_16x16x32_bf16 v[38:41], v[166:169], v[190:193], 0
	v_mfma_f32_16x16x32_bf16 v[34:37], v[174:177], v[190:193], 0
	v_mfma_f32_16x16x32_bf16 v[22:25], v[166:169], v[198:201], 0
	v_mfma_f32_16x16x32_bf16 v[18:21], v[174:177], v[198:201], 0
	v_mfma_f32_16x16x32_bf16 v[4:7], v[166:169], v[206:209], 0
	v_mfma_f32_16x16x32_bf16 v[0:3], v[174:177], v[206:209], 0
	v_mfma_f32_16x16x32_bf16 v[54:57], v[170:173], v[186:189], v[54:57]
	v_mfma_f32_16x16x32_bf16 v[50:53], v[178:181], v[186:189], v[50:53]
	v_mfma_f32_16x16x32_bf16 v[38:41], v[170:173], v[194:197], v[38:41]
	v_mfma_f32_16x16x32_bf16 v[34:37], v[178:181], v[194:197], v[34:37]
	v_mfma_f32_16x16x32_bf16 v[22:25], v[170:173], v[202:205], v[22:25]
	v_mfma_f32_16x16x32_bf16 v[18:21], v[178:181], v[202:205], v[18:21]
	v_mfma_f32_16x16x32_bf16 v[4:7], v[170:173], v[210:213], v[4:7]
	v_mfma_f32_16x16x32_bf16 v[0:3], v[178:181], v[210:213], v[0:3]
	s_barrier
	s_setprio 0
	s_add_i32 s95, 0, 0x18000
	v_add_u32_e32 v149, s95, v146
	s_add_i32 vcc_lo, 0, 0x1c000
	ds_read_b128 v[150:153], v149
	ds_read_b128 v[154:157], v149 offset:1024
	ds_read_b128 v[158:161], v149 offset:2048
	ds_read_b128 v[162:165], v149 offset:3072
	v_add_u32_e32 v149, vcc_lo, v146
	ds_read_b128 v[166:169], v149
	ds_read_b128 v[170:173], v149 offset:1024
	ds_read_b128 v[174:177], v149 offset:2048
	ds_read_b128 v[178:181], v149 offset:3072
	s_add_u32 s6, s42, 0x100000
	s_addc_u32 s7, s43, 0
	s_mov_b32 m0, s73
	v_lshl_add_u64 v[220:221], s[6:7], 0, v[136:137]
	ds_read_b128 v[182:185], v148 offset:32768
	ds_read_b128 v[186:189], v148 offset:33792
	ds_read_b128 v[190:193], v148 offset:34816
	ds_read_b128 v[194:197], v148 offset:35840
	ds_read_b128 v[198:201], v148 offset:36864
	ds_read_b128 v[202:205], v148 offset:37888
	ds_read_b128 v[206:209], v148 offset:38912
	ds_read_b128 v[210:213], v148 offset:39936
	global_load_lds_dwordx4 v[220:221], off
	v_lshl_add_u64 v[220:221], s[6:7], 0, v[132:133]
	s_mov_b32 m0, s82
	s_nop 0
	global_load_lds_dwordx4 v[220:221], off
	s_waitcnt vmcnt(8)
	s_waitcnt lgkmcnt(0)
	s_setprio 1
	s_barrier
	v_mfma_f32_16x16x32_bf16 v[126:129], v[150:153], v[182:185], v[126:129]
	v_mfma_f32_16x16x32_bf16 v[122:125], v[158:161], v[182:185], v[122:125]
	v_mfma_f32_16x16x32_bf16 v[110:113], v[150:153], v[190:193], v[110:113]
	v_mfma_f32_16x16x32_bf16 v[106:109], v[158:161], v[190:193], v[106:109]
	v_mfma_f32_16x16x32_bf16 v[94:97], v[150:153], v[198:201], v[94:97]
	v_mfma_f32_16x16x32_bf16 v[90:93], v[158:161], v[198:201], v[90:93]
	v_mfma_f32_16x16x32_bf16 v[78:81], v[150:153], v[206:209], v[78:81]
	v_mfma_f32_16x16x32_bf16 v[74:77], v[158:161], v[206:209], v[74:77]
	v_mfma_f32_16x16x32_bf16 v[126:129], v[154:157], v[186:189], v[126:129]
	v_mfma_f32_16x16x32_bf16 v[122:125], v[162:165], v[186:189], v[122:125]
	v_mfma_f32_16x16x32_bf16 v[110:113], v[154:157], v[194:197], v[110:113]
	v_mfma_f32_16x16x32_bf16 v[106:109], v[162:165], v[194:197], v[106:109]
	v_mfma_f32_16x16x32_bf16 v[94:97], v[154:157], v[202:205], v[94:97]
	v_mfma_f32_16x16x32_bf16 v[90:93], v[162:165], v[202:205], v[90:93]
	v_mfma_f32_16x16x32_bf16 v[78:81], v[154:157], v[210:213], v[78:81]
	v_mfma_f32_16x16x32_bf16 v[74:77], v[162:165], v[210:213], v[74:77]
	v_mfma_f32_16x16x32_bf16 v[118:121], v[166:169], v[182:185], v[118:121]
	v_mfma_f32_16x16x32_bf16 v[114:117], v[174:177], v[182:185], v[114:117]
	v_mfma_f32_16x16x32_bf16 v[102:105], v[166:169], v[190:193], v[102:105]
	v_mfma_f32_16x16x32_bf16 v[98:101], v[174:177], v[190:193], v[98:101]
	v_mfma_f32_16x16x32_bf16 v[86:89], v[166:169], v[198:201], v[86:89]
	v_mfma_f32_16x16x32_bf16 v[82:85], v[174:177], v[198:201], v[82:85]
	v_mfma_f32_16x16x32_bf16 v[70:73], v[166:169], v[206:209], v[70:73]
	v_mfma_f32_16x16x32_bf16 v[66:69], v[174:177], v[206:209], v[66:69]
	v_mfma_f32_16x16x32_bf16 v[118:121], v[170:173], v[186:189], v[118:121]
	v_mfma_f32_16x16x32_bf16 v[114:117], v[178:181], v[186:189], v[114:117]
	v_mfma_f32_16x16x32_bf16 v[102:105], v[170:173], v[194:197], v[102:105]
	v_mfma_f32_16x16x32_bf16 v[98:101], v[178:181], v[194:197], v[98:101]
	v_mfma_f32_16x16x32_bf16 v[86:89], v[170:173], v[202:205], v[86:89]
	v_mfma_f32_16x16x32_bf16 v[82:85], v[178:181], v[202:205], v[82:85]
	v_mfma_f32_16x16x32_bf16 v[70:73], v[170:173], v[210:213], v[70:73]
	v_mfma_f32_16x16x32_bf16 v[66:69], v[178:181], v[210:213], v[66:69]
	s_barrier
; #define PG8_STAGEA(bufoff, gbase, voff) PG8_STAGE_X(bufoff, gbase, voff, AUXA)
; #define PG8_STAGEB(bufoff, gbase, voff) PG8_STAGE_X(bufoff, gbase, voff, AUXB)
; #define PG8_LDA(dst, b, h) do { _Pragma("unroll") for (int m = 0; m < 4; ++m) _Pragma("unroll") for (int k = 0; k < 2; ++k) dst[m][k] = *(const PG8_LAS bf16x8*)(lds + PG8_SA(b, h) + aoff + m * 2048 + k * 1024); } while (0)
; #define PG8_WAIT_V(n) asm volatile("s_waitcnt vmcnt(" #n ")" ::: "memory")
; #define PG8_WAIT_L(n) asm volatile("s_waitcnt lgkmcnt(" #n ")" ::: "memory")
;     ...
;         for (int t = t0; t < nt; t += 2) {
;             const bool last = (t == nt - 2);
;             const char* a1 = cA + (size_t)(t + 1) * kstepA;
;             const char* a2 = last ? nA : cA + (size_t)(t + 2) * kstepA; const char* b2 = last ? nB : cB + (size_t)(t + 2) * kstepB;
;             const char* a3 = a2 + kstepA; const char* b3 = b2 + kstepB;
;             if (last && has_next) S.a_ready(nxt);
;             if constexpr (SP2) {
;             PG8_LDB(B0, 0, 0); PG8_LDB(B1, 0, 1); PG8_SCHED; PG8_LDA(At, 0, 0); PG8_STAGEA(PG8_SA(1, 1), a1 + hstepA, voffA);
;     ...
;             const int relax = __builtin_amdgcn_readfirstlane((t == 0 && ui > 0) ? 1 : 0);
;             PG8_WAIT_VR(8, 24, relax); PG8_WAIT_L(0); PG8_BAR; PG8_MMA(0, 0, At, B0); PG8_MMA(0, 1, At, B1); PG8_BAR; PG8_SCHED;
;     ...
;             PG8_WAIT_V(8); PG8_WAIT_L(0); PG8_BAR; PG8_MMA(0, 0, At, B0); PG8_MMA(0, 1, At, B1); PG8_BAR; PG8_SCHED;
;     ...
;             PG8_LDA(At, 0, 1); PG8_STAGEB(PG8_SB(0, 0), b2, voffB); PG8_STAGEB(PG8_SB(0, 1), b2 + hstepB, voffB); PG8_STAGEA(PG8_SA(0, 0), a2, voffA);
;     ...
;             PG8_WAIT_VR(8, 24, relax); PG8_WAIT_L(0); PG8_BAR; PG8_MMA(1, 0, At, B0); PG8_MMA(1, 1, At, B1); PG8_BAR; PG8_SCHED;
;     ...
;             PG8_WAIT_V(8); PG8_WAIT_L(0); PG8_BAR; PG8_MMA(1, 0, At, B0); PG8_MMA(1, 1, At, B1); PG8_BAR; PG8_SCHED;
;     ...
;             PG8_LDB(B0, 1, 0); PG8_LDB(B1, 1, 1); PG8_SCHED; PG8_LDA(At, 1, 0); PG8_STAGEA(PG8_SA(0, 1), a2 + hstepA, voffA);
;             PG8_WAIT_V(8); PG8_WAIT_L(0); PG8_BAR; PG8_MMA(0, 0, At, B0); PG8_MMA(0, 1, At, B1); PG8_BAR; PG8_SCHED;
;             PG8_LDA(At, 1, 1); PG8_STAGEB(PG8_SB(1, 0), b3, voffB); PG8_STAGEB(PG8_SB(1, 1), b3 + hstepB, voffB); PG8_STAGEA(PG8_SA(1, 0), a3, voffA);
;             PG8_WAIT_V(8); PG8_WAIT_L(0); PG8_BAR; PG8_MMA(1, 0, At, B0); PG8_MMA(1, 1, At, B1); PG8_BAR; PG8_SCHED;
	s_setprio 0
	s_add_i32 s6, s95, s50
	v_lshl_add_u64 v[144:145], v[144:145], 0, s[86:87]
	s_mov_b32 m0, s6
	ds_read_b128 v[182:185], v148 offset:49152
	ds_read_b128 v[186:189], v148 offset:50176
	ds_read_b128 v[190:193], v148 offset:51200
	ds_read_b128 v[194:197], v148 offset:52224
	ds_read_b128 v[198:201], v148 offset:53248
	ds_read_b128 v[202:205], v148 offset:54272
	ds_read_b128 v[206:209], v148 offset:55296
	ds_read_b128 v[210:213], v148 offset:56320
	global_load_lds_dwordx4 v[144:145], off
	s_add_i32 m0, s6, 0x2000
	s_add_u32 s6, s16, 0x100080
	v_lshl_add_u64 v[144:145], v[214:215], 0, s[86:87]
	s_addc_u32 s7, s17, 0
	s_add_i32 s16, vcc_lo, s50
	global_load_lds_dwordx4 v[144:145], off
	v_lshl_add_u64 v[144:145], s[6:7], 0, v[134:135]
	s_mov_b32 m0, s16
	s_nop 0
	global_load_lds_dwordx4 v[144:145], off
	v_lshl_add_u64 v[144:145], s[6:7], 0, v[130:131]
	s_add_i32 m0, s16, 0x2000
	s_nop 0
	global_load_lds_dwordx4 v[144:145], off
	v_lshl_add_u64 v[144:145], v[216:217], 0, s[86:87]
	s_mov_b32 m0, s83
	s_nop 0
	global_load_lds_dwordx4 v[144:145], off
	v_lshl_add_u64 v[144:145], v[218:219], 0, s[86:87]
	s_mov_b32 m0, s90
	s_nop 0
	global_load_lds_dwordx4 v[144:145], off
	s_waitcnt vmcnt(8)
	s_waitcnt lgkmcnt(0)
	s_nop 0
	s_setprio 1
	s_barrier
	v_mfma_f32_16x16x32_bf16 v[62:65], v[150:153], v[182:185], v[62:65]
	v_mfma_f32_16x16x32_bf16 v[58:61], v[158:161], v[182:185], v[58:61]
	v_mfma_f32_16x16x32_bf16 v[46:49], v[150:153], v[190:193], v[46:49]
	v_mfma_f32_16x16x32_bf16 v[42:45], v[158:161], v[190:193], v[42:45]
	v_mfma_f32_16x16x32_bf16 v[30:33], v[150:153], v[198:201], v[30:33]
	v_mfma_f32_16x16x32_bf16 v[26:29], v[158:161], v[198:201], v[26:29]
	v_mfma_f32_16x16x32_bf16 v[12:15], v[150:153], v[206:209], v[12:15]
	v_mfma_f32_16x16x32_bf16 v[8:11], v[158:161], v[206:209], v[8:11]
	v_mfma_f32_16x16x32_bf16 v[62:65], v[154:157], v[186:189], v[62:65]
	v_mfma_f32_16x16x32_bf16 v[58:61], v[162:165], v[186:189], v[58:61]
	v_mfma_f32_16x16x32_bf16 v[46:49], v[154:157], v[194:197], v[46:49]
	v_mfma_f32_16x16x32_bf16 v[42:45], v[162:165], v[194:197], v[42:45]
	v_mfma_f32_16x16x32_bf16 v[30:33], v[154:157], v[202:205], v[30:33]
	v_mfma_f32_16x16x32_bf16 v[26:29], v[162:165], v[202:205], v[26:29]
	v_mfma_f32_16x16x32_bf16 v[12:15], v[154:157], v[210:213], v[12:15]
	v_mfma_f32_16x16x32_bf16 v[8:11], v[162:165], v[210:213], v[8:11]
	v_mfma_f32_16x16x32_bf16 v[54:57], v[166:169], v[182:185], v[54:57]
	v_mfma_f32_16x16x32_bf16 v[50:53], v[174:177], v[182:185], v[50:53]
	v_mfma_f32_16x16x32_bf16 v[38:41], v[166:169], v[190:193], v[38:41]
	v_mfma_f32_16x16x32_bf16 v[34:37], v[174:177], v[190:193], v[34:37]
	v_mfma_f32_16x16x32_bf16 v[22:25], v[166:169], v[198:201], v[22:25]
	v_mfma_f32_16x16x32_bf16 v[18:21], v[174:177], v[198:201], v[18:21]
	v_mfma_f32_16x16x32_bf16 v[4:7], v[166:169], v[206:209], v[4:7]
	v_mfma_f32_16x16x32_bf16 v[0:3], v[174:177], v[206:209], v[0:3]
	v_mfma_f32_16x16x32_bf16 v[54:57], v[170:173], v[186:189], v[54:57]
	v_mfma_f32_16x16x32_bf16 v[50:53], v[178:181], v[186:189], v[50:53]
	v_mfma_f32_16x16x32_bf16 v[38:41], v[170:173], v[194:197], v[38:41]
	v_mfma_f32_16x16x32_bf16 v[34:37], v[178:181], v[194:197], v[34:37]
	v_mfma_f32_16x16x32_bf16 v[22:25], v[170:173], v[202:205], v[22:25]
	v_mfma_f32_16x16x32_bf16 v[18:21], v[178:181], v[202:205], v[18:21]
	v_mfma_f32_16x16x32_bf16 v[4:7], v[170:173], v[210:213], v[4:7]
	v_mfma_f32_16x16x32_bf16 v[0:3], v[178:181], v[210:213], v[0:3]
	s_barrier
	s_setprio 0
	s_add_i32 s39, s39, 2
	s_add_u32 s40, s40, 0x100
	s_addc_u32 s41, s41, 0
	s_add_u32 s12, s12, 0x100
	s_addc_u32 s13, s13, 0
.LBB0_712:
	s_add_u32 s6, s40, 0xfff00080
	s_addc_u32 s7, s41, -1
	s_add_i32 s95, 0, 0x10000
	s_cmp_eq_u32 s39, 60
	s_cselect_b32 s43, s0, s7
	s_cselect_b32 s42, s1, s6
	v_add_u32_e32 v144, s95, v146
	s_cselect_b32 s17, s23, s13
	s_cselect_b32 s16, s25, s12
	s_add_i32 vcc_lo, 0, 0x14000
	ds_read_b128 v[150:153], v144
	ds_read_b128 v[154:157], v144 offset:1024
	ds_read_b128 v[158:161], v144 offset:2048
	ds_read_b128 v[162:165], v144 offset:3072
	v_add_u32_e32 v144, vcc_lo, v146
	ds_read_b128 v[166:169], v144
	ds_read_b128 v[170:173], v144 offset:1024
	ds_read_b128 v[174:177], v144 offset:2048
	ds_read_b128 v[178:181], v144 offset:3072
	v_lshl_add_u64 v[144:145], s[40:41], 0, v[140:141]
	s_add_i32 m0, s69, 0xc000
	ds_read_b128 v[182:185], v148
	ds_read_b128 v[186:189], v148 offset:1024
	ds_read_b128 v[190:193], v148 offset:2048
	ds_read_b128 v[194:197], v148 offset:3072
	ds_read_b128 v[198:201], v148 offset:4096
	ds_read_b128 v[202:205], v148 offset:5120
	ds_read_b128 v[206:209], v148 offset:6144
	ds_read_b128 v[210:213], v148 offset:7168
	global_load_lds_dwordx4 v[144:145], off
	v_lshl_add_u64 v[144:145], s[40:41], 0, v[142:143]
	s_add_i32 m0, s69, 0xe000
	s_nop 0
	global_load_lds_dwordx4 v[144:145], off
	s_waitcnt vmcnt(8)
	s_waitcnt lgkmcnt(0)
	s_setprio 1
	s_barrier
; #define PG8_STAGEA(bufoff, gbase, voff) PG8_STAGE_X(bufoff, gbase, voff, AUXA)
; #define PG8_STAGEB(bufoff, gbase, voff) PG8_STAGE_X(bufoff, gbase, voff, AUXB)
; #define PG8_LDA(dst, b, h) do { _Pragma("unroll") for (int m = 0; m < 4; ++m) _Pragma("unroll") for (int k = 0; k < 2; ++k) dst[m][k] = *(const PG8_LAS bf16x8*)(lds + PG8_SA(b, h) + aoff + m * 2048 + k * 1024); } while (0)
; #define PG8_LDB(dst, b, h) do { _Pragma("unroll") for (int n = 0; n < 2; ++n) _Pragma("unroll") for (int k = 0; k < 2; ++k) dst[n][k] = *(const PG8_LAS bf16x8*)(lds + PG8_SB(b, h) + boff + n * 2048 + k * 1024); } while (0)
; #define PG8_MMA(ai, bj, At, Bt) do { if (GEMM_PRIO_MODE == 0) __builtin_amdgcn_s_setprio(1); PG8_MMA_LOOPS \
;         acc[ai][bj][m][n] = __builtin_amdgcn_mfma_f32_16x16x32_bf16(Bt[n][k], At[m][k], acc[ai][bj][m][n], 0, 0, 0); if (GEMM_PRIO_MODE == 0) __builtin_amdgcn_s_setprio(0); } while (0)
; #define PG8_WAIT_V(n) asm volatile("s_waitcnt vmcnt(" #n ")" ::: "memory")
; #define PG8_WAIT_VR(n, nr, flag) asm volatile("s_cmp_eq_u32 %0, 0\n\ts_cbranch_scc1 .Lpg8s%=\n\ts_waitcnt vmcnt(" #nr ")\n\ts_branch .Lpg8d%=\n.Lpg8s%=:\n\ts_waitcnt vmcnt(" #n ")\n.Lpg8d%=:" :: "s"(flag) : "memory", "scc")
; #define PG8_WAIT_L(n) asm volatile("s_waitcnt lgkmcnt(" #n ")" ::: "memory")
; #define PG8_BAR __builtin_amdgcn_s_barrier()
; #define PG8_SCHED __builtin_amdgcn_sched_barrier(0)
;     ...
;             PG8_LDB(B0, 0, 0); PG8_LDB(B1, 0, 1); PG8_SCHED; PG8_LDA(At, 0, 0); PG8_STAGEA(PG8_SA(1, 1), a1 + hstepA, voffA);
;     ...
;             const int relax = __builtin_amdgcn_readfirstlane((t == 0 && ui > 0) ? 1 : 0);
;             PG8_WAIT_VR(8, 24, relax); PG8_WAIT_L(0); PG8_BAR; PG8_MMA(0, 0, At, B0); PG8_MMA(0, 1, At, B1); PG8_BAR; PG8_SCHED;
;     ...
;             PG8_WAIT_V(8); PG8_WAIT_L(0); PG8_BAR; PG8_MMA(0, 0, At, B0); PG8_MMA(0, 1, At, B1); PG8_BAR; PG8_SCHED;
;     ...
;             PG8_LDA(At, 0, 1); PG8_STAGEB(PG8_SB(0, 0), b2, voffB); PG8_STAGEB(PG8_SB(0, 1), b2 + hstepB, voffB); PG8_STAGEA(PG8_SA(0, 0), a2, voffA);
;     ...
;             PG8_WAIT_VR(8, 24, relax); PG8_WAIT_L(0); PG8_BAR; PG8_MMA(1, 0, At, B0); PG8_MMA(1, 1, At, B1); PG8_BAR; PG8_SCHED;
;     ...
;             PG8_WAIT_V(8); PG8_WAIT_L(0); PG8_BAR; PG8_MMA(1, 0, At, B0); PG8_MMA(1, 1, At, B1); PG8_BAR; PG8_SCHED;
	v_mfma_f32_16x16x32_bf16 v[126:129], v[150:153], v[182:185], v[126:129]
	v_mfma_f32_16x16x32_bf16 v[122:125], v[158:161], v[182:185], v[122:125]
	v_mfma_f32_16x16x32_bf16 v[110:113], v[150:153], v[190:193], v[110:113]
	v_mfma_f32_16x16x32_bf16 v[106:109], v[158:161], v[190:193], v[106:109]
	v_mfma_f32_16x16x32_bf16 v[94:97], v[150:153], v[198:201], v[94:97]
	v_mfma_f32_16x16x32_bf16 v[90:93], v[158:161], v[198:201], v[90:93]
	v_mfma_f32_16x16x32_bf16 v[78:81], v[150:153], v[206:209], v[78:81]
	v_mfma_f32_16x16x32_bf16 v[74:77], v[158:161], v[206:209], v[74:77]
	v_mfma_f32_16x16x32_bf16 v[126:129], v[154:157], v[186:189], v[126:129]
	v_mfma_f32_16x16x32_bf16 v[122:125], v[162:165], v[186:189], v[122:125]
	v_mfma_f32_16x16x32_bf16 v[110:113], v[154:157], v[194:197], v[110:113]
	v_mfma_f32_16x16x32_bf16 v[106:109], v[162:165], v[194:197], v[106:109]
	v_mfma_f32_16x16x32_bf16 v[94:97], v[154:157], v[202:205], v[94:97]
	v_mfma_f32_16x16x32_bf16 v[90:93], v[162:165], v[202:205], v[90:93]
	v_mfma_f32_16x16x32_bf16 v[78:81], v[154:157], v[210:213], v[78:81]
	v_mfma_f32_16x16x32_bf16 v[74:77], v[162:165], v[210:213], v[74:77]
	v_mfma_f32_16x16x32_bf16 v[118:121], v[166:169], v[182:185], v[118:121]
	v_mfma_f32_16x16x32_bf16 v[114:117], v[174:177], v[182:185], v[114:117]
	v_mfma_f32_16x16x32_bf16 v[102:105], v[166:169], v[190:193], v[102:105]
	v_mfma_f32_16x16x32_bf16 v[98:101], v[174:177], v[190:193], v[98:101]
	v_mfma_f32_16x16x32_bf16 v[86:89], v[166:169], v[198:201], v[86:89]
	v_mfma_f32_16x16x32_bf16 v[82:85], v[174:177], v[198:201], v[82:85]
	v_mfma_f32_16x16x32_bf16 v[70:73], v[166:169], v[206:209], v[70:73]
	v_mfma_f32_16x16x32_bf16 v[66:69], v[174:177], v[206:209], v[66:69]
	v_mfma_f32_16x16x32_bf16 v[118:121], v[170:173], v[186:189], v[118:121]
	v_mfma_f32_16x16x32_bf16 v[114:117], v[178:181], v[186:189], v[114:117]
	v_mfma_f32_16x16x32_bf16 v[102:105], v[170:173], v[194:197], v[102:105]
	v_mfma_f32_16x16x32_bf16 v[98:101], v[178:181], v[194:197], v[98:101]
	v_mfma_f32_16x16x32_bf16 v[86:89], v[170:173], v[202:205], v[86:89]
	v_mfma_f32_16x16x32_bf16 v[82:85], v[178:181], v[202:205], v[82:85]
	v_mfma_f32_16x16x32_bf16 v[70:73], v[170:173], v[210:213], v[70:73]
	v_mfma_f32_16x16x32_bf16 v[66:69], v[178:181], v[210:213], v[66:69]
	s_barrier
	s_setprio 0
	s_add_i32 s6, s95, s50
	v_lshl_add_u64 v[144:145], s[16:17], 0, v[134:135]
	s_mov_b32 m0, s6
	ds_read_b128 v[182:185], v148 offset:16384
	ds_read_b128 v[186:189], v148 offset:17408
	ds_read_b128 v[190:193], v148 offset:18432
	ds_read_b128 v[194:197], v148 offset:19456
	ds_read_b128 v[198:201], v148 offset:20480
	ds_read_b128 v[202:205], v148 offset:21504
	ds_read_b128 v[206:209], v148 offset:22528
	ds_read_b128 v[210:213], v148 offset:23552
	global_load_lds_dwordx4 v[144:145], off
	s_add_i32 m0, s6, 0x2000
	s_add_u32 s6, s16, 0x100000
	v_lshl_add_u64 v[214:215], s[16:17], 0, v[130:131]
	s_addc_u32 s7, s17, 0
	s_add_i32 s95, vcc_lo, s50
	global_load_lds_dwordx4 v[214:215], off
	v_lshl_add_u64 v[216:217], s[6:7], 0, v[134:135]
	s_mov_b32 m0, s95
	v_lshl_add_u64 v[218:219], s[42:43], 0, v[132:133]
	global_load_lds_dwordx4 v[216:217], off
	v_lshl_add_u64 v[216:217], s[6:7], 0, v[130:131]
	s_add_i32 m0, s95, 0x2000
	s_nop 0
	global_load_lds_dwordx4 v[216:217], off
	v_lshl_add_u64 v[216:217], s[42:43], 0, v[136:137]
	s_mov_b32 m0, s69
	s_nop 0
	global_load_lds_dwordx4 v[216:217], off
	s_mov_b32 m0, s72
	s_nop 0
	global_load_lds_dwordx4 v[218:219], off
	s_waitcnt vmcnt(8)
	s_waitcnt lgkmcnt(0)
	s_setprio 1
	s_barrier
	v_mfma_f32_16x16x32_bf16 v[62:65], v[150:153], v[182:185], v[62:65]
	v_mfma_f32_16x16x32_bf16 v[58:61], v[158:161], v[182:185], v[58:61]
	v_mfma_f32_16x16x32_bf16 v[46:49], v[150:153], v[190:193], v[46:49]
	v_mfma_f32_16x16x32_bf16 v[42:45], v[158:161], v[190:193], v[42:45]
	v_mfma_f32_16x16x32_bf16 v[30:33], v[150:153], v[198:201], v[30:33]
	v_mfma_f32_16x16x32_bf16 v[26:29], v[158:161], v[198:201], v[26:29]
	v_mfma_f32_16x16x32_bf16 v[12:15], v[150:153], v[206:209], v[12:15]
	v_mfma_f32_16x16x32_bf16 v[8:11], v[158:161], v[206:209], v[8:11]
	v_mfma_f32_16x16x32_bf16 v[62:65], v[154:157], v[186:189], v[62:65]
	v_mfma_f32_16x16x32_bf16 v[58:61], v[162:165], v[186:189], v[58:61]
	v_mfma_f32_16x16x32_bf16 v[46:49], v[154:157], v[194:197], v[46:49]
	v_mfma_f32_16x16x32_bf16 v[42:45], v[162:165], v[194:197], v[42:45]
	v_mfma_f32_16x16x32_bf16 v[30:33], v[154:157], v[202:205], v[30:33]
	v_mfma_f32_16x16x32_bf16 v[26:29], v[162:165], v[202:205], v[26:29]
	v_mfma_f32_16x16x32_bf16 v[12:15], v[154:157], v[210:213], v[12:15]
	v_mfma_f32_16x16x32_bf16 v[8:11], v[162:165], v[210:213], v[8:11]
	v_mfma_f32_16x16x32_bf16 v[54:57], v[166:169], v[182:185], v[54:57]
	v_mfma_f32_16x16x32_bf16 v[50:53], v[174:177], v[182:185], v[50:53]
	v_mfma_f32_16x16x32_bf16 v[38:41], v[166:169], v[190:193], v[38:41]
	v_mfma_f32_16x16x32_bf16 v[34:37], v[174:177], v[190:193], v[34:37]
	v_mfma_f32_16x16x32_bf16 v[22:25], v[166:169], v[198:201], v[22:25]
	v_mfma_f32_16x16x32_bf16 v[18:21], v[174:177], v[198:201], v[18:21]
	v_mfma_f32_16x16x32_bf16 v[4:7], v[166:169], v[206:209], v[4:7]
	v_mfma_f32_16x16x32_bf16 v[0:3], v[174:177], v[206:209], v[0:3]
	v_mfma_f32_16x16x32_bf16 v[54:57], v[170:173], v[186:189], v[54:57]
	v_mfma_f32_16x16x32_bf16 v[50:53], v[178:181], v[186:189], v[50:53]
	v_mfma_f32_16x16x32_bf16 v[38:41], v[170:173], v[194:197], v[38:41]
	v_mfma_f32_16x16x32_bf16 v[34:37], v[178:181], v[194:197], v[34:37]
	v_mfma_f32_16x16x32_bf16 v[22:25], v[170:173], v[202:205], v[22:25]
	v_mfma_f32_16x16x32_bf16 v[18:21], v[178:181], v[202:205], v[18:21]
	v_mfma_f32_16x16x32_bf16 v[4:7], v[170:173], v[210:213], v[4:7]
	v_mfma_f32_16x16x32_bf16 v[0:3], v[178:181], v[210:213], v[0:3]
	s_barrier
; #define PG8_STAGEA(bufoff, gbase, voff) PG8_STAGE_X(bufoff, gbase, voff, AUXA)
; #define PG8_LDA(dst, b, h) do { _Pragma("unroll") for (int m = 0; m < 4; ++m) _Pragma("unroll") for (int k = 0; k < 2; ++k) dst[m][k] = *(const PG8_LAS bf16x8*)(lds + PG8_SA(b, h) + aoff + m * 2048 + k * 1024); } while (0)
; #define PG8_LDB(dst, b, h) do { _Pragma("unroll") for (int n = 0; n < 2; ++n) _Pragma("unroll") for (int k = 0; k < 2; ++k) dst[n][k] = *(const PG8_LAS bf16x8*)(lds + PG8_SB(b, h) + boff + n * 2048 + k * 1024); } while (0)
; #define PG8_MMA(ai, bj, At, Bt) do { if (GEMM_PRIO_MODE == 0) __builtin_amdgcn_s_setprio(1); PG8_MMA_LOOPS \
;         acc[ai][bj][m][n] = __builtin_amdgcn_mfma_f32_16x16x32_bf16(Bt[n][k], At[m][k], acc[ai][bj][m][n], 0, 0, 0); if (GEMM_PRIO_MODE == 0) __builtin_amdgcn_s_setprio(0); } while (0)
; #define PG8_WAIT_V(n) asm volatile("s_waitcnt vmcnt(" #n ")" ::: "memory")
; #define PG8_WAIT_L(n) asm volatile("s_waitcnt lgkmcnt(" #n ")" ::: "memory")
; #define PG8_BAR __builtin_amdgcn_s_barrier()
; #define PG8_SCHED __builtin_amdgcn_sched_barrier(0)
;     ...
;             PG8_LDB(B0, 1, 0); PG8_LDB(B1, 1, 1); PG8_SCHED; PG8_LDA(At, 1, 0); PG8_STAGEA(PG8_SA(0, 1), a2 + hstepA, voffA);
;             PG8_WAIT_V(8); PG8_WAIT_L(0); PG8_BAR; PG8_MMA(0, 0, At, B0); PG8_MMA(0, 1, At, B1); PG8_BAR; PG8_SCHED;
	s_setprio 0
	s_add_i32 s95, 0, 0x18000
	v_add_u32_e32 v149, s95, v146
	s_add_i32 vcc_lo, 0, 0x1c000
	ds_read_b128 v[150:153], v149
	ds_read_b128 v[154:157], v149 offset:1024
	ds_read_b128 v[158:161], v149 offset:2048
	ds_read_b128 v[162:165], v149 offset:3072
	v_add_u32_e32 v149, vcc_lo, v146
	ds_read_b128 v[166:169], v149
	ds_read_b128 v[170:173], v149 offset:1024
	ds_read_b128 v[174:177], v149 offset:2048
	ds_read_b128 v[178:181], v149 offset:3072
	s_add_u32 s6, s42, 0x100000
	s_addc_u32 s7, s43, 0
	s_mov_b32 m0, s73
	v_lshl_add_u64 v[220:221], s[6:7], 0, v[136:137]
	ds_read_b128 v[182:185], v148 offset:32768
	ds_read_b128 v[186:189], v148 offset:33792
	ds_read_b128 v[190:193], v148 offset:34816
	ds_read_b128 v[194:197], v148 offset:35840
	ds_read_b128 v[198:201], v148 offset:36864
	ds_read_b128 v[202:205], v148 offset:37888
	ds_read_b128 v[206:209], v148 offset:38912
	ds_read_b128 v[210:213], v148 offset:39936
	global_load_lds_dwordx4 v[220:221], off
	v_lshl_add_u64 v[220:221], s[6:7], 0, v[132:133]
	s_mov_b32 m0, s82
	s_nop 0
	global_load_lds_dwordx4 v[220:221], off
	s_waitcnt vmcnt(8)
	s_waitcnt lgkmcnt(0)
	s_setprio 1
	s_barrier
	v_mfma_f32_16x16x32_bf16 v[126:129], v[150:153], v[182:185], v[126:129]
	v_mfma_f32_16x16x32_bf16 v[122:125], v[158:161], v[182:185], v[122:125]
	v_mfma_f32_16x16x32_bf16 v[110:113], v[150:153], v[190:193], v[110:113]
	v_mfma_f32_16x16x32_bf16 v[106:109], v[158:161], v[190:193], v[106:109]
	v_mfma_f32_16x16x32_bf16 v[94:97], v[150:153], v[198:201], v[94:97]
	v_mfma_f32_16x16x32_bf16 v[90:93], v[158:161], v[198:201], v[90:93]
	v_mfma_f32_16x16x32_bf16 v[78:81], v[150:153], v[206:209], v[78:81]
	v_mfma_f32_16x16x32_bf16 v[74:77], v[158:161], v[206:209], v[74:77]
	v_mfma_f32_16x16x32_bf16 v[126:129], v[154:157], v[186:189], v[126:129]
	v_mfma_f32_16x16x32_bf16 v[122:125], v[162:165], v[186:189], v[122:125]
	v_mfma_f32_16x16x32_bf16 v[110:113], v[154:157], v[194:197], v[110:113]
	v_mfma_f32_16x16x32_bf16 v[106:109], v[162:165], v[194:197], v[106:109]
	v_mfma_f32_16x16x32_bf16 v[94:97], v[154:157], v[202:205], v[94:97]
	v_mfma_f32_16x16x32_bf16 v[90:93], v[162:165], v[202:205], v[90:93]
	v_mfma_f32_16x16x32_bf16 v[78:81], v[154:157], v[210:213], v[78:81]
	v_mfma_f32_16x16x32_bf16 v[74:77], v[162:165], v[210:213], v[74:77]
	v_mfma_f32_16x16x32_bf16 v[118:121], v[166:169], v[182:185], v[118:121]
	v_mfma_f32_16x16x32_bf16 v[114:117], v[174:177], v[182:185], v[114:117]
	v_mfma_f32_16x16x32_bf16 v[102:105], v[166:169], v[190:193], v[102:105]
	v_mfma_f32_16x16x32_bf16 v[98:101], v[174:177], v[190:193], v[98:101]
	v_mfma_f32_16x16x32_bf16 v[86:89], v[166:169], v[198:201], v[86:89]
	v_mfma_f32_16x16x32_bf16 v[82:85], v[174:177], v[198:201], v[82:85]
	v_mfma_f32_16x16x32_bf16 v[70:73], v[166:169], v[206:209], v[70:73]
	v_mfma_f32_16x16x32_bf16 v[66:69], v[174:177], v[206:209], v[66:69]
	v_mfma_f32_16x16x32_bf16 v[118:121], v[170:173], v[186:189], v[118:121]
	v_mfma_f32_16x16x32_bf16 v[114:117], v[178:181], v[186:189], v[114:117]
	v_mfma_f32_16x16x32_bf16 v[102:105], v[170:173], v[194:197], v[102:105]
	v_mfma_f32_16x16x32_bf16 v[98:101], v[178:181], v[194:197], v[98:101]
	v_mfma_f32_16x16x32_bf16 v[86:89], v[170:173], v[202:205], v[86:89]
	v_mfma_f32_16x16x32_bf16 v[82:85], v[178:181], v[202:205], v[82:85]
	v_mfma_f32_16x16x32_bf16 v[70:73], v[170:173], v[210:213], v[70:73]
	v_mfma_f32_16x16x32_bf16 v[66:69], v[178:181], v[210:213], v[66:69]
	s_barrier
; #define PG8_STAGEA(bufoff, gbase, voff) PG8_STAGE_X(bufoff, gbase, voff, AUXA)
; #define PG8_STAGEB(bufoff, gbase, voff) PG8_STAGE_X(bufoff, gbase, voff, AUXB)
; #define PG8_LDA(dst, b, h) do { _Pragma("unroll") for (int m = 0; m < 4; ++m) _Pragma("unroll") for (int k = 0; k < 2; ++k) dst[m][k] = *(const PG8_LAS bf16x8*)(lds + PG8_SA(b, h) + aoff + m * 2048 + k * 1024); } while (0)
; #define PG8_MMA(ai, bj, At, Bt) do { if (GEMM_PRIO_MODE == 0) __builtin_amdgcn_s_setprio(1); PG8_MMA_LOOPS \
;         acc[ai][bj][m][n] = __builtin_amdgcn_mfma_f32_16x16x32_bf16(Bt[n][k], At[m][k], acc[ai][bj][m][n], 0, 0, 0); if (GEMM_PRIO_MODE == 0) __builtin_amdgcn_s_setprio(0); } while (0)
; #define PG8_WAIT_V(n) asm volatile("s_waitcnt vmcnt(" #n ")" ::: "memory")
; #define PG8_WAIT_L(n) asm volatile("s_waitcnt lgkmcnt(" #n ")" ::: "memory")
; #define PG8_BAR __builtin_amdgcn_s_barrier()
; #define PG8_SCHED __builtin_amdgcn_sched_barrier(0)
;     ...
;             PG8_LDA(At, 1, 1); PG8_STAGEB(PG8_SB(1, 0), b3, voffB); PG8_STAGEB(PG8_SB(1, 1), b3 + hstepB, voffB); PG8_STAGEA(PG8_SA(1, 0), a3, voffA);
;             PG8_WAIT_V(8); PG8_WAIT_L(0); PG8_BAR; PG8_MMA(1, 0, At, B0); PG8_MMA(1, 1, At, B1); PG8_BAR; PG8_SCHED;
;     ...
;         if constexpr (ALIGN_EPI) { if (wr == 0) PG8_BAR; }
	s_setprio 0
	s_add_i32 s6, s95, s50
	v_lshl_add_u64 v[144:145], v[144:145], 0, s[86:87]
	s_mov_b32 m0, s6
	ds_read_b128 v[182:185], v148 offset:49152
	ds_read_b128 v[186:189], v148 offset:50176
	ds_read_b128 v[190:193], v148 offset:51200
	ds_read_b128 v[194:197], v148 offset:52224
	ds_read_b128 v[198:201], v148 offset:53248
	ds_read_b128 v[202:205], v148 offset:54272
	ds_read_b128 v[206:209], v148 offset:55296
	ds_read_b128 v[210:213], v148 offset:56320
	global_load_lds_dwordx4 v[144:145], off
	s_add_i32 m0, s6, 0x2000
	s_add_u32 s6, s16, 0x100080
	v_lshl_add_u64 v[144:145], v[214:215], 0, s[86:87]
	s_addc_u32 s7, s17, 0
	s_add_i32 s16, vcc_lo, s50
	global_load_lds_dwordx4 v[144:145], off
	v_lshl_add_u64 v[144:145], s[6:7], 0, v[134:135]
	s_mov_b32 m0, s16
	s_nop 0
	global_load_lds_dwordx4 v[144:145], off
	v_lshl_add_u64 v[144:145], s[6:7], 0, v[130:131]
	s_add_i32 m0, s16, 0x2000
	s_nop 0
	global_load_lds_dwordx4 v[144:145], off
	v_lshl_add_u64 v[144:145], v[216:217], 0, s[86:87]
	s_mov_b32 m0, s83
	s_nop 0
	global_load_lds_dwordx4 v[144:145], off
	v_lshl_add_u64 v[144:145], v[218:219], 0, s[86:87]
	s_mov_b32 m0, s90
	s_nop 0
	global_load_lds_dwordx4 v[144:145], off
	s_waitcnt vmcnt(8)
	s_waitcnt lgkmcnt(0)
	s_nop 0
	s_setprio 1
	s_barrier
	v_mfma_f32_16x16x32_bf16 v[62:65], v[150:153], v[182:185], v[62:65]
	v_mfma_f32_16x16x32_bf16 v[58:61], v[158:161], v[182:185], v[58:61]
	v_mfma_f32_16x16x32_bf16 v[46:49], v[150:153], v[190:193], v[46:49]
	v_mfma_f32_16x16x32_bf16 v[42:45], v[158:161], v[190:193], v[42:45]
	v_mfma_f32_16x16x32_bf16 v[30:33], v[150:153], v[198:201], v[30:33]
	v_mfma_f32_16x16x32_bf16 v[26:29], v[158:161], v[198:201], v[26:29]
	v_mfma_f32_16x16x32_bf16 v[12:15], v[150:153], v[206:209], v[12:15]
	v_mfma_f32_16x16x32_bf16 v[8:11], v[158:161], v[206:209], v[8:11]
	v_mfma_f32_16x16x32_bf16 v[62:65], v[154:157], v[186:189], v[62:65]
	v_mfma_f32_16x16x32_bf16 v[58:61], v[162:165], v[186:189], v[58:61]
	v_mfma_f32_16x16x32_bf16 v[46:49], v[154:157], v[194:197], v[46:49]
	v_mfma_f32_16x16x32_bf16 v[42:45], v[162:165], v[194:197], v[42:45]
	v_mfma_f32_16x16x32_bf16 v[30:33], v[154:157], v[202:205], v[30:33]
	v_mfma_f32_16x16x32_bf16 v[26:29], v[162:165], v[202:205], v[26:29]
	v_mfma_f32_16x16x32_bf16 v[12:15], v[154:157], v[210:213], v[12:15]
	v_mfma_f32_16x16x32_bf16 v[8:11], v[162:165], v[210:213], v[8:11]
	v_mfma_f32_16x16x32_bf16 v[54:57], v[166:169], v[182:185], v[54:57]
	v_mfma_f32_16x16x32_bf16 v[50:53], v[174:177], v[182:185], v[50:53]
	v_mfma_f32_16x16x32_bf16 v[38:41], v[166:169], v[190:193], v[38:41]
	v_mfma_f32_16x16x32_bf16 v[34:37], v[174:177], v[190:193], v[34:37]
	v_mfma_f32_16x16x32_bf16 v[22:25], v[166:169], v[198:201], v[22:25]
	v_mfma_f32_16x16x32_bf16 v[18:21], v[174:177], v[198:201], v[18:21]
	v_mfma_f32_16x16x32_bf16 v[4:7], v[166:169], v[206:209], v[4:7]
	v_mfma_f32_16x16x32_bf16 v[0:3], v[174:177], v[206:209], v[0:3]
	v_mfma_f32_16x16x32_bf16 v[54:57], v[170:173], v[186:189], v[54:57]
	v_mfma_f32_16x16x32_bf16 v[50:53], v[178:181], v[186:189], v[50:53]
	v_mfma_f32_16x16x32_bf16 v[38:41], v[170:173], v[194:197], v[38:41]
	v_mfma_f32_16x16x32_bf16 v[34:37], v[178:181], v[194:197], v[34:37]
	v_mfma_f32_16x16x32_bf16 v[22:25], v[170:173], v[202:205], v[22:25]
	v_mfma_f32_16x16x32_bf16 v[18:21], v[178:181], v[202:205], v[18:21]
	v_mfma_f32_16x16x32_bf16 v[4:7], v[170:173], v[210:213], v[4:7]
	v_mfma_f32_16x16x32_bf16 v[0:3], v[178:181], v[210:213], v[0:3]
	s_barrier
	s_setprio 0
	s_add_i32 s39, s39, 2
	s_add_u32 s40, s40, 0x100
	s_addc_u32 s41, s41, 0
	s_add_u32 s12, s12, 0x100
	s_addc_u32 s13, s13, 0
	s_cmp_gt_u32 s39, 61
	s_cbranch_scc0 .LBB0_712
	s_and_b64 vcc, exec, s[18:19]
	s_cbranch_vccz .LBB0_715
	s_barrier

; #define PG8_STAGEA(bufoff, gbase, voff) PG8_STAGE_X(bufoff, gbase, voff, AUXA)
; #define PG8_STR(x) PG8_STR2(x)
;     ...
;         const bool has_next = S.next(ui + 1, nxt);
;         const char* nA = has_next ? (const char*)g.A + (size_t)nxt.pm * tstepA : cA; const char* nB = has_next ? (const char*)g.Bt + (size_t)nxt.pn * tstepB : cB;
;         int t0 = 0;
;         if constexpr (SP2 && GEMM_RELAX == 1) { if (ui > 0) {
;             const char* a1 = cA + kstepA; const char* a2 = cA + 2 * kstepA; const char* b2 = cB + 2 * kstepB; const char* a3 = a2 + kstepA; const char* b3 = b2 + kstepB;
;             PG8_LDB(B0, 0, 0); PG8_LDB(B1, 0, 1); PG8_SCHED; PG8_LDA(At, 0, 0); PG8_STAGEA(PG8_SA(1, 1), a1 + hstepA, voffA);
;             PG8_WAIT_V(24); PG8_WAIT_L(0); PG8_BAR; PG8_MMA(0, 0, At, B0); PG8_MMA(0, 1, At, B1); PG8_BAR; PG8_SCHED;
;             PG8_LDA(At, 0, 1); PG8_STAGEB(PG8_SB(0, 0), b2, voffB); PG8_STAGEB(PG8_SB(0, 1), b2 + hstepB, voffB); PG8_STAGEA(PG8_SA(0, 0), a2, voffA);
;             PG8_WAIT_V(24); PG8_WAIT_L(0); PG8_BAR; PG8_MMA(1, 0, At, B0); PG8_MMA(1, 1, At, B1); PG8_BAR; PG8_SCHED;
;             PG8_LDB(B0, 1, 0); PG8_LDB(B1, 1, 1); PG8_SCHED; PG8_LDA(At, 1, 0); PG8_STAGEA(PG8_SA(0, 1), a2 + hstepA, voffA);
;             PG8_WAIT_V(8); PG8_WAIT_L(0); PG8_BAR; PG8_MMA(0, 0, At, B0); PG8_MMA(0, 1, At, B1); PG8_BAR; PG8_SCHED;
;             PG8_LDA(At, 1, 1); PG8_STAGEB(PG8_SB(1, 0), b3, voffB); PG8_STAGEB(PG8_SB(1, 1), b3 + hstepB, voffB); PG8_STAGEA(PG8_SA(1, 0), a3, voffA);
;             PG8_WAIT_V(8); PG8_WAIT_L(0); PG8_BAR; PG8_MMA(1, 0, At, B0); PG8_MMA(1, 1, At, B1); PG8_BAR; PG8_SCHED;
;             t0 = 2; } }
;     ...
;         asm volatile(".p2align " PG8_STR(GEMM_LOOP_ALIGN) ::: "memory");
;     ...
;         for (int t = t0; t < nt; t += 2) {
;             const bool last = (t == nt - 2);
;             const char* a1 = cA + (size_t)(t + 1) * kstepA;
;             const char* a2 = last ? nA : cA + (size_t)(t + 2) * kstepA; const char* b2 = last ? nB : cB + (size_t)(t + 2) * kstepB;
;             const char* a3 = a2 + kstepA; const char* b3 = b2 + kstepB;
;             if (last && has_next) S.a_ready(nxt);
;             if constexpr (SP2) {
;             PG8_LDB(B0, 0, 0); PG8_LDB(B1, 0, 1); PG8_SCHED; PG8_LDA(At, 0, 0); PG8_STAGEA(PG8_SA(1, 1), a1 + hstepA, voffA);
;     ...
;             const int relax = __builtin_amdgcn_readfirstlane((t == 0 && ui > 0) ? 1 : 0);
.LBB0_847:
	s_ashr_i32 s11, s10, 31
	s_lshl_b64 s[18:19], s[10:11], 23
	s_add_u32 s18, s62, s18
	s_addc_u32 s19, s63, s19
	s_and_b64 s[22:23], s[20:21], exec
	s_cselect_b32 s11, s19, s1
	s_cselect_b32 s73, s18, s0
	s_ashr_i32 s15, s14, 31
	s_lshl_b64 s[22:23], s[14:15], 23
	s_add_u32 s22, s12, s22
	s_addc_u32 s23, s13, s23
	s_and_b64 s[24:25], s[20:21], exec
	s_cselect_b32 s15, s23, s17
	s_cselect_b32 s78, s22, s16
	s_add_u32 s24, s0, 0xc000
	s_addc_u32 s25, s1, 0
	s_add_u32 s0, s16, 0x10000
	s_addc_u32 s1, s17, 0
	s_mov_b32 s82, -2
	s_waitcnt lgkmcnt(0)
	s_add_u32 s16, s24, 0x4000
	s_addc_u32 s17, s25, 0
	s_cmpk_eq_i32 s82, 0xfc
	s_cselect_b32 s36, s73, s16
	s_cselect_b32 s37, s11, s17
	s_cselect_b32 s16, s78, s0
	s_cselect_b32 s17, s15, s1
	s_add_u32 s26, s36, 0x8000
	s_addc_u32 s27, s37, 0
	s_add_i32 s83, 0, 0x10000
	s_add_i32 s94, 0, 0x14000
	v_add_u32_e32 v152, s83, v157
	v_add_u32_e32 v174, s94, v157
	ds_read_b128 v[130:133], v152
	ds_read_b128 v[134:137], v152 offset:1024
	ds_read_b128 v[148:151], v152 offset:2048
	ds_read_b128 v[152:155], v152 offset:3072
	ds_read_b128 v[162:165], v174
	ds_read_b128 v[166:169], v174 offset:1024
	ds_read_b128 v[170:173], v174 offset:2048
	ds_read_b128 v[174:177], v174 offset:3072
	v_lshl_add_u64 v[210:211], s[24:25], 0, v[144:145]
	s_add_i32 m0, s39, 0xc000
	ds_read_b128 v[178:181], v161
	ds_read_b128 v[182:185], v161 offset:1024
	ds_read_b128 v[186:189], v161 offset:2048
	ds_read_b128 v[190:193], v161 offset:3072
	ds_read_b128 v[194:197], v161 offset:4096
	ds_read_b128 v[198:201], v161 offset:5120
	ds_read_b128 v[202:205], v161 offset:6144
	ds_read_b128 v[206:209], v161 offset:7168
	global_load_lds_dwordx4 v[210:211], off
	v_lshl_add_u64 v[210:211], s[24:25], 0, v[146:147]
	s_add_i32 m0, s39, 0xe000
	s_nop 0
	global_load_lds_dwordx4 v[210:211], off
	s_waitcnt vmcnt(8)
	s_waitcnt lgkmcnt(0)
	s_setprio 1
	s_barrier
	v_mfma_f32_16x16x32_bf16 v[126:129], v[130:133], v[178:181], 0
	v_mfma_f32_16x16x32_bf16 v[122:125], v[148:151], v[178:181], 0
	v_mfma_f32_16x16x32_bf16 v[110:113], v[130:133], v[186:189], 0
	v_mfma_f32_16x16x32_bf16 v[106:109], v[148:151], v[186:189], 0
	v_mfma_f32_16x16x32_bf16 v[94:97], v[130:133], v[194:197], 0
	v_mfma_f32_16x16x32_bf16 v[90:93], v[148:151], v[194:197], 0
	v_mfma_f32_16x16x32_bf16 v[78:81], v[130:133], v[202:205], 0
	v_mfma_f32_16x16x32_bf16 v[74:77], v[148:151], v[202:205], 0
	v_mfma_f32_16x16x32_bf16 v[126:129], v[134:137], v[182:185], v[126:129]
	v_mfma_f32_16x16x32_bf16 v[122:125], v[152:155], v[182:185], v[122:125]
	v_mfma_f32_16x16x32_bf16 v[110:113], v[134:137], v[190:193], v[110:113]
	v_mfma_f32_16x16x32_bf16 v[106:109], v[152:155], v[190:193], v[106:109]
	v_mfma_f32_16x16x32_bf16 v[94:97], v[134:137], v[198:201], v[94:97]
	v_mfma_f32_16x16x32_bf16 v[90:93], v[152:155], v[198:201], v[90:93]
	v_mfma_f32_16x16x32_bf16 v[78:81], v[134:137], v[206:209], v[78:81]
	v_mfma_f32_16x16x32_bf16 v[74:77], v[152:155], v[206:209], v[74:77]
	v_mfma_f32_16x16x32_bf16 v[118:121], v[162:165], v[178:181], 0
	v_mfma_f32_16x16x32_bf16 v[114:117], v[170:173], v[178:181], 0
	v_mfma_f32_16x16x32_bf16 v[102:105], v[162:165], v[186:189], 0
	v_mfma_f32_16x16x32_bf16 v[98:101], v[170:173], v[186:189], 0
	v_mfma_f32_16x16x32_bf16 v[86:89], v[162:165], v[194:197], 0
	v_mfma_f32_16x16x32_bf16 v[82:85], v[170:173], v[194:197], 0
	v_mfma_f32_16x16x32_bf16 v[70:73], v[162:165], v[202:205], 0
	v_mfma_f32_16x16x32_bf16 v[66:69], v[170:173], v[202:205], 0
	v_mfma_f32_16x16x32_bf16 v[118:121], v[166:169], v[182:185], v[118:121]
	v_mfma_f32_16x16x32_bf16 v[114:117], v[174:177], v[182:185], v[114:117]
	v_mfma_f32_16x16x32_bf16 v[102:105], v[166:169], v[190:193], v[102:105]
	v_mfma_f32_16x16x32_bf16 v[98:101], v[174:177], v[190:193], v[98:101]
	v_mfma_f32_16x16x32_bf16 v[86:89], v[166:169], v[198:201], v[86:89]
	v_mfma_f32_16x16x32_bf16 v[82:85], v[174:177], v[198:201], v[82:85]
	v_mfma_f32_16x16x32_bf16 v[70:73], v[166:169], v[206:209], v[70:73]
	v_mfma_f32_16x16x32_bf16 v[66:69], v[174:177], v[206:209], v[66:69]
	s_barrier
	s_setprio 0
	s_add_i32 s83, s83, s38
	v_lshl_add_u64 v[210:211], s[16:17], 0, v[16:17]
	s_mov_b32 m0, s83
	ds_read_b128 v[178:181], v161 offset:16384
	ds_read_b128 v[182:185], v161 offset:17408
	ds_read_b128 v[186:189], v161 offset:18432
	ds_read_b128 v[190:193], v161 offset:19456
	ds_read_b128 v[194:197], v161 offset:20480
	ds_read_b128 v[198:201], v161 offset:21504
	ds_read_b128 v[202:205], v161 offset:22528
	ds_read_b128 v[206:209], v161 offset:23552
	global_load_lds_dwordx4 v[210:211], off
	s_add_i32 m0, s83, 0x2000
	s_add_u32 s90, s16, 0x4000
	v_lshl_add_u64 v[210:211], s[16:17], 0, v[138:139]
	s_addc_u32 s91, s17, 0
	s_add_i32 s83, s94, s38
	global_load_lds_dwordx4 v[210:211], off
	v_lshl_add_u64 v[210:211], s[90:91], 0, v[16:17]
	s_mov_b32 m0, s83
	s_nop 0
	global_load_lds_dwordx4 v[210:211], off
	v_lshl_add_u64 v[210:211], s[90:91], 0, v[138:139]
	s_add_i32 m0, s83, 0x2000
	s_nop 0
	global_load_lds_dwordx4 v[210:211], off
	v_lshl_add_u64 v[210:211], s[36:37], 0, v[142:143]
	s_mov_b32 m0, s39
	s_nop 0
	global_load_lds_dwordx4 v[210:211], off
	v_lshl_add_u64 v[210:211], s[36:37], 0, v[140:141]
	s_mov_b32 m0, s40
	s_nop 0
	global_load_lds_dwordx4 v[210:211], off
	s_waitcnt vmcnt(8)
	s_waitcnt lgkmcnt(0)
	s_nop 0
	s_setprio 1
	s_barrier
; #define PG8_STAGEA(bufoff, gbase, voff) PG8_STAGE_X(bufoff, gbase, voff, AUXA)
; #define PG8_STAGEB(bufoff, gbase, voff) PG8_STAGE_X(bufoff, gbase, voff, AUXB)
; #define PG8_LDA(dst, b, h) do { _Pragma("unroll") for (int m = 0; m < 4; ++m) _Pragma("unroll") for (int k = 0; k < 2; ++k) dst[m][k] = *(const PG8_LAS bf16x8*)(lds + PG8_SA(b, h) + aoff + m * 2048 + k * 1024); } while (0)
; #define PG8_LDB(dst, b, h) do { _Pragma("unroll") for (int n = 0; n < 2; ++n) _Pragma("unroll") for (int k = 0; k < 2; ++k) dst[n][k] = *(const PG8_LAS bf16x8*)(lds + PG8_SB(b, h) + boff + n * 2048 + k * 1024); } while (0)
; #define PG8_MMA(ai, bj, At, Bt) do { if (GEMM_PRIO_MODE == 0) __builtin_amdgcn_s_setprio(1); PG8_MMA_LOOPS \
;         acc[ai][bj][m][n] = __builtin_amdgcn_mfma_f32_16x16x32_bf16(Bt[n][k], At[m][k], acc[ai][bj][m][n], 0, 0, 0); if (GEMM_PRIO_MODE == 0) __builtin_amdgcn_s_setprio(0); } while (0)
; #define PG8_WAIT_V(n) asm volatile("s_waitcnt vmcnt(" #n ")" ::: "memory")
; #define PG8_WAIT_VR(n, nr, flag) asm volatile("s_cmp_eq_u32 %0, 0\n\ts_cbranch_scc1 .Lpg8s%=\n\ts_waitcnt vmcnt(" #nr ")\n\ts_branch .Lpg8d%=\n.Lpg8s%=:\n\ts_waitcnt vmcnt(" #n ")\n.Lpg8d%=:" :: "s"(flag) : "memory", "scc")
; #define PG8_WAIT_L(n) asm volatile("s_waitcnt lgkmcnt(" #n ")" ::: "memory")
; #define PG8_BAR __builtin_amdgcn_s_barrier()
; #define PG8_SCHED __builtin_amdgcn_sched_barrier(0)
;     ...
;             PG8_LDA(At, 0, 1); PG8_STAGEB(PG8_SB(0, 0), b2, voffB); PG8_STAGEB(PG8_SB(0, 1), b2 + hstepB, voffB); PG8_STAGEA(PG8_SA(0, 0), a2, voffA);
;     ...
;             PG8_WAIT_VR(8, 24, relax); PG8_WAIT_L(0); PG8_BAR; PG8_MMA(1, 0, At, B0); PG8_MMA(1, 1, At, B1); PG8_BAR; PG8_SCHED;
;     ...
;             PG8_WAIT_V(8); PG8_WAIT_L(0); PG8_BAR; PG8_MMA(1, 0, At, B0); PG8_MMA(1, 1, At, B1); PG8_BAR; PG8_SCHED;
;     ...
;             PG8_LDB(B0, 1, 0); PG8_LDB(B1, 1, 1); PG8_SCHED; PG8_LDA(At, 1, 0); PG8_STAGEA(PG8_SA(0, 1), a2 + hstepA, voffA);
;             PG8_WAIT_V(8); PG8_WAIT_L(0); PG8_BAR; PG8_MMA(0, 0, At, B0); PG8_MMA(0, 1, At, B1); PG8_BAR; PG8_SCHED;
	v_mfma_f32_16x16x32_bf16 v[62:65], v[130:133], v[178:181], 0
	v_mfma_f32_16x16x32_bf16 v[58:61], v[148:151], v[178:181], 0
	v_mfma_f32_16x16x32_bf16 v[46:49], v[130:133], v[186:189], 0
	v_mfma_f32_16x16x32_bf16 v[42:45], v[148:151], v[186:189], 0
	v_mfma_f32_16x16x32_bf16 v[30:33], v[130:133], v[194:197], 0
	v_mfma_f32_16x16x32_bf16 v[26:29], v[148:151], v[194:197], 0
	v_mfma_f32_16x16x32_bf16 v[12:15], v[130:133], v[202:205], 0
	v_mfma_f32_16x16x32_bf16 v[8:11], v[148:151], v[202:205], 0
	v_mfma_f32_16x16x32_bf16 v[62:65], v[134:137], v[182:185], v[62:65]
	v_mfma_f32_16x16x32_bf16 v[58:61], v[152:155], v[182:185], v[58:61]
	v_mfma_f32_16x16x32_bf16 v[46:49], v[134:137], v[190:193], v[46:49]
	v_mfma_f32_16x16x32_bf16 v[42:45], v[152:155], v[190:193], v[42:45]
	v_mfma_f32_16x16x32_bf16 v[30:33], v[134:137], v[198:201], v[30:33]
	v_mfma_f32_16x16x32_bf16 v[26:29], v[152:155], v[198:201], v[26:29]
	v_mfma_f32_16x16x32_bf16 v[12:15], v[134:137], v[206:209], v[12:15]
	v_mfma_f32_16x16x32_bf16 v[8:11], v[152:155], v[206:209], v[8:11]
	v_mfma_f32_16x16x32_bf16 v[54:57], v[162:165], v[178:181], 0
	v_mfma_f32_16x16x32_bf16 v[50:53], v[170:173], v[178:181], 0
	v_mfma_f32_16x16x32_bf16 v[38:41], v[162:165], v[186:189], 0
	v_mfma_f32_16x16x32_bf16 v[34:37], v[170:173], v[186:189], 0
	v_mfma_f32_16x16x32_bf16 v[22:25], v[162:165], v[194:197], 0
	v_mfma_f32_16x16x32_bf16 v[18:21], v[170:173], v[194:197], 0
	v_mfma_f32_16x16x32_bf16 v[4:7], v[162:165], v[202:205], 0
	v_mfma_f32_16x16x32_bf16 v[0:3], v[170:173], v[202:205], 0
	v_mfma_f32_16x16x32_bf16 v[54:57], v[166:169], v[182:185], v[54:57]
	v_mfma_f32_16x16x32_bf16 v[50:53], v[174:177], v[182:185], v[50:53]
	v_mfma_f32_16x16x32_bf16 v[38:41], v[166:169], v[190:193], v[38:41]
	v_mfma_f32_16x16x32_bf16 v[34:37], v[174:177], v[190:193], v[34:37]
	v_mfma_f32_16x16x32_bf16 v[22:25], v[166:169], v[198:201], v[22:25]
	v_mfma_f32_16x16x32_bf16 v[18:21], v[174:177], v[198:201], v[18:21]
	v_mfma_f32_16x16x32_bf16 v[4:7], v[166:169], v[206:209], v[4:7]
	v_mfma_f32_16x16x32_bf16 v[0:3], v[174:177], v[206:209], v[0:3]
	s_barrier
	s_setprio 0
	s_add_i32 s83, 0, 0x18000
	s_add_i32 s90, 0, 0x1c000
	v_add_u32_e32 v152, s83, v157
	v_add_u32_e32 v174, s90, v157
	ds_read_b128 v[130:133], v152
	ds_read_b128 v[134:137], v152 offset:1024
	ds_read_b128 v[148:151], v152 offset:2048
	ds_read_b128 v[152:155], v152 offset:3072
	ds_read_b128 v[162:165], v174
	ds_read_b128 v[166:169], v174 offset:1024
	ds_read_b128 v[170:173], v174 offset:2048
	ds_read_b128 v[174:177], v174 offset:3072
	s_add_u32 s36, s36, 0x4000
	s_addc_u32 s37, s37, 0
	s_mov_b32 m0, s41
	v_lshl_add_u64 v[210:211], s[36:37], 0, v[142:143]
	ds_read_b128 v[178:181], v161 offset:32768
	ds_read_b128 v[182:185], v161 offset:33792
	ds_read_b128 v[186:189], v161 offset:34816
	ds_read_b128 v[190:193], v161 offset:35840
	ds_read_b128 v[194:197], v161 offset:36864
	ds_read_b128 v[198:201], v161 offset:37888
	ds_read_b128 v[202:205], v161 offset:38912
	ds_read_b128 v[206:209], v161 offset:39936
	global_load_lds_dwordx4 v[210:211], off
	v_lshl_add_u64 v[210:211], s[36:37], 0, v[140:141]
	s_mov_b32 m0, s42
	s_nop 0
	global_load_lds_dwordx4 v[210:211], off
	s_waitcnt vmcnt(8)
	s_waitcnt lgkmcnt(0)
	s_setprio 1
	s_barrier
	v_mfma_f32_16x16x32_bf16 v[126:129], v[130:133], v[178:181], v[126:129]
	v_mfma_f32_16x16x32_bf16 v[122:125], v[148:151], v[178:181], v[122:125]
	v_mfma_f32_16x16x32_bf16 v[110:113], v[130:133], v[186:189], v[110:113]
	v_mfma_f32_16x16x32_bf16 v[106:109], v[148:151], v[186:189], v[106:109]
	v_mfma_f32_16x16x32_bf16 v[94:97], v[130:133], v[194:197], v[94:97]
	v_mfma_f32_16x16x32_bf16 v[90:93], v[148:151], v[194:197], v[90:93]
	v_mfma_f32_16x16x32_bf16 v[78:81], v[130:133], v[202:205], v[78:81]
	v_mfma_f32_16x16x32_bf16 v[74:77], v[148:151], v[202:205], v[74:77]
	v_mfma_f32_16x16x32_bf16 v[126:129], v[134:137], v[182:185], v[126:129]
	v_mfma_f32_16x16x32_bf16 v[122:125], v[152:155], v[182:185], v[122:125]
	v_mfma_f32_16x16x32_bf16 v[110:113], v[134:137], v[190:193], v[110:113]
	v_mfma_f32_16x16x32_bf16 v[106:109], v[152:155], v[190:193], v[106:109]
	v_mfma_f32_16x16x32_bf16 v[94:97], v[134:137], v[198:201], v[94:97]
	v_mfma_f32_16x16x32_bf16 v[90:93], v[152:155], v[198:201], v[90:93]
	v_mfma_f32_16x16x32_bf16 v[78:81], v[134:137], v[206:209], v[78:81]
	v_mfma_f32_16x16x32_bf16 v[74:77], v[152:155], v[206:209], v[74:77]
	v_mfma_f32_16x16x32_bf16 v[118:121], v[162:165], v[178:181], v[118:121]
	v_mfma_f32_16x16x32_bf16 v[114:117], v[170:173], v[178:181], v[114:117]
	v_mfma_f32_16x16x32_bf16 v[102:105], v[162:165], v[186:189], v[102:105]
	v_mfma_f32_16x16x32_bf16 v[98:101], v[170:173], v[186:189], v[98:101]
	v_mfma_f32_16x16x32_bf16 v[86:89], v[162:165], v[194:197], v[86:89]
	v_mfma_f32_16x16x32_bf16 v[82:85], v[170:173], v[194:197], v[82:85]
	v_mfma_f32_16x16x32_bf16 v[70:73], v[162:165], v[202:205], v[70:73]
	v_mfma_f32_16x16x32_bf16 v[66:69], v[170:173], v[202:205], v[66:69]
	v_mfma_f32_16x16x32_bf16 v[118:121], v[166:169], v[182:185], v[118:121]
	v_mfma_f32_16x16x32_bf16 v[114:117], v[174:177], v[182:185], v[114:117]
	v_mfma_f32_16x16x32_bf16 v[102:105], v[166:169], v[190:193], v[102:105]
	v_mfma_f32_16x16x32_bf16 v[98:101], v[174:177], v[190:193], v[98:101]
	v_mfma_f32_16x16x32_bf16 v[86:89], v[166:169], v[198:201], v[86:89]
	v_mfma_f32_16x16x32_bf16 v[82:85], v[174:177], v[198:201], v[82:85]
	v_mfma_f32_16x16x32_bf16 v[70:73], v[166:169], v[206:209], v[70:73]
	v_mfma_f32_16x16x32_bf16 v[66:69], v[174:177], v[206:209], v[66:69]
	s_barrier
; #define PG8_STAGEA(bufoff, gbase, voff) PG8_STAGE_X(bufoff, gbase, voff, AUXA)
; #define PG8_STAGEB(bufoff, gbase, voff) PG8_STAGE_X(bufoff, gbase, voff, AUXB)
; #define PG8_LDA(dst, b, h) do { _Pragma("unroll") for (int m = 0; m < 4; ++m) _Pragma("unroll") for (int k = 0; k < 2; ++k) dst[m][k] = *(const PG8_LAS bf16x8*)(lds + PG8_SA(b, h) + aoff + m * 2048 + k * 1024); } while (0)
; #define PG8_WAIT_V(n) asm volatile("s_waitcnt vmcnt(" #n ")" ::: "memory")
; #define PG8_WAIT_L(n) asm volatile("s_waitcnt lgkmcnt(" #n ")" ::: "memory")
;     ...
;         for (int t = t0; t < nt; t += 2) {
;             const bool last = (t == nt - 2);
;             const char* a1 = cA + (size_t)(t + 1) * kstepA;
;             const char* a2 = last ? nA : cA + (size_t)(t + 2) * kstepA; const char* b2 = last ? nB : cB + (size_t)(t + 2) * kstepB;
;             const char* a3 = a2 + kstepA; const char* b3 = b2 + kstepB;
;             if (last && has_next) S.a_ready(nxt);
;             if constexpr (SP2) {
;             PG8_LDB(B0, 0, 0); PG8_LDB(B1, 0, 1); PG8_SCHED; PG8_LDA(At, 0, 0); PG8_STAGEA(PG8_SA(1, 1), a1 + hstepA, voffA);
;     ...
;             const int relax = __builtin_amdgcn_readfirstlane((t == 0 && ui > 0) ? 1 : 0);
;             PG8_WAIT_VR(8, 24, relax); PG8_WAIT_L(0); PG8_BAR; PG8_MMA(0, 0, At, B0); PG8_MMA(0, 1, At, B1); PG8_BAR; PG8_SCHED;
;     ...
;             PG8_WAIT_V(8); PG8_WAIT_L(0); PG8_BAR; PG8_MMA(0, 0, At, B0); PG8_MMA(0, 1, At, B1); PG8_BAR; PG8_SCHED;
;     ...
;             PG8_LDA(At, 0, 1); PG8_STAGEB(PG8_SB(0, 0), b2, voffB); PG8_STAGEB(PG8_SB(0, 1), b2 + hstepB, voffB); PG8_STAGEA(PG8_SA(0, 0), a2, voffA);
;     ...
;             PG8_WAIT_VR(8, 24, relax); PG8_WAIT_L(0); PG8_BAR; PG8_MMA(1, 0, At, B0); PG8_MMA(1, 1, At, B1); PG8_BAR; PG8_SCHED;
;     ...
;             PG8_WAIT_V(8); PG8_WAIT_L(0); PG8_BAR; PG8_MMA(1, 0, At, B0); PG8_MMA(1, 1, At, B1); PG8_BAR; PG8_SCHED;
;     ...
;             PG8_LDB(B0, 1, 0); PG8_LDB(B1, 1, 1); PG8_SCHED; PG8_LDA(At, 1, 0); PG8_STAGEA(PG8_SA(0, 1), a2 + hstepA, voffA);
;             PG8_WAIT_V(8); PG8_WAIT_L(0); PG8_BAR; PG8_MMA(0, 0, At, B0); PG8_MMA(0, 1, At, B1); PG8_BAR; PG8_SCHED;
;             PG8_LDA(At, 1, 1); PG8_STAGEB(PG8_SB(1, 0), b3, voffB); PG8_STAGEB(PG8_SB(1, 1), b3 + hstepB, voffB); PG8_STAGEA(PG8_SA(1, 0), a3, voffA);
;             PG8_WAIT_V(8); PG8_WAIT_L(0); PG8_BAR; PG8_MMA(1, 0, At, B0); PG8_MMA(1, 1, At, B1); PG8_BAR; PG8_SCHED;
	s_setprio 0
	s_add_u32 s36, s16, 0x8000
	s_addc_u32 s37, s17, 0
	s_add_i32 s83, s83, s38
	v_lshl_add_u64 v[210:211], s[36:37], 0, v[16:17]
	s_mov_b32 m0, s83
	ds_read_b128 v[178:181], v161 offset:49152
	ds_read_b128 v[182:185], v161 offset:50176
	ds_read_b128 v[186:189], v161 offset:51200
	ds_read_b128 v[190:193], v161 offset:52224
	ds_read_b128 v[194:197], v161 offset:53248
	ds_read_b128 v[198:201], v161 offset:54272
	ds_read_b128 v[202:205], v161 offset:55296
	ds_read_b128 v[206:209], v161 offset:56320
	global_load_lds_dwordx4 v[210:211], off
	s_add_i32 m0, s83, 0x2000
	s_add_u32 s16, s16, 0xc000
	v_lshl_add_u64 v[210:211], s[36:37], 0, v[138:139]
	s_addc_u32 s17, s17, 0
	s_add_i32 s36, s90, s38
	global_load_lds_dwordx4 v[210:211], off
	v_lshl_add_u64 v[210:211], s[16:17], 0, v[16:17]
	s_mov_b32 m0, s36
	s_nop 0
	global_load_lds_dwordx4 v[210:211], off
	v_lshl_add_u64 v[210:211], s[16:17], 0, v[138:139]
	s_add_i32 m0, s36, 0x2000
	s_nop 0
	global_load_lds_dwordx4 v[210:211], off
	v_lshl_add_u64 v[210:211], s[26:27], 0, v[142:143]
	s_mov_b32 m0, s50
	s_nop 0
	global_load_lds_dwordx4 v[210:211], off
	v_lshl_add_u64 v[210:211], s[26:27], 0, v[140:141]
	s_mov_b32 m0, s51
	s_nop 0
	global_load_lds_dwordx4 v[210:211], off
	s_waitcnt vmcnt(8)
	s_waitcnt lgkmcnt(0)
	s_setprio 1
	s_barrier
	v_mfma_f32_16x16x32_bf16 v[62:65], v[130:133], v[178:181], v[62:65]
	v_mfma_f32_16x16x32_bf16 v[58:61], v[148:151], v[178:181], v[58:61]
	v_mfma_f32_16x16x32_bf16 v[46:49], v[130:133], v[186:189], v[46:49]
	v_mfma_f32_16x16x32_bf16 v[42:45], v[148:151], v[186:189], v[42:45]
	v_mfma_f32_16x16x32_bf16 v[30:33], v[130:133], v[194:197], v[30:33]
	v_mfma_f32_16x16x32_bf16 v[26:29], v[148:151], v[194:197], v[26:29]
	v_mfma_f32_16x16x32_bf16 v[12:15], v[130:133], v[202:205], v[12:15]
	v_mfma_f32_16x16x32_bf16 v[8:11], v[148:151], v[202:205], v[8:11]
	v_mfma_f32_16x16x32_bf16 v[62:65], v[134:137], v[182:185], v[62:65]
	v_mfma_f32_16x16x32_bf16 v[58:61], v[152:155], v[182:185], v[58:61]
	v_mfma_f32_16x16x32_bf16 v[46:49], v[134:137], v[190:193], v[46:49]
	v_mfma_f32_16x16x32_bf16 v[42:45], v[152:155], v[190:193], v[42:45]
	v_mfma_f32_16x16x32_bf16 v[30:33], v[134:137], v[198:201], v[30:33]
	v_mfma_f32_16x16x32_bf16 v[26:29], v[152:155], v[198:201], v[26:29]
	v_mfma_f32_16x16x32_bf16 v[12:15], v[134:137], v[206:209], v[12:15]
	v_mfma_f32_16x16x32_bf16 v[8:11], v[152:155], v[206:209], v[8:11]
	v_mfma_f32_16x16x32_bf16 v[54:57], v[162:165], v[178:181], v[54:57]
	v_mfma_f32_16x16x32_bf16 v[50:53], v[170:173], v[178:181], v[50:53]
	v_mfma_f32_16x16x32_bf16 v[38:41], v[162:165], v[186:189], v[38:41]
	v_mfma_f32_16x16x32_bf16 v[34:37], v[170:173], v[186:189], v[34:37]
	v_mfma_f32_16x16x32_bf16 v[22:25], v[162:165], v[194:197], v[22:25]
	v_mfma_f32_16x16x32_bf16 v[18:21], v[170:173], v[194:197], v[18:21]
	v_mfma_f32_16x16x32_bf16 v[4:7], v[162:165], v[202:205], v[4:7]
	v_mfma_f32_16x16x32_bf16 v[0:3], v[170:173], v[202:205], v[0:3]
	v_mfma_f32_16x16x32_bf16 v[54:57], v[166:169], v[182:185], v[54:57]
	v_mfma_f32_16x16x32_bf16 v[50:53], v[174:177], v[182:185], v[50:53]
	v_mfma_f32_16x16x32_bf16 v[38:41], v[166:169], v[190:193], v[38:41]
	v_mfma_f32_16x16x32_bf16 v[34:37], v[174:177], v[190:193], v[34:37]
	v_mfma_f32_16x16x32_bf16 v[22:25], v[166:169], v[198:201], v[22:25]
	v_mfma_f32_16x16x32_bf16 v[18:21], v[174:177], v[198:201], v[18:21]
	v_mfma_f32_16x16x32_bf16 v[4:7], v[166:169], v[206:209], v[4:7]
	v_mfma_f32_16x16x32_bf16 v[0:3], v[174:177], v[206:209], v[0:3]
	s_barrier
	s_setprio 0
	s_add_i32 s82, s82, 2
	s_add_u32 s24, s24, 0x10000
	s_addc_u32 s25, s25, 0
	s_add_u32 s0, s0, 0x10000
	s_addc_u32 s1, s1, 0
.LBB0_848:
	s_add_u32 s16, s24, 0x4000
	s_addc_u32 s17, s25, 0
	s_cmpk_eq_i32 s82, 0xfc
	s_cselect_b32 s36, s73, s16
	s_cselect_b32 s37, s11, s17
	s_cselect_b32 s16, s78, s0
	s_cselect_b32 s17, s15, s1
	s_add_u32 s26, s36, 0x8000
	s_addc_u32 s27, s37, 0
	s_add_i32 s83, 0, 0x10000
	s_add_i32 s94, 0, 0x14000
	v_add_u32_e32 v152, s83, v157
	v_add_u32_e32 v174, s94, v157
	ds_read_b128 v[130:133], v152
	ds_read_b128 v[134:137], v152 offset:1024
	ds_read_b128 v[148:151], v152 offset:2048
	ds_read_b128 v[152:155], v152 offset:3072
	ds_read_b128 v[162:165], v174
	ds_read_b128 v[166:169], v174 offset:1024
	ds_read_b128 v[170:173], v174 offset:2048
	ds_read_b128 v[174:177], v174 offset:3072
	v_lshl_add_u64 v[210:211], s[24:25], 0, v[144:145]
	s_add_i32 m0, s39, 0xc000
	ds_read_b128 v[178:181], v161
	ds_read_b128 v[182:185], v161 offset:1024
	ds_read_b128 v[186:189], v161 offset:2048
	ds_read_b128 v[190:193], v161 offset:3072
	ds_read_b128 v[194:197], v161 offset:4096
	ds_read_b128 v[198:201], v161 offset:5120
	ds_read_b128 v[202:205], v161 offset:6144
	ds_read_b128 v[206:209], v161 offset:7168
	global_load_lds_dwordx4 v[210:211], off
	v_lshl_add_u64 v[210:211], s[24:25], 0, v[146:147]
	s_add_i32 m0, s39, 0xe000
	s_nop 0
	global_load_lds_dwordx4 v[210:211], off
	s_waitcnt vmcnt(8)
	s_waitcnt lgkmcnt(0)
	s_nop 0
	s_setprio 1
	s_barrier
; #define PG8_STAGEA(bufoff, gbase, voff) PG8_STAGE_X(bufoff, gbase, voff, AUXA)
; #define PG8_STAGEB(bufoff, gbase, voff) PG8_STAGE_X(bufoff, gbase, voff, AUXB)
; #define PG8_LDA(dst, b, h) do { _Pragma("unroll") for (int m = 0; m < 4; ++m) _Pragma("unroll") for (int k = 0; k < 2; ++k) dst[m][k] = *(const PG8_LAS bf16x8*)(lds + PG8_SA(b, h) + aoff + m * 2048 + k * 1024); } while (0)
; #define PG8_LDB(dst, b, h) do { _Pragma("unroll") for (int n = 0; n < 2; ++n) _Pragma("unroll") for (int k = 0; k < 2; ++k) dst[n][k] = *(const PG8_LAS bf16x8*)(lds + PG8_SB(b, h) + boff + n * 2048 + k * 1024); } while (0)
; #define PG8_MMA(ai, bj, At, Bt) do { if (GEMM_PRIO_MODE == 0) __builtin_amdgcn_s_setprio(1); PG8_MMA_LOOPS \
;         acc[ai][bj][m][n] = __builtin_amdgcn_mfma_f32_16x16x32_bf16(Bt[n][k], At[m][k], acc[ai][bj][m][n], 0, 0, 0); if (GEMM_PRIO_MODE == 0) __builtin_amdgcn_s_setprio(0); } while (0)
; #define PG8_WAIT_V(n) asm volatile("s_waitcnt vmcnt(" #n ")" ::: "memory")
; #define PG8_WAIT_VR(n, nr, flag) asm volatile("s_cmp_eq_u32 %0, 0\n\ts_cbranch_scc1 .Lpg8s%=\n\ts_waitcnt vmcnt(" #nr ")\n\ts_branch .Lpg8d%=\n.Lpg8s%=:\n\ts_waitcnt vmcnt(" #n ")\n.Lpg8d%=:" :: "s"(flag) : "memory", "scc")
; #define PG8_WAIT_L(n) asm volatile("s_waitcnt lgkmcnt(" #n ")" ::: "memory")
; #define PG8_BAR __builtin_amdgcn_s_barrier()
; #define PG8_SCHED __builtin_amdgcn_sched_barrier(0)
;     ...
;             PG8_LDB(B0, 0, 0); PG8_LDB(B1, 0, 1); PG8_SCHED; PG8_LDA(At, 0, 0); PG8_STAGEA(PG8_SA(1, 1), a1 + hstepA, voffA);
;     ...
;             const int relax = __builtin_amdgcn_readfirstlane((t == 0 && ui > 0) ? 1 : 0);
;             PG8_WAIT_VR(8, 24, relax); PG8_WAIT_L(0); PG8_BAR; PG8_MMA(0, 0, At, B0); PG8_MMA(0, 1, At, B1); PG8_BAR; PG8_SCHED;
;     ...
;             PG8_WAIT_V(8); PG8_WAIT_L(0); PG8_BAR; PG8_MMA(0, 0, At, B0); PG8_MMA(0, 1, At, B1); PG8_BAR; PG8_SCHED;
;     ...
;             PG8_LDA(At, 0, 1); PG8_STAGEB(PG8_SB(0, 0), b2, voffB); PG8_STAGEB(PG8_SB(0, 1), b2 + hstepB, voffB); PG8_STAGEA(PG8_SA(0, 0), a2, voffA);
;     ...
;             PG8_WAIT_VR(8, 24, relax); PG8_WAIT_L(0); PG8_BAR; PG8_MMA(1, 0, At, B0); PG8_MMA(1, 1, At, B1); PG8_BAR; PG8_SCHED;
;     ...
;             PG8_WAIT_V(8); PG8_WAIT_L(0); PG8_BAR; PG8_MMA(1, 0, At, B0); PG8_MMA(1, 1, At, B1); PG8_BAR; PG8_SCHED;
	v_mfma_f32_16x16x32_bf16 v[126:129], v[130:133], v[178:181], v[126:129]
	v_mfma_f32_16x16x32_bf16 v[122:125], v[148:151], v[178:181], v[122:125]
	v_mfma_f32_16x16x32_bf16 v[110:113], v[130:133], v[186:189], v[110:113]
	v_mfma_f32_16x16x32_bf16 v[106:109], v[148:151], v[186:189], v[106:109]
	v_mfma_f32_16x16x32_bf16 v[94:97], v[130:133], v[194:197], v[94:97]
	v_mfma_f32_16x16x32_bf16 v[90:93], v[148:151], v[194:197], v[90:93]
	v_mfma_f32_16x16x32_bf16 v[78:81], v[130:133], v[202:205], v[78:81]
	v_mfma_f32_16x16x32_bf16 v[74:77], v[148:151], v[202:205], v[74:77]
	v_mfma_f32_16x16x32_bf16 v[126:129], v[134:137], v[182:185], v[126:129]
	v_mfma_f32_16x16x32_bf16 v[122:125], v[152:155], v[182:185], v[122:125]
	v_mfma_f32_16x16x32_bf16 v[110:113], v[134:137], v[190:193], v[110:113]
	v_mfma_f32_16x16x32_bf16 v[106:109], v[152:155], v[190:193], v[106:109]
	v_mfma_f32_16x16x32_bf16 v[94:97], v[134:137], v[198:201], v[94:97]
	v_mfma_f32_16x16x32_bf16 v[90:93], v[152:155], v[198:201], v[90:93]
	v_mfma_f32_16x16x32_bf16 v[78:81], v[134:137], v[206:209], v[78:81]
	v_mfma_f32_16x16x32_bf16 v[74:77], v[152:155], v[206:209], v[74:77]
	v_mfma_f32_16x16x32_bf16 v[118:121], v[162:165], v[178:181], v[118:121]
	v_mfma_f32_16x16x32_bf16 v[114:117], v[170:173], v[178:181], v[114:117]
	v_mfma_f32_16x16x32_bf16 v[102:105], v[162:165], v[186:189], v[102:105]
	v_mfma_f32_16x16x32_bf16 v[98:101], v[170:173], v[186:189], v[98:101]
	v_mfma_f32_16x16x32_bf16 v[86:89], v[162:165], v[194:197], v[86:89]
	v_mfma_f32_16x16x32_bf16 v[82:85], v[170:173], v[194:197], v[82:85]
	v_mfma_f32_16x16x32_bf16 v[70:73], v[162:165], v[202:205], v[70:73]
	v_mfma_f32_16x16x32_bf16 v[66:69], v[170:173], v[202:205], v[66:69]
	v_mfma_f32_16x16x32_bf16 v[118:121], v[166:169], v[182:185], v[118:121]
	v_mfma_f32_16x16x32_bf16 v[114:117], v[174:177], v[182:185], v[114:117]
	v_mfma_f32_16x16x32_bf16 v[102:105], v[166:169], v[190:193], v[102:105]
	v_mfma_f32_16x16x32_bf16 v[98:101], v[174:177], v[190:193], v[98:101]
	v_mfma_f32_16x16x32_bf16 v[86:89], v[166:169], v[198:201], v[86:89]
	v_mfma_f32_16x16x32_bf16 v[82:85], v[174:177], v[198:201], v[82:85]
	v_mfma_f32_16x16x32_bf16 v[70:73], v[166:169], v[206:209], v[70:73]
	v_mfma_f32_16x16x32_bf16 v[66:69], v[174:177], v[206:209], v[66:69]
	s_barrier
	s_setprio 0
	s_add_i32 s83, s83, s38
	v_lshl_add_u64 v[210:211], s[16:17], 0, v[16:17]
	s_mov_b32 m0, s83
	ds_read_b128 v[178:181], v161 offset:16384
	ds_read_b128 v[182:185], v161 offset:17408
	ds_read_b128 v[186:189], v161 offset:18432
	ds_read_b128 v[190:193], v161 offset:19456
	ds_read_b128 v[194:197], v161 offset:20480
	ds_read_b128 v[198:201], v161 offset:21504
	ds_read_b128 v[202:205], v161 offset:22528
	ds_read_b128 v[206:209], v161 offset:23552
	global_load_lds_dwordx4 v[210:211], off
	s_add_i32 m0, s83, 0x2000
	s_add_u32 s90, s16, 0x4000
	v_lshl_add_u64 v[210:211], s[16:17], 0, v[138:139]
	s_addc_u32 s91, s17, 0
	s_add_i32 s83, s94, s38
	global_load_lds_dwordx4 v[210:211], off
	v_lshl_add_u64 v[210:211], s[90:91], 0, v[16:17]
	s_mov_b32 m0, s83
	s_nop 0
	global_load_lds_dwordx4 v[210:211], off
	v_lshl_add_u64 v[210:211], s[90:91], 0, v[138:139]
	s_add_i32 m0, s83, 0x2000
	s_nop 0
	global_load_lds_dwordx4 v[210:211], off
	v_lshl_add_u64 v[210:211], s[36:37], 0, v[142:143]
	s_mov_b32 m0, s39
	s_nop 0
	global_load_lds_dwordx4 v[210:211], off
	v_lshl_add_u64 v[210:211], s[36:37], 0, v[140:141]
	s_mov_b32 m0, s40
	s_nop 0
	global_load_lds_dwordx4 v[210:211], off
	s_waitcnt vmcnt(8)
	s_waitcnt lgkmcnt(0)
	s_nop 0
	s_setprio 1
	s_barrier
	v_mfma_f32_16x16x32_bf16 v[62:65], v[130:133], v[178:181], v[62:65]
	v_mfma_f32_16x16x32_bf16 v[58:61], v[148:151], v[178:181], v[58:61]
	v_mfma_f32_16x16x32_bf16 v[46:49], v[130:133], v[186:189], v[46:49]
	v_mfma_f32_16x16x32_bf16 v[42:45], v[148:151], v[186:189], v[42:45]
	v_mfma_f32_16x16x32_bf16 v[30:33], v[130:133], v[194:197], v[30:33]
	v_mfma_f32_16x16x32_bf16 v[26:29], v[148:151], v[194:197], v[26:29]
	v_mfma_f32_16x16x32_bf16 v[12:15], v[130:133], v[202:205], v[12:15]
	v_mfma_f32_16x16x32_bf16 v[8:11], v[148:151], v[202:205], v[8:11]
	v_mfma_f32_16x16x32_bf16 v[62:65], v[134:137], v[182:185], v[62:65]
	v_mfma_f32_16x16x32_bf16 v[58:61], v[152:155], v[182:185], v[58:61]
	v_mfma_f32_16x16x32_bf16 v[46:49], v[134:137], v[190:193], v[46:49]
	v_mfma_f32_16x16x32_bf16 v[42:45], v[152:155], v[190:193], v[42:45]
	v_mfma_f32_16x16x32_bf16 v[30:33], v[134:137], v[198:201], v[30:33]
	v_mfma_f32_16x16x32_bf16 v[26:29], v[152:155], v[198:201], v[26:29]
	v_mfma_f32_16x16x32_bf16 v[12:15], v[134:137], v[206:209], v[12:15]
	v_mfma_f32_16x16x32_bf16 v[8:11], v[152:155], v[206:209], v[8:11]
	v_mfma_f32_16x16x32_bf16 v[54:57], v[162:165], v[178:181], v[54:57]
	v_mfma_f32_16x16x32_bf16 v[50:53], v[170:173], v[178:181], v[50:53]
	v_mfma_f32_16x16x32_bf16 v[38:41], v[162:165], v[186:189], v[38:41]
	v_mfma_f32_16x16x32_bf16 v[34:37], v[170:173], v[186:189], v[34:37]
	v_mfma_f32_16x16x32_bf16 v[22:25], v[162:165], v[194:197], v[22:25]
	v_mfma_f32_16x16x32_bf16 v[18:21], v[170:173], v[194:197], v[18:21]
	v_mfma_f32_16x16x32_bf16 v[4:7], v[162:165], v[202:205], v[4:7]
	v_mfma_f32_16x16x32_bf16 v[0:3], v[170:173], v[202:205], v[0:3]
	v_mfma_f32_16x16x32_bf16 v[54:57], v[166:169], v[182:185], v[54:57]
	v_mfma_f32_16x16x32_bf16 v[50:53], v[174:177], v[182:185], v[50:53]
	v_mfma_f32_16x16x32_bf16 v[38:41], v[166:169], v[190:193], v[38:41]
	v_mfma_f32_16x16x32_bf16 v[34:37], v[174:177], v[190:193], v[34:37]
	v_mfma_f32_16x16x32_bf16 v[22:25], v[166:169], v[198:201], v[22:25]
	v_mfma_f32_16x16x32_bf16 v[18:21], v[174:177], v[198:201], v[18:21]
	v_mfma_f32_16x16x32_bf16 v[4:7], v[166:169], v[206:209], v[4:7]
	v_mfma_f32_16x16x32_bf16 v[0:3], v[174:177], v[206:209], v[0:3]
	s_barrier
; #define PG8_STAGEA(bufoff, gbase, voff) PG8_STAGE_X(bufoff, gbase, voff, AUXA)
; #define PG8_LDA(dst, b, h) do { _Pragma("unroll") for (int m = 0; m < 4; ++m) _Pragma("unroll") for (int k = 0; k < 2; ++k) dst[m][k] = *(const PG8_LAS bf16x8*)(lds + PG8_SA(b, h) + aoff + m * 2048 + k * 1024); } while (0)
; #define PG8_LDB(dst, b, h) do { _Pragma("unroll") for (int n = 0; n < 2; ++n) _Pragma("unroll") for (int k = 0; k < 2; ++k) dst[n][k] = *(const PG8_LAS bf16x8*)(lds + PG8_SB(b, h) + boff + n * 2048 + k * 1024); } while (0)
; #define PG8_MMA(ai, bj, At, Bt) do { if (GEMM_PRIO_MODE == 0) __builtin_amdgcn_s_setprio(1); PG8_MMA_LOOPS \
;         acc[ai][bj][m][n] = __builtin_amdgcn_mfma_f32_16x16x32_bf16(Bt[n][k], At[m][k], acc[ai][bj][m][n], 0, 0, 0); if (GEMM_PRIO_MODE == 0) __builtin_amdgcn_s_setprio(0); } while (0)
; #define PG8_WAIT_V(n) asm volatile("s_waitcnt vmcnt(" #n ")" ::: "memory")
; #define PG8_WAIT_L(n) asm volatile("s_waitcnt lgkmcnt(" #n ")" ::: "memory")
; #define PG8_BAR __builtin_amdgcn_s_barrier()
; #define PG8_SCHED __builtin_amdgcn_sched_barrier(0)
;     ...
;             PG8_LDB(B0, 1, 0); PG8_LDB(B1, 1, 1); PG8_SCHED; PG8_LDA(At, 1, 0); PG8_STAGEA(PG8_SA(0, 1), a2 + hstepA, voffA);
;             PG8_WAIT_V(8); PG8_WAIT_L(0); PG8_BAR; PG8_MMA(0, 0, At, B0); PG8_MMA(0, 1, At, B1); PG8_BAR; PG8_SCHED;
	s_setprio 0
	s_add_i32 s83, 0, 0x18000
	s_add_i32 s90, 0, 0x1c000
	v_add_u32_e32 v152, s83, v157
	v_add_u32_e32 v174, s90, v157
	ds_read_b128 v[130:133], v152
	ds_read_b128 v[134:137], v152 offset:1024
	ds_read_b128 v[148:151], v152 offset:2048
	ds_read_b128 v[152:155], v152 offset:3072
	ds_read_b128 v[162:165], v174
	ds_read_b128 v[166:169], v174 offset:1024
	ds_read_b128 v[170:173], v174 offset:2048
	ds_read_b128 v[174:177], v174 offset:3072
	s_add_u32 s36, s36, 0x4000
	s_addc_u32 s37, s37, 0
	s_mov_b32 m0, s41
	v_lshl_add_u64 v[210:211], s[36:37], 0, v[142:143]
	ds_read_b128 v[178:181], v161 offset:32768
	ds_read_b128 v[182:185], v161 offset:33792
	ds_read_b128 v[186:189], v161 offset:34816
	ds_read_b128 v[190:193], v161 offset:35840
	ds_read_b128 v[194:197], v161 offset:36864
	ds_read_b128 v[198:201], v161 offset:37888
	ds_read_b128 v[202:205], v161 offset:38912
	ds_read_b128 v[206:209], v161 offset:39936
	global_load_lds_dwordx4 v[210:211], off
	v_lshl_add_u64 v[210:211], s[36:37], 0, v[140:141]
	s_mov_b32 m0, s42
	s_nop 0
	global_load_lds_dwordx4 v[210:211], off
	s_waitcnt vmcnt(8)
	s_waitcnt lgkmcnt(0)
	s_setprio 1
	s_barrier
	v_mfma_f32_16x16x32_bf16 v[126:129], v[130:133], v[178:181], v[126:129]
	v_mfma_f32_16x16x32_bf16 v[122:125], v[148:151], v[178:181], v[122:125]
	v_mfma_f32_16x16x32_bf16 v[110:113], v[130:133], v[186:189], v[110:113]
	v_mfma_f32_16x16x32_bf16 v[106:109], v[148:151], v[186:189], v[106:109]
	v_mfma_f32_16x16x32_bf16 v[94:97], v[130:133], v[194:197], v[94:97]
	v_mfma_f32_16x16x32_bf16 v[90:93], v[148:151], v[194:197], v[90:93]
	v_mfma_f32_16x16x32_bf16 v[78:81], v[130:133], v[202:205], v[78:81]
	v_mfma_f32_16x16x32_bf16 v[74:77], v[148:151], v[202:205], v[74:77]
	v_mfma_f32_16x16x32_bf16 v[126:129], v[134:137], v[182:185], v[126:129]
	v_mfma_f32_16x16x32_bf16 v[122:125], v[152:155], v[182:185], v[122:125]
	v_mfma_f32_16x16x32_bf16 v[110:113], v[134:137], v[190:193], v[110:113]
	v_mfma_f32_16x16x32_bf16 v[106:109], v[152:155], v[190:193], v[106:109]
	v_mfma_f32_16x16x32_bf16 v[94:97], v[134:137], v[198:201], v[94:97]
	v_mfma_f32_16x16x32_bf16 v[90:93], v[152:155], v[198:201], v[90:93]
	v_mfma_f32_16x16x32_bf16 v[78:81], v[134:137], v[206:209], v[78:81]
	v_mfma_f32_16x16x32_bf16 v[74:77], v[152:155], v[206:209], v[74:77]
	v_mfma_f32_16x16x32_bf16 v[118:121], v[162:165], v[178:181], v[118:121]
	v_mfma_f32_16x16x32_bf16 v[114:117], v[170:173], v[178:181], v[114:117]
	v_mfma_f32_16x16x32_bf16 v[102:105], v[162:165], v[186:189], v[102:105]
	v_mfma_f32_16x16x32_bf16 v[98:101], v[170:173], v[186:189], v[98:101]
	v_mfma_f32_16x16x32_bf16 v[86:89], v[162:165], v[194:197], v[86:89]
	v_mfma_f32_16x16x32_bf16 v[82:85], v[170:173], v[194:197], v[82:85]
	v_mfma_f32_16x16x32_bf16 v[70:73], v[162:165], v[202:205], v[70:73]
	v_mfma_f32_16x16x32_bf16 v[66:69], v[170:173], v[202:205], v[66:69]
	v_mfma_f32_16x16x32_bf16 v[118:121], v[166:169], v[182:185], v[118:121]
	v_mfma_f32_16x16x32_bf16 v[114:117], v[174:177], v[182:185], v[114:117]
	v_mfma_f32_16x16x32_bf16 v[102:105], v[166:169], v[190:193], v[102:105]
	v_mfma_f32_16x16x32_bf16 v[98:101], v[174:177], v[190:193], v[98:101]
	v_mfma_f32_16x16x32_bf16 v[86:89], v[166:169], v[198:201], v[86:89]
	v_mfma_f32_16x16x32_bf16 v[82:85], v[174:177], v[198:201], v[82:85]
	v_mfma_f32_16x16x32_bf16 v[70:73], v[166:169], v[206:209], v[70:73]
	v_mfma_f32_16x16x32_bf16 v[66:69], v[174:177], v[206:209], v[66:69]
	s_barrier
; #define PG8_STAGEA(bufoff, gbase, voff) PG8_STAGE_X(bufoff, gbase, voff, AUXA)
; #define PG8_STAGEB(bufoff, gbase, voff) PG8_STAGE_X(bufoff, gbase, voff, AUXB)
; #define PG8_LDA(dst, b, h) do { _Pragma("unroll") for (int m = 0; m < 4; ++m) _Pragma("unroll") for (int k = 0; k < 2; ++k) dst[m][k] = *(const PG8_LAS bf16x8*)(lds + PG8_SA(b, h) + aoff + m * 2048 + k * 1024); } while (0)
; #define PG8_MMA(ai, bj, At, Bt) do { if (GEMM_PRIO_MODE == 0) __builtin_amdgcn_s_setprio(1); PG8_MMA_LOOPS \
;         acc[ai][bj][m][n] = __builtin_amdgcn_mfma_f32_16x16x32_bf16(Bt[n][k], At[m][k], acc[ai][bj][m][n], 0, 0, 0); if (GEMM_PRIO_MODE == 0) __builtin_amdgcn_s_setprio(0); } while (0)
; #define PG8_WAIT_V(n) asm volatile("s_waitcnt vmcnt(" #n ")" ::: "memory")
; #define PG8_WAIT_L(n) asm volatile("s_waitcnt lgkmcnt(" #n ")" ::: "memory")
; #define PG8_BAR __builtin_amdgcn_s_barrier()
; #define PG8_SCHED __builtin_amdgcn_sched_barrier(0)
;     ...
;             PG8_LDA(At, 1, 1); PG8_STAGEB(PG8_SB(1, 0), b3, voffB); PG8_STAGEB(PG8_SB(1, 1), b3 + hstepB, voffB); PG8_STAGEA(PG8_SA(1, 0), a3, voffA);
;             PG8_WAIT_V(8); PG8_WAIT_L(0); PG8_BAR; PG8_MMA(1, 0, At, B0); PG8_MMA(1, 1, At, B1); PG8_BAR; PG8_SCHED;
;     ...
;         if constexpr (ALIGN_EPI) { if (wr == 0) PG8_BAR; }
	s_setprio 0
	s_add_u32 s36, s16, 0x8000
	s_addc_u32 s37, s17, 0
	s_add_i32 s83, s83, s38
	v_lshl_add_u64 v[210:211], s[36:37], 0, v[16:17]
	s_mov_b32 m0, s83
	ds_read_b128 v[178:181], v161 offset:49152
	ds_read_b128 v[182:185], v161 offset:50176
	ds_read_b128 v[186:189], v161 offset:51200
	ds_read_b128 v[190:193], v161 offset:52224
	ds_read_b128 v[194:197], v161 offset:53248
	ds_read_b128 v[198:201], v161 offset:54272
	ds_read_b128 v[202:205], v161 offset:55296
	ds_read_b128 v[206:209], v161 offset:56320
	global_load_lds_dwordx4 v[210:211], off
	s_add_i32 m0, s83, 0x2000
	s_add_u32 s16, s16, 0xc000
	v_lshl_add_u64 v[210:211], s[36:37], 0, v[138:139]
	s_addc_u32 s17, s17, 0
	s_add_i32 s36, s90, s38
	global_load_lds_dwordx4 v[210:211], off
	v_lshl_add_u64 v[210:211], s[16:17], 0, v[16:17]
	s_mov_b32 m0, s36
	s_nop 0
	global_load_lds_dwordx4 v[210:211], off
	v_lshl_add_u64 v[210:211], s[16:17], 0, v[138:139]
	s_add_i32 m0, s36, 0x2000
	s_nop 0
	global_load_lds_dwordx4 v[210:211], off
	v_lshl_add_u64 v[210:211], s[26:27], 0, v[142:143]
	s_mov_b32 m0, s50
	s_nop 0
	global_load_lds_dwordx4 v[210:211], off
	v_lshl_add_u64 v[210:211], s[26:27], 0, v[140:141]
	s_mov_b32 m0, s51
	s_nop 0
	global_load_lds_dwordx4 v[210:211], off
	s_waitcnt vmcnt(8)
	s_waitcnt lgkmcnt(0)
	s_setprio 1
	s_barrier
	v_mfma_f32_16x16x32_bf16 v[62:65], v[130:133], v[178:181], v[62:65]
	v_mfma_f32_16x16x32_bf16 v[58:61], v[148:151], v[178:181], v[58:61]
	v_mfma_f32_16x16x32_bf16 v[46:49], v[130:133], v[186:189], v[46:49]
	v_mfma_f32_16x16x32_bf16 v[42:45], v[148:151], v[186:189], v[42:45]
	v_mfma_f32_16x16x32_bf16 v[30:33], v[130:133], v[194:197], v[30:33]
	v_mfma_f32_16x16x32_bf16 v[26:29], v[148:151], v[194:197], v[26:29]
	v_mfma_f32_16x16x32_bf16 v[12:15], v[130:133], v[202:205], v[12:15]
	v_mfma_f32_16x16x32_bf16 v[8:11], v[148:151], v[202:205], v[8:11]
	v_mfma_f32_16x16x32_bf16 v[62:65], v[134:137], v[182:185], v[62:65]
	v_mfma_f32_16x16x32_bf16 v[58:61], v[152:155], v[182:185], v[58:61]
	v_mfma_f32_16x16x32_bf16 v[46:49], v[134:137], v[190:193], v[46:49]
	v_mfma_f32_16x16x32_bf16 v[42:45], v[152:155], v[190:193], v[42:45]
	v_mfma_f32_16x16x32_bf16 v[30:33], v[134:137], v[198:201], v[30:33]
	v_mfma_f32_16x16x32_bf16 v[26:29], v[152:155], v[198:201], v[26:29]
	v_mfma_f32_16x16x32_bf16 v[12:15], v[134:137], v[206:209], v[12:15]
	v_mfma_f32_16x16x32_bf16 v[8:11], v[152:155], v[206:209], v[8:11]
	v_mfma_f32_16x16x32_bf16 v[54:57], v[162:165], v[178:181], v[54:57]
	v_mfma_f32_16x16x32_bf16 v[50:53], v[170:173], v[178:181], v[50:53]
	v_mfma_f32_16x16x32_bf16 v[38:41], v[162:165], v[186:189], v[38:41]
	v_mfma_f32_16x16x32_bf16 v[34:37], v[170:173], v[186:189], v[34:37]
	v_mfma_f32_16x16x32_bf16 v[22:25], v[162:165], v[194:197], v[22:25]
	v_mfma_f32_16x16x32_bf16 v[18:21], v[170:173], v[194:197], v[18:21]
	v_mfma_f32_16x16x32_bf16 v[4:7], v[162:165], v[202:205], v[4:7]
	v_mfma_f32_16x16x32_bf16 v[0:3], v[170:173], v[202:205], v[0:3]
	v_mfma_f32_16x16x32_bf16 v[54:57], v[166:169], v[182:185], v[54:57]
	v_mfma_f32_16x16x32_bf16 v[50:53], v[174:177], v[182:185], v[50:53]
	v_mfma_f32_16x16x32_bf16 v[38:41], v[166:169], v[190:193], v[38:41]
	v_mfma_f32_16x16x32_bf16 v[34:37], v[174:177], v[190:193], v[34:37]
	v_mfma_f32_16x16x32_bf16 v[22:25], v[166:169], v[198:201], v[22:25]
	v_mfma_f32_16x16x32_bf16 v[18:21], v[174:177], v[198:201], v[18:21]
	v_mfma_f32_16x16x32_bf16 v[4:7], v[166:169], v[206:209], v[4:7]
	v_mfma_f32_16x16x32_bf16 v[0:3], v[174:177], v[206:209], v[0:3]
	s_barrier
	s_setprio 0
	s_add_i32 s82, s82, 2
	s_add_u32 s24, s24, 0x10000
	s_addc_u32 s25, s25, 0
	s_add_u32 s0, s0, 0x10000
	s_addc_u32 s1, s1, 0
	s_cmpk_gt_u32 s82, 0xfd
	s_cbranch_scc0 .LBB0_848
	s_and_b64 vcc, exec, s[8:9]
	s_cbranch_vccz .LBB0_851
	s_barrier
